# K-loops: the next-unit prefetch DMAs of the last K-iteration are issued with EXEC=0 when the workgroup has no next unit (they fetched tiles nobody reads)
# speedup vs baseline: 1.0047x; 1.0008x over previous
; #define PG8_STAGEA(bufoff, gbase) PG8_STAGE_(bufoff, gbase, voffA)
; #define PG8_STAGEB(bufoff, gbase) PG8_STAGE_(bufoff, gbase, voffB)
; #define PG8_LDA(dst, b, h) do { _Pragma("unroll") for (int m = 0; m < 4; ++m) _Pragma("unroll") for (int k = 0; k < 2; ++k) dst[m][k] = *(const LAS bf16x8*)(lds + PG8_SA(b, h) + aoff + m * 2048 + k * 1024); } while (0)
; #define PG8_LDB(dst, b, h) do { _Pragma("unroll") for (int n = 0; n < 2; ++n) _Pragma("unroll") for (int k = 0; k < 2; ++k) dst[n][k] = *(const LAS bf16x8*)(lds + PG8_SB(b, h) + boff + n * 2048 + k * 1024); } while (0)
; #define PG8_MMA(ai, bj, At, Bt_) do { __builtin_amdgcn_s_setprio(1); _Pragma("unroll") for (int m = 0; m < 4; ++m) _Pragma("unroll") for (int n = 0; n < 2; ++n) _Pragma("unroll") for (int k = 0; k < 2; ++k) \
;         acc[ai][bj][m][n] = __builtin_amdgcn_mfma_f32_16x16x32_bf16(Bt_[n][k], At[m][k], acc[ai][bj][m][n], 0, 0, 0); __builtin_amdgcn_s_setprio(0); } while (0)
; #define PG8_WAIT_V(n) asm volatile("s_waitcnt vmcnt(" #n ")" ::: "memory")
; #define PG8_WAIT_L(n) asm volatile("s_waitcnt lgkmcnt(" #n ")" ::: "memory")
; #define PG8_BAR __builtin_amdgcn_s_barrier()
; template <int EK, int SK = -1>
; __device__ __forceinline__ void gemm_phase(LAS unsigned char* lds, const bf16_t* A, const bf16_t* Bt, int nM, int N, int K, const EpiArgs& E) {
;     ...
;         const bool has_next = S.next(ui + 1, nxt);
;         const char* nA = has_next ? (const char*)A + (size_t)nxt.pm * tstep : cA; const char* nB = has_next ? (const char*)Bt + (size_t)nxt.pn * tstep : cB;
;         for (int t = 0; t < nt; t += 2) {
;             const bool last = (t == nt - 2);
;             const char* a1 = cA + (size_t)(t + 1) * kstep;
;             const char* a2 = last ? nA : cA + (size_t)(t + 2) * kstep; const char* b2 = last ? nB : cB + (size_t)(t + 2) * kstep;
;             const char* a3 = a2 + kstep; const char* b3 = b2 + kstep;
;             PG8_LDB(B0, 0, 0); PG8_LDB(B1, 0, 1); PG8_SCHED; PG8_LDA(At, 0, 0); PG8_STAGEA(PG8_SA(1, 1), a1 + hstep);
;             PG8_WAIT_V(8); PG8_WAIT_L(0); PG8_BAR; PG8_MMA(0, 0, At, B0); PG8_MMA(0, 1, At, B1); PG8_BAR; PG8_SCHED;
;             PG8_LDA(At, 0, 1); PG8_STAGEB(PG8_SB(0, 0), b2); PG8_STAGEB(PG8_SB(0, 1), b2 + hstep); PG8_STAGEA(PG8_SA(0, 0), a2);
;             PG8_WAIT_V(8); PG8_WAIT_L(0); PG8_BAR; PG8_MMA(1, 0, At, B0); PG8_MMA(1, 1, At, B1); PG8_BAR; PG8_SCHED;
.LBB0_198:
	v_add_u32_e32 v150, s54, v152
	ds_read_b128 v[156:159], v150
	ds_read_b128 v[160:163], v150 offset:1024
	ds_read_b128 v[164:167], v150 offset:2048
	ds_read_b128 v[168:171], v150 offset:3072
	v_add_u32_e32 v150, s55, v152
	s_add_u32 s82, s70, s78
	ds_read_b128 v[172:175], v150
	ds_read_b128 v[176:179], v150 offset:1024
	ds_read_b128 v[180:183], v150 offset:2048
	ds_read_b128 v[184:187], v150 offset:3072
	s_addc_u32 s83, s71, s79
	s_add_u32 s82, s82, 0x100
	s_addc_u32 s83, s83, 0
	s_add_u32 s93, s58, s78
	s_addc_u32 s94, s59, s79
	s_cmpk_eq_i32 s78, 0x700
	s_cselect_b32 s85, s75, s83
	s_cselect_b32 s84, s90, s82
	s_cselect_b32 s83, s73, s94
	s_cselect_b32 s82, s91, s93
	s_mov_b64 s[100:101], -1
	s_cmpk_lg_i32 s78, 0x700
	s_cbranch_scc1 .Lmy_mk_198
	s_not_b64 s[100:101], s[4:5]
.Lmy_mk_198:
	v_lshl_add_u64 v[150:151], v[146:147], 0, s[78:79]
	s_add_i32 m0, s67, 0xc000
	ds_read_b128 v[188:191], v155
	ds_read_b128 v[192:195], v155 offset:1024
	ds_read_b128 v[196:199], v155 offset:2048
	ds_read_b128 v[200:203], v155 offset:3072
	ds_read_b128 v[204:207], v155 offset:4096
	ds_read_b128 v[208:211], v155 offset:5120
	ds_read_b128 v[212:215], v155 offset:6144
	ds_read_b128 v[216:219], v155 offset:7168
	global_load_lds_dwordx4 v[150:151], off
	v_lshl_add_u64 v[150:151], v[148:149], 0, s[78:79]
	s_add_i32 m0, s67, 0xe000
	s_nop 0
	global_load_lds_dwordx4 v[150:151], off
	s_waitcnt vmcnt(8)
	s_waitcnt lgkmcnt(0)
	s_barrier
	s_waitcnt lgkmcnt(0)
	v_mfma_f32_16x16x32_bf16 v[110:113], v[156:159], v[188:191], v[110:113]
	v_mfma_f32_16x16x32_bf16 v[106:109], v[164:167], v[188:191], v[106:109]
	v_mfma_f32_16x16x32_bf16 v[102:105], v[156:159], v[196:199], v[102:105]
	v_mfma_f32_16x16x32_bf16 v[98:101], v[164:167], v[196:199], v[98:101]
	v_mfma_f32_16x16x32_bf16 v[94:97], v[156:159], v[204:207], v[94:97]
	v_mfma_f32_16x16x32_bf16 v[90:93], v[164:167], v[204:207], v[90:93]
	v_mfma_f32_16x16x32_bf16 v[86:89], v[156:159], v[212:215], v[86:89]
	v_mfma_f32_16x16x32_bf16 v[82:85], v[164:167], v[212:215], v[82:85]
	v_mfma_f32_16x16x32_bf16 v[110:113], v[160:163], v[192:195], v[110:113]
	v_mfma_f32_16x16x32_bf16 v[106:109], v[168:171], v[192:195], v[106:109]
	v_mfma_f32_16x16x32_bf16 v[102:105], v[160:163], v[200:203], v[102:105]
	v_mfma_f32_16x16x32_bf16 v[98:101], v[168:171], v[200:203], v[98:101]
	v_mfma_f32_16x16x32_bf16 v[94:97], v[160:163], v[208:211], v[94:97]
	v_mfma_f32_16x16x32_bf16 v[90:93], v[168:171], v[208:211], v[90:93]
	v_mfma_f32_16x16x32_bf16 v[86:89], v[160:163], v[216:219], v[86:89]
	v_mfma_f32_16x16x32_bf16 v[82:85], v[168:171], v[216:219], v[82:85]
	v_mfma_f32_16x16x32_bf16 v[78:81], v[172:175], v[188:191], v[78:81]
	v_mfma_f32_16x16x32_bf16 v[74:77], v[180:183], v[188:191], v[74:77]
	v_mfma_f32_16x16x32_bf16 v[70:73], v[172:175], v[196:199], v[70:73]
	v_mfma_f32_16x16x32_bf16 v[66:69], v[180:183], v[196:199], v[66:69]
	v_mfma_f32_16x16x32_bf16 v[62:65], v[172:175], v[204:207], v[62:65]
	v_mfma_f32_16x16x32_bf16 v[58:61], v[180:183], v[204:207], v[58:61]
	v_mfma_f32_16x16x32_bf16 v[54:57], v[172:175], v[212:215], v[54:57]
	v_mfma_f32_16x16x32_bf16 v[50:53], v[180:183], v[212:215], v[50:53]
	v_mfma_f32_16x16x32_bf16 v[78:81], v[176:179], v[192:195], v[78:81]
	v_mfma_f32_16x16x32_bf16 v[74:77], v[184:187], v[192:195], v[74:77]
	v_mfma_f32_16x16x32_bf16 v[70:73], v[176:179], v[200:203], v[70:73]
	v_mfma_f32_16x16x32_bf16 v[66:69], v[184:187], v[200:203], v[66:69]
	v_mfma_f32_16x16x32_bf16 v[62:65], v[176:179], v[208:211], v[62:65]
	v_mfma_f32_16x16x32_bf16 v[58:61], v[184:187], v[208:211], v[58:61]
	v_mfma_f32_16x16x32_bf16 v[54:57], v[176:179], v[216:219], v[54:57]
	v_mfma_f32_16x16x32_bf16 v[50:53], v[184:187], v[216:219], v[50:53]
	s_barrier
	s_add_i32 s93, s54, s87
	v_lshl_add_u64 v[150:151], s[82:83], 0, v[132:133]
	s_mov_b32 m0, s93
	ds_read_b128 v[188:191], v155 offset:16384
	ds_read_b128 v[192:195], v155 offset:17408
	ds_read_b128 v[196:199], v155 offset:18432
	ds_read_b128 v[200:203], v155 offset:19456
	ds_read_b128 v[204:207], v155 offset:20480
	ds_read_b128 v[208:211], v155 offset:21504
	ds_read_b128 v[212:215], v155 offset:22528
	ds_read_b128 v[216:219], v155 offset:23552
	s_mov_b64 exec, s[100:101]
	global_load_lds_dwordx4 v[150:151], off
	s_mov_b64 exec, -1
	s_add_i32 m0, s93, 0x2000
	s_add_u32 s94, s82, 0x40000
	v_lshl_add_u64 v[220:221], s[82:83], 0, v[136:137]
	s_addc_u32 s95, s83, 0
	s_add_i32 s93, s55, s87
	s_mov_b64 exec, s[100:101]
	global_load_lds_dwordx4 v[220:221], off
	s_mov_b64 exec, -1
	v_lshl_add_u64 v[222:223], s[94:95], 0, v[132:133]
	s_mov_b32 m0, s93
	v_lshl_add_u64 v[224:225], s[84:85], 0, v[134:135]
	s_mov_b64 exec, s[100:101]
	global_load_lds_dwordx4 v[222:223], off
	s_mov_b64 exec, -1
	v_lshl_add_u64 v[222:223], s[94:95], 0, v[136:137]
	s_add_i32 m0, s93, 0x2000
	s_nop 0
	s_mov_b64 exec, s[100:101]
	global_load_lds_dwordx4 v[222:223], off
	s_mov_b64 exec, -1
	v_lshl_add_u64 v[222:223], s[84:85], 0, v[130:131]
	s_mov_b32 m0, s67
	s_nop 0
	s_mov_b64 exec, s[100:101]
	global_load_lds_dwordx4 v[222:223], off
	s_mov_b64 exec, -1
	s_mov_b32 m0, s69
	s_nop 0
	s_mov_b64 exec, s[100:101]
	global_load_lds_dwordx4 v[224:225], off
	s_mov_b64 exec, -1
	s_waitcnt vmcnt(8)
	s_waitcnt lgkmcnt(0)
	s_barrier
; #define PG8_STAGEA(bufoff, gbase) PG8_STAGE_(bufoff, gbase, voffA)
; #define PG8_LDA(dst, b, h) do { _Pragma("unroll") for (int m = 0; m < 4; ++m) _Pragma("unroll") for (int k = 0; k < 2; ++k) dst[m][k] = *(const LAS bf16x8*)(lds + PG8_SA(b, h) + aoff + m * 2048 + k * 1024); } while (0)
; #define PG8_LDB(dst, b, h) do { _Pragma("unroll") for (int n = 0; n < 2; ++n) _Pragma("unroll") for (int k = 0; k < 2; ++k) dst[n][k] = *(const LAS bf16x8*)(lds + PG8_SB(b, h) + boff + n * 2048 + k * 1024); } while (0)
; #define PG8_MMA(ai, bj, At, Bt_) do { __builtin_amdgcn_s_setprio(1); _Pragma("unroll") for (int m = 0; m < 4; ++m) _Pragma("unroll") for (int n = 0; n < 2; ++n) _Pragma("unroll") for (int k = 0; k < 2; ++k) \
;         acc[ai][bj][m][n] = __builtin_amdgcn_mfma_f32_16x16x32_bf16(Bt_[n][k], At[m][k], acc[ai][bj][m][n], 0, 0, 0); __builtin_amdgcn_s_setprio(0); } while (0)
; #define PG8_WAIT_V(n) asm volatile("s_waitcnt vmcnt(" #n ")" ::: "memory")
; #define PG8_WAIT_L(n) asm volatile("s_waitcnt lgkmcnt(" #n ")" ::: "memory")
; #define PG8_BAR __builtin_amdgcn_s_barrier()
; #define PG8_SCHED __builtin_amdgcn_sched_barrier(0)
; template <int EK, int SK = -1>
; __device__ __forceinline__ void gemm_phase(LAS unsigned char* lds, const bf16_t* A, const bf16_t* Bt, int nM, int N, int K, const EpiArgs& E) {
;     ...
;             PG8_WAIT_V(8); PG8_WAIT_L(0); PG8_BAR; PG8_MMA(1, 0, At, B0); PG8_MMA(1, 1, At, B1); PG8_BAR; PG8_SCHED;
;             PG8_LDB(B0, 1, 0); PG8_LDB(B1, 1, 1); PG8_SCHED; PG8_LDA(At, 1, 0); PG8_STAGEA(PG8_SA(0, 1), a2 + hstep);
;             PG8_WAIT_V(8); PG8_WAIT_L(0); PG8_BAR; PG8_MMA(0, 0, At, B0); PG8_MMA(0, 1, At, B1); PG8_BAR; PG8_SCHED;
	s_waitcnt lgkmcnt(0)
	v_mfma_f32_16x16x32_bf16 v[46:49], v[156:159], v[188:191], v[46:49]
	v_mfma_f32_16x16x32_bf16 v[42:45], v[164:167], v[188:191], v[42:45]
	v_mfma_f32_16x16x32_bf16 v[38:41], v[156:159], v[196:199], v[38:41]
	v_mfma_f32_16x16x32_bf16 v[34:37], v[164:167], v[196:199], v[34:37]
	v_mfma_f32_16x16x32_bf16 v[30:33], v[156:159], v[204:207], v[30:33]
	v_mfma_f32_16x16x32_bf16 v[26:29], v[164:167], v[204:207], v[26:29]
	v_mfma_f32_16x16x32_bf16 v[22:25], v[156:159], v[212:215], v[22:25]
	v_mfma_f32_16x16x32_bf16 v[18:21], v[164:167], v[212:215], v[18:21]
	v_mfma_f32_16x16x32_bf16 v[46:49], v[160:163], v[192:195], v[46:49]
	v_mfma_f32_16x16x32_bf16 v[42:45], v[168:171], v[192:195], v[42:45]
	v_mfma_f32_16x16x32_bf16 v[38:41], v[160:163], v[200:203], v[38:41]
	v_mfma_f32_16x16x32_bf16 v[34:37], v[168:171], v[200:203], v[34:37]
	v_mfma_f32_16x16x32_bf16 v[30:33], v[160:163], v[208:211], v[30:33]
	v_mfma_f32_16x16x32_bf16 v[26:29], v[168:171], v[208:211], v[26:29]
	v_mfma_f32_16x16x32_bf16 v[22:25], v[160:163], v[216:219], v[22:25]
	v_mfma_f32_16x16x32_bf16 v[18:21], v[168:171], v[216:219], v[18:21]
	v_mfma_f32_16x16x32_bf16 v[14:17], v[172:175], v[188:191], v[14:17]
	v_mfma_f32_16x16x32_bf16 v[10:13], v[180:183], v[188:191], v[10:13]
	v_mfma_f32_16x16x32_bf16 v[6:9], v[172:175], v[196:199], v[6:9]
	v_mfma_f32_16x16x32_bf16 v[2:5], v[180:183], v[196:199], v[2:5]
	v_mfma_f32_16x16x32_bf16 v[114:117], v[172:175], v[204:207], v[114:117]
	v_mfma_f32_16x16x32_bf16 v[118:121], v[180:183], v[204:207], v[118:121]
	v_mfma_f32_16x16x32_bf16 v[122:125], v[172:175], v[212:215], v[122:125]
	v_mfma_f32_16x16x32_bf16 v[126:129], v[180:183], v[212:215], v[126:129]
	v_mfma_f32_16x16x32_bf16 v[14:17], v[176:179], v[192:195], v[14:17]
	v_mfma_f32_16x16x32_bf16 v[10:13], v[184:187], v[192:195], v[10:13]
	v_mfma_f32_16x16x32_bf16 v[6:9], v[176:179], v[200:203], v[6:9]
	v_mfma_f32_16x16x32_bf16 v[2:5], v[184:187], v[200:203], v[2:5]
	v_mfma_f32_16x16x32_bf16 v[114:117], v[176:179], v[208:211], v[114:117]
	v_mfma_f32_16x16x32_bf16 v[118:121], v[184:187], v[208:211], v[118:121]
	v_mfma_f32_16x16x32_bf16 v[122:125], v[176:179], v[216:219], v[122:125]
	v_mfma_f32_16x16x32_bf16 v[126:129], v[184:187], v[216:219], v[126:129]
	s_barrier
	s_add_i32 s93, 0, 0x18000
	s_add_i32 s94, 0, 0x1c000
	v_add_u32_e32 v168, s93, v152
	v_add_u32_e32 v184, s94, v152
	ds_read_b128 v[156:159], v168
	ds_read_b128 v[160:163], v168 offset:1024
	ds_read_b128 v[164:167], v168 offset:2048
	ds_read_b128 v[168:171], v168 offset:3072
	ds_read_b128 v[172:175], v184
	ds_read_b128 v[176:179], v184 offset:1024
	ds_read_b128 v[180:183], v184 offset:2048
	ds_read_b128 v[184:187], v184 offset:3072
	s_add_u32 s84, s84, 0x40000
	s_addc_u32 s85, s85, 0
	s_mov_b32 m0, s88
	v_lshl_add_u64 v[226:227], s[84:85], 0, v[130:131]
	ds_read_b128 v[188:191], v155 offset:32768
	ds_read_b128 v[192:195], v155 offset:33792
	ds_read_b128 v[196:199], v155 offset:34816
	ds_read_b128 v[200:203], v155 offset:35840
	ds_read_b128 v[204:207], v155 offset:36864
	ds_read_b128 v[208:211], v155 offset:37888
	ds_read_b128 v[212:215], v155 offset:38912
	ds_read_b128 v[216:219], v155 offset:39936
	s_mov_b64 exec, s[100:101]
	global_load_lds_dwordx4 v[226:227], off
	s_mov_b64 exec, -1
	v_lshl_add_u64 v[226:227], s[84:85], 0, v[134:135]
	s_mov_b32 m0, s89
	s_nop 0
	s_mov_b64 exec, s[100:101]
	global_load_lds_dwordx4 v[226:227], off
	s_mov_b64 exec, -1
	s_waitcnt vmcnt(8)
	s_waitcnt lgkmcnt(0)
	s_barrier
	s_waitcnt lgkmcnt(0)
	v_mfma_f32_16x16x32_bf16 v[110:113], v[156:159], v[188:191], v[110:113]
	v_mfma_f32_16x16x32_bf16 v[106:109], v[164:167], v[188:191], v[106:109]
	v_mfma_f32_16x16x32_bf16 v[102:105], v[156:159], v[196:199], v[102:105]
	v_mfma_f32_16x16x32_bf16 v[98:101], v[164:167], v[196:199], v[98:101]
	v_mfma_f32_16x16x32_bf16 v[94:97], v[156:159], v[204:207], v[94:97]
	v_mfma_f32_16x16x32_bf16 v[90:93], v[164:167], v[204:207], v[90:93]
	v_mfma_f32_16x16x32_bf16 v[86:89], v[156:159], v[212:215], v[86:89]
	v_mfma_f32_16x16x32_bf16 v[82:85], v[164:167], v[212:215], v[82:85]
	v_mfma_f32_16x16x32_bf16 v[110:113], v[160:163], v[192:195], v[110:113]
	v_mfma_f32_16x16x32_bf16 v[106:109], v[168:171], v[192:195], v[106:109]
	v_mfma_f32_16x16x32_bf16 v[102:105], v[160:163], v[200:203], v[102:105]
	v_mfma_f32_16x16x32_bf16 v[98:101], v[168:171], v[200:203], v[98:101]
	v_mfma_f32_16x16x32_bf16 v[94:97], v[160:163], v[208:211], v[94:97]
	v_mfma_f32_16x16x32_bf16 v[90:93], v[168:171], v[208:211], v[90:93]
	v_mfma_f32_16x16x32_bf16 v[86:89], v[160:163], v[216:219], v[86:89]
	v_mfma_f32_16x16x32_bf16 v[82:85], v[168:171], v[216:219], v[82:85]
	v_mfma_f32_16x16x32_bf16 v[78:81], v[172:175], v[188:191], v[78:81]
	v_mfma_f32_16x16x32_bf16 v[74:77], v[180:183], v[188:191], v[74:77]
	v_mfma_f32_16x16x32_bf16 v[70:73], v[172:175], v[196:199], v[70:73]
	v_mfma_f32_16x16x32_bf16 v[66:69], v[180:183], v[196:199], v[66:69]
	v_mfma_f32_16x16x32_bf16 v[62:65], v[172:175], v[204:207], v[62:65]
	v_mfma_f32_16x16x32_bf16 v[58:61], v[180:183], v[204:207], v[58:61]
	v_mfma_f32_16x16x32_bf16 v[54:57], v[172:175], v[212:215], v[54:57]
	v_mfma_f32_16x16x32_bf16 v[50:53], v[180:183], v[212:215], v[50:53]
	v_mfma_f32_16x16x32_bf16 v[78:81], v[176:179], v[192:195], v[78:81]
	v_mfma_f32_16x16x32_bf16 v[74:77], v[184:187], v[192:195], v[74:77]
	v_mfma_f32_16x16x32_bf16 v[70:73], v[176:179], v[200:203], v[70:73]
	v_mfma_f32_16x16x32_bf16 v[66:69], v[184:187], v[200:203], v[66:69]
	v_mfma_f32_16x16x32_bf16 v[62:65], v[176:179], v[208:211], v[62:65]
	v_mfma_f32_16x16x32_bf16 v[58:61], v[184:187], v[208:211], v[58:61]
	v_mfma_f32_16x16x32_bf16 v[54:57], v[176:179], v[216:219], v[54:57]
	v_mfma_f32_16x16x32_bf16 v[50:53], v[184:187], v[216:219], v[50:53]
	s_barrier
; #define PG8_STAGEA(bufoff, gbase) PG8_STAGE_(bufoff, gbase, voffA)
; #define PG8_STAGEB(bufoff, gbase) PG8_STAGE_(bufoff, gbase, voffB)
; #define PG8_LDA(dst, b, h) do { _Pragma("unroll") for (int m = 0; m < 4; ++m) _Pragma("unroll") for (int k = 0; k < 2; ++k) dst[m][k] = *(const LAS bf16x8*)(lds + PG8_SA(b, h) + aoff + m * 2048 + k * 1024); } while (0)
; #define PG8_MMA(ai, bj, At, Bt_) do { __builtin_amdgcn_s_setprio(1); _Pragma("unroll") for (int m = 0; m < 4; ++m) _Pragma("unroll") for (int n = 0; n < 2; ++n) _Pragma("unroll") for (int k = 0; k < 2; ++k) \
;         acc[ai][bj][m][n] = __builtin_amdgcn_mfma_f32_16x16x32_bf16(Bt_[n][k], At[m][k], acc[ai][bj][m][n], 0, 0, 0); __builtin_amdgcn_s_setprio(0); } while (0)
; #define PG8_WAIT_V(n) asm volatile("s_waitcnt vmcnt(" #n ")" ::: "memory")
; #define PG8_WAIT_L(n) asm volatile("s_waitcnt lgkmcnt(" #n ")" ::: "memory")
; #define PG8_BAR __builtin_amdgcn_s_barrier()
; #define PG8_SCHED __builtin_amdgcn_sched_barrier(0)
; template <int EK, int SK = -1>
; __device__ __forceinline__ void gemm_phase(LAS unsigned char* lds, const bf16_t* A, const bf16_t* Bt, int nM, int N, int K, const EpiArgs& E) {
;     ...
;             PG8_LDA(At, 1, 1); PG8_STAGEB(PG8_SB(1, 0), b3); PG8_STAGEB(PG8_SB(1, 1), b3 + hstep); PG8_STAGEA(PG8_SA(1, 0), a3);
;             PG8_WAIT_V(8); PG8_WAIT_L(0); PG8_BAR; PG8_MMA(1, 0, At, B0); PG8_MMA(1, 1, At, B1); PG8_BAR; PG8_SCHED;
	s_add_i32 s84, s93, s87
	v_lshl_add_u64 v[150:151], v[150:151], 0, s[10:11]
	s_mov_b32 m0, s84
	ds_read_b128 v[188:191], v155 offset:49152
	ds_read_b128 v[192:195], v155 offset:50176
	ds_read_b128 v[196:199], v155 offset:51200
	ds_read_b128 v[200:203], v155 offset:52224
	ds_read_b128 v[204:207], v155 offset:53248
	ds_read_b128 v[208:211], v155 offset:54272
	ds_read_b128 v[212:215], v155 offset:55296
	ds_read_b128 v[216:219], v155 offset:56320
	s_mov_b64 exec, s[100:101]
	global_load_lds_dwordx4 v[150:151], off
	s_mov_b64 exec, -1
	s_add_i32 m0, s84, 0x2000
	s_add_u32 s82, s82, 0x40080
	v_lshl_add_u64 v[150:151], v[220:221], 0, s[10:11]
	s_addc_u32 s83, s83, 0
	s_add_i32 s84, s94, s87
	s_mov_b64 exec, s[100:101]
	global_load_lds_dwordx4 v[150:151], off
	s_mov_b64 exec, -1
	v_lshl_add_u64 v[150:151], s[82:83], 0, v[132:133]
	s_mov_b32 m0, s84
	s_nop 0
	s_mov_b64 exec, s[100:101]
	global_load_lds_dwordx4 v[150:151], off
	s_mov_b64 exec, -1
	v_lshl_add_u64 v[150:151], s[82:83], 0, v[136:137]
	s_add_i32 m0, s84, 0x2000
	s_nop 0
	s_mov_b64 exec, s[100:101]
	global_load_lds_dwordx4 v[150:151], off
	s_mov_b64 exec, -1
	v_lshl_add_u64 v[150:151], v[222:223], 0, s[10:11]
	s_mov_b32 m0, s52
	s_nop 0
	s_mov_b64 exec, s[100:101]
	global_load_lds_dwordx4 v[150:151], off
	s_mov_b64 exec, -1
	v_lshl_add_u64 v[150:151], v[224:225], 0, s[10:11]
	s_mov_b32 m0, s53
	s_nop 0
	s_mov_b64 exec, s[100:101]
	global_load_lds_dwordx4 v[150:151], off
	s_mov_b64 exec, -1
	s_waitcnt vmcnt(8)
	s_waitcnt lgkmcnt(0)
	s_barrier
	s_waitcnt lgkmcnt(0)
	v_mfma_f32_16x16x32_bf16 v[46:49], v[156:159], v[188:191], v[46:49]
	v_mfma_f32_16x16x32_bf16 v[42:45], v[164:167], v[188:191], v[42:45]
	v_mfma_f32_16x16x32_bf16 v[38:41], v[156:159], v[196:199], v[38:41]
	v_mfma_f32_16x16x32_bf16 v[34:37], v[164:167], v[196:199], v[34:37]
	v_mfma_f32_16x16x32_bf16 v[30:33], v[156:159], v[204:207], v[30:33]
	v_mfma_f32_16x16x32_bf16 v[26:29], v[164:167], v[204:207], v[26:29]
	v_mfma_f32_16x16x32_bf16 v[22:25], v[156:159], v[212:215], v[22:25]
	v_mfma_f32_16x16x32_bf16 v[18:21], v[164:167], v[212:215], v[18:21]
	v_mfma_f32_16x16x32_bf16 v[46:49], v[160:163], v[192:195], v[46:49]
	v_mfma_f32_16x16x32_bf16 v[42:45], v[168:171], v[192:195], v[42:45]
	v_mfma_f32_16x16x32_bf16 v[38:41], v[160:163], v[200:203], v[38:41]
	v_mfma_f32_16x16x32_bf16 v[34:37], v[168:171], v[200:203], v[34:37]
	v_mfma_f32_16x16x32_bf16 v[30:33], v[160:163], v[208:211], v[30:33]
	v_mfma_f32_16x16x32_bf16 v[26:29], v[168:171], v[208:211], v[26:29]
	v_mfma_f32_16x16x32_bf16 v[22:25], v[160:163], v[216:219], v[22:25]
	v_mfma_f32_16x16x32_bf16 v[18:21], v[168:171], v[216:219], v[18:21]
	v_mfma_f32_16x16x32_bf16 v[14:17], v[172:175], v[188:191], v[14:17]
	v_mfma_f32_16x16x32_bf16 v[10:13], v[180:183], v[188:191], v[10:13]
	v_mfma_f32_16x16x32_bf16 v[6:9], v[172:175], v[196:199], v[6:9]
	v_mfma_f32_16x16x32_bf16 v[2:5], v[180:183], v[196:199], v[2:5]
	v_mfma_f32_16x16x32_bf16 v[114:117], v[172:175], v[204:207], v[114:117]
	v_mfma_f32_16x16x32_bf16 v[118:121], v[180:183], v[204:207], v[118:121]
	v_mfma_f32_16x16x32_bf16 v[122:125], v[172:175], v[212:215], v[122:125]
	v_mfma_f32_16x16x32_bf16 v[126:129], v[180:183], v[212:215], v[126:129]
	v_mfma_f32_16x16x32_bf16 v[14:17], v[176:179], v[192:195], v[14:17]
	v_mfma_f32_16x16x32_bf16 v[10:13], v[184:187], v[192:195], v[10:13]
	v_mfma_f32_16x16x32_bf16 v[6:9], v[176:179], v[200:203], v[6:9]
	v_mfma_f32_16x16x32_bf16 v[2:5], v[184:187], v[200:203], v[2:5]
	v_mfma_f32_16x16x32_bf16 v[114:117], v[176:179], v[208:211], v[114:117]
	v_mfma_f32_16x16x32_bf16 v[118:121], v[184:187], v[208:211], v[118:121]
	v_mfma_f32_16x16x32_bf16 v[122:125], v[176:179], v[216:219], v[122:125]
	v_mfma_f32_16x16x32_bf16 v[126:129], v[184:187], v[216:219], v[126:129]
	s_barrier
	s_add_i32 s92, s92, 2
	s_add_u32 s78, s78, 0x100
	s_addc_u32 s79, s79, 0
	s_cmp_gt_u32 s92, 13
	s_cbranch_scc0 .LBB0_198

; #define PG8_STAGEA(bufoff, gbase) PG8_STAGE_(bufoff, gbase, voffA)
; #define PG8_STAGEB(bufoff, gbase) PG8_STAGE_(bufoff, gbase, voffB)
; #define PG8_LDA(dst, b, h) do { _Pragma("unroll") for (int m = 0; m < 4; ++m) _Pragma("unroll") for (int k = 0; k < 2; ++k) dst[m][k] = *(const LAS bf16x8*)(lds + PG8_SA(b, h) + aoff + m * 2048 + k * 1024); } while (0)
; #define PG8_LDB(dst, b, h) do { _Pragma("unroll") for (int n = 0; n < 2; ++n) _Pragma("unroll") for (int k = 0; k < 2; ++k) dst[n][k] = *(const LAS bf16x8*)(lds + PG8_SB(b, h) + boff + n * 2048 + k * 1024); } while (0)
; #define PG8_MMA(ai, bj, At, Bt_) do { __builtin_amdgcn_s_setprio(1); _Pragma("unroll") for (int m = 0; m < 4; ++m) _Pragma("unroll") for (int n = 0; n < 2; ++n) _Pragma("unroll") for (int k = 0; k < 2; ++k) \
;         acc[ai][bj][m][n] = __builtin_amdgcn_mfma_f32_16x16x32_bf16(Bt_[n][k], At[m][k], acc[ai][bj][m][n], 0, 0, 0); __builtin_amdgcn_s_setprio(0); } while (0)
; #define PG8_WAIT_V(n) asm volatile("s_waitcnt vmcnt(" #n ")" ::: "memory")
; #define PG8_WAIT_L(n) asm volatile("s_waitcnt lgkmcnt(" #n ")" ::: "memory")
; #define PG8_BAR __builtin_amdgcn_s_barrier()
; template <int EK, int SK = -1>
; __device__ __forceinline__ void gemm_phase(LAS unsigned char* lds, const bf16_t* A, const bf16_t* Bt, int nM, int N, int K, const EpiArgs& E) {
;     ...
;         const bool has_next = S.next(ui + 1, nxt);
;         const char* nA = has_next ? (const char*)A + (size_t)nxt.pm * tstep : cA; const char* nB = has_next ? (const char*)Bt + (size_t)nxt.pn * tstep : cB;
;         for (int t = 0; t < nt; t += 2) {
;             const bool last = (t == nt - 2);
;             const char* a1 = cA + (size_t)(t + 1) * kstep;
;             const char* a2 = last ? nA : cA + (size_t)(t + 2) * kstep; const char* b2 = last ? nB : cB + (size_t)(t + 2) * kstep;
;             const char* a3 = a2 + kstep; const char* b3 = b2 + kstep;
;             PG8_LDB(B0, 0, 0); PG8_LDB(B1, 0, 1); PG8_SCHED; PG8_LDA(At, 0, 0); PG8_STAGEA(PG8_SA(1, 1), a1 + hstep);
;             PG8_WAIT_V(8); PG8_WAIT_L(0); PG8_BAR; PG8_MMA(0, 0, At, B0); PG8_MMA(0, 1, At, B1); PG8_BAR; PG8_SCHED;
;             PG8_LDA(At, 0, 1); PG8_STAGEB(PG8_SB(0, 0), b2); PG8_STAGEB(PG8_SB(0, 1), b2 + hstep); PG8_STAGEA(PG8_SA(0, 0), a2);
;             PG8_WAIT_V(8); PG8_WAIT_L(0); PG8_BAR; PG8_MMA(1, 0, At, B0); PG8_MMA(1, 1, At, B1); PG8_BAR; PG8_SCHED;
.LBB0_413:
	v_add_u32_e32 v150, s95, v152
	ds_read_b128 v[156:159], v150
	ds_read_b128 v[160:163], v150 offset:1024
	ds_read_b128 v[164:167], v150 offset:2048
	ds_read_b128 v[168:171], v150 offset:3072
	v_add_u32_e32 v150, s96, v152
	s_add_u32 s59, s18, s80
	ds_read_b128 v[172:175], v150
	ds_read_b128 v[176:179], v150 offset:1024
	ds_read_b128 v[180:183], v150 offset:2048
	ds_read_b128 v[184:187], v150 offset:3072
	s_addc_u32 s73, s19, s81
	s_add_u32 s59, s59, 0x100
	s_addc_u32 s73, s73, 0
	s_add_u32 s75, s53, s80
	s_addc_u32 s82, s54, s81
	s_cmpk_eq_i32 s80, 0x700
	s_cselect_b32 s85, s40, s73
	s_cselect_b32 s84, s55, s59
	s_cselect_b32 s83, s56, s82
	s_cselect_b32 s82, s57, s75
	s_mov_b64 s[100:101], -1
	s_cmpk_lg_i32 s80, 0x700
	s_cbranch_scc1 .Lmy_mk_413
	s_not_b64 s[100:101], s[6:7]
.Lmy_mk_413:
	v_lshl_add_u64 v[150:151], v[146:147], 0, s[80:81]
	s_add_i32 m0, s15, 0xc000
	ds_read_b128 v[188:191], v154
	ds_read_b128 v[192:195], v154 offset:1024
	ds_read_b128 v[196:199], v154 offset:2048
	ds_read_b128 v[200:203], v154 offset:3072
	ds_read_b128 v[204:207], v154 offset:4096
	ds_read_b128 v[208:211], v154 offset:5120
	ds_read_b128 v[212:215], v154 offset:6144
	ds_read_b128 v[216:219], v154 offset:7168
	global_load_lds_dwordx4 v[150:151], off
	v_lshl_add_u64 v[150:151], v[148:149], 0, s[80:81]
	s_add_i32 m0, s15, 0xe000
	s_nop 0
	global_load_lds_dwordx4 v[150:151], off
	s_waitcnt vmcnt(8)
	s_waitcnt lgkmcnt(0)
	s_barrier
	s_waitcnt lgkmcnt(0)
	v_mfma_f32_16x16x32_bf16 v[126:129], v[156:159], v[188:191], v[126:129]
	v_mfma_f32_16x16x32_bf16 v[122:125], v[164:167], v[188:191], v[122:125]
	v_mfma_f32_16x16x32_bf16 v[118:121], v[156:159], v[196:199], v[118:121]
	v_mfma_f32_16x16x32_bf16 v[114:117], v[164:167], v[196:199], v[114:117]
	v_mfma_f32_16x16x32_bf16 v[110:113], v[156:159], v[204:207], v[110:113]
	v_mfma_f32_16x16x32_bf16 v[106:109], v[164:167], v[204:207], v[106:109]
	v_mfma_f32_16x16x32_bf16 v[102:105], v[156:159], v[212:215], v[102:105]
	v_mfma_f32_16x16x32_bf16 v[98:101], v[164:167], v[212:215], v[98:101]
	v_mfma_f32_16x16x32_bf16 v[126:129], v[160:163], v[192:195], v[126:129]
	v_mfma_f32_16x16x32_bf16 v[122:125], v[168:171], v[192:195], v[122:125]
	v_mfma_f32_16x16x32_bf16 v[118:121], v[160:163], v[200:203], v[118:121]
	v_mfma_f32_16x16x32_bf16 v[114:117], v[168:171], v[200:203], v[114:117]
	v_mfma_f32_16x16x32_bf16 v[110:113], v[160:163], v[208:211], v[110:113]
	v_mfma_f32_16x16x32_bf16 v[106:109], v[168:171], v[208:211], v[106:109]
	v_mfma_f32_16x16x32_bf16 v[102:105], v[160:163], v[216:219], v[102:105]
	v_mfma_f32_16x16x32_bf16 v[98:101], v[168:171], v[216:219], v[98:101]
	v_mfma_f32_16x16x32_bf16 v[94:97], v[172:175], v[188:191], v[94:97]
	v_mfma_f32_16x16x32_bf16 v[90:93], v[180:183], v[188:191], v[90:93]
	v_mfma_f32_16x16x32_bf16 v[86:89], v[172:175], v[196:199], v[86:89]
	v_mfma_f32_16x16x32_bf16 v[82:85], v[180:183], v[196:199], v[82:85]
	v_mfma_f32_16x16x32_bf16 v[78:81], v[172:175], v[204:207], v[78:81]
	v_mfma_f32_16x16x32_bf16 v[74:77], v[180:183], v[204:207], v[74:77]
	v_mfma_f32_16x16x32_bf16 v[70:73], v[172:175], v[212:215], v[70:73]
	v_mfma_f32_16x16x32_bf16 v[66:69], v[180:183], v[212:215], v[66:69]
	v_mfma_f32_16x16x32_bf16 v[94:97], v[176:179], v[192:195], v[94:97]
	v_mfma_f32_16x16x32_bf16 v[90:93], v[184:187], v[192:195], v[90:93]
	v_mfma_f32_16x16x32_bf16 v[86:89], v[176:179], v[200:203], v[86:89]
	v_mfma_f32_16x16x32_bf16 v[82:85], v[184:187], v[200:203], v[82:85]
	v_mfma_f32_16x16x32_bf16 v[78:81], v[176:179], v[208:211], v[78:81]
	v_mfma_f32_16x16x32_bf16 v[74:77], v[184:187], v[208:211], v[74:77]
	v_mfma_f32_16x16x32_bf16 v[70:73], v[176:179], v[216:219], v[70:73]
	v_mfma_f32_16x16x32_bf16 v[66:69], v[184:187], v[216:219], v[66:69]
	s_barrier
	s_add_i32 s59, s95, s88
	v_lshl_add_u64 v[150:151], s[82:83], 0, v[132:133]
	s_mov_b32 m0, s59
	ds_read_b128 v[188:191], v154 offset:16384
	ds_read_b128 v[192:195], v154 offset:17408
	ds_read_b128 v[196:199], v154 offset:18432
	ds_read_b128 v[200:203], v154 offset:19456
	ds_read_b128 v[204:207], v154 offset:20480
	ds_read_b128 v[208:211], v154 offset:21504
	ds_read_b128 v[212:215], v154 offset:22528
	ds_read_b128 v[216:219], v154 offset:23552
	s_mov_b64 exec, s[100:101]
	global_load_lds_dwordx4 v[150:151], off
	s_mov_b64 exec, -1
	s_add_i32 m0, s59, 0x2000
	s_add_u32 vcc_lo, s82, 0x40000
	v_lshl_add_u64 v[220:221], s[82:83], 0, v[136:137]
	s_addc_u32 vcc_hi, s83, 0
	s_add_i32 s59, s96, s88
	s_mov_b64 exec, s[100:101]
	global_load_lds_dwordx4 v[220:221], off
	s_mov_b64 exec, -1
	v_lshl_add_u64 v[222:223], vcc, 0, v[132:133]
	s_mov_b32 m0, s59
	v_lshl_add_u64 v[224:225], s[84:85], 0, v[134:135]
	s_mov_b64 exec, s[100:101]
	global_load_lds_dwordx4 v[222:223], off
	s_mov_b64 exec, -1
	v_lshl_add_u64 v[222:223], vcc, 0, v[136:137]
	s_add_i32 m0, s59, 0x2000
	s_nop 0
	s_mov_b64 exec, s[100:101]
	global_load_lds_dwordx4 v[222:223], off
	s_mov_b64 exec, -1
	v_lshl_add_u64 v[222:223], s[84:85], 0, v[130:131]
	s_mov_b32 m0, s15
	s_nop 0
	s_mov_b64 exec, s[100:101]
	global_load_lds_dwordx4 v[222:223], off
	s_mov_b64 exec, -1
	s_mov_b32 m0, s17
	s_nop 0
	s_mov_b64 exec, s[100:101]
	global_load_lds_dwordx4 v[224:225], off
	s_mov_b64 exec, -1
	s_waitcnt vmcnt(8)
	s_waitcnt lgkmcnt(0)
	s_barrier
; #define PG8_STAGEA(bufoff, gbase) PG8_STAGE_(bufoff, gbase, voffA)
; #define PG8_LDA(dst, b, h) do { _Pragma("unroll") for (int m = 0; m < 4; ++m) _Pragma("unroll") for (int k = 0; k < 2; ++k) dst[m][k] = *(const LAS bf16x8*)(lds + PG8_SA(b, h) + aoff + m * 2048 + k * 1024); } while (0)
; #define PG8_LDB(dst, b, h) do { _Pragma("unroll") for (int n = 0; n < 2; ++n) _Pragma("unroll") for (int k = 0; k < 2; ++k) dst[n][k] = *(const LAS bf16x8*)(lds + PG8_SB(b, h) + boff + n * 2048 + k * 1024); } while (0)
; #define PG8_MMA(ai, bj, At, Bt_) do { __builtin_amdgcn_s_setprio(1); _Pragma("unroll") for (int m = 0; m < 4; ++m) _Pragma("unroll") for (int n = 0; n < 2; ++n) _Pragma("unroll") for (int k = 0; k < 2; ++k) \
;         acc[ai][bj][m][n] = __builtin_amdgcn_mfma_f32_16x16x32_bf16(Bt_[n][k], At[m][k], acc[ai][bj][m][n], 0, 0, 0); __builtin_amdgcn_s_setprio(0); } while (0)
; #define PG8_WAIT_V(n) asm volatile("s_waitcnt vmcnt(" #n ")" ::: "memory")
; #define PG8_WAIT_L(n) asm volatile("s_waitcnt lgkmcnt(" #n ")" ::: "memory")
; #define PG8_BAR __builtin_amdgcn_s_barrier()
; #define PG8_SCHED __builtin_amdgcn_sched_barrier(0)
; template <int EK, int SK = -1>
; __device__ __forceinline__ void gemm_phase(LAS unsigned char* lds, const bf16_t* A, const bf16_t* Bt, int nM, int N, int K, const EpiArgs& E) {
;     ...
;             PG8_WAIT_V(8); PG8_WAIT_L(0); PG8_BAR; PG8_MMA(1, 0, At, B0); PG8_MMA(1, 1, At, B1); PG8_BAR; PG8_SCHED;
;             PG8_LDB(B0, 1, 0); PG8_LDB(B1, 1, 1); PG8_SCHED; PG8_LDA(At, 1, 0); PG8_STAGEA(PG8_SA(0, 1), a2 + hstep);
;             PG8_WAIT_V(8); PG8_WAIT_L(0); PG8_BAR; PG8_MMA(0, 0, At, B0); PG8_MMA(0, 1, At, B1); PG8_BAR; PG8_SCHED;
	s_waitcnt lgkmcnt(0)
	v_mfma_f32_16x16x32_bf16 v[62:65], v[156:159], v[188:191], v[62:65]
	v_mfma_f32_16x16x32_bf16 v[58:61], v[164:167], v[188:191], v[58:61]
	v_mfma_f32_16x16x32_bf16 v[54:57], v[156:159], v[196:199], v[54:57]
	v_mfma_f32_16x16x32_bf16 v[50:53], v[164:167], v[196:199], v[50:53]
	v_mfma_f32_16x16x32_bf16 v[46:49], v[156:159], v[204:207], v[46:49]
	v_mfma_f32_16x16x32_bf16 v[42:45], v[164:167], v[204:207], v[42:45]
	v_mfma_f32_16x16x32_bf16 v[38:41], v[156:159], v[212:215], v[38:41]
	v_mfma_f32_16x16x32_bf16 v[34:37], v[164:167], v[212:215], v[34:37]
	v_mfma_f32_16x16x32_bf16 v[62:65], v[160:163], v[192:195], v[62:65]
	v_mfma_f32_16x16x32_bf16 v[58:61], v[168:171], v[192:195], v[58:61]
	v_mfma_f32_16x16x32_bf16 v[54:57], v[160:163], v[200:203], v[54:57]
	v_mfma_f32_16x16x32_bf16 v[50:53], v[168:171], v[200:203], v[50:53]
	v_mfma_f32_16x16x32_bf16 v[46:49], v[160:163], v[208:211], v[46:49]
	v_mfma_f32_16x16x32_bf16 v[42:45], v[168:171], v[208:211], v[42:45]
	v_mfma_f32_16x16x32_bf16 v[38:41], v[160:163], v[216:219], v[38:41]
	v_mfma_f32_16x16x32_bf16 v[34:37], v[168:171], v[216:219], v[34:37]
	v_mfma_f32_16x16x32_bf16 v[30:33], v[172:175], v[188:191], v[30:33]
	v_mfma_f32_16x16x32_bf16 v[26:29], v[180:183], v[188:191], v[26:29]
	v_mfma_f32_16x16x32_bf16 v[22:25], v[172:175], v[196:199], v[22:25]
	v_mfma_f32_16x16x32_bf16 v[18:21], v[180:183], v[196:199], v[18:21]
	v_mfma_f32_16x16x32_bf16 v[14:17], v[172:175], v[204:207], v[14:17]
	v_mfma_f32_16x16x32_bf16 v[10:13], v[180:183], v[204:207], v[10:13]
	v_mfma_f32_16x16x32_bf16 v[6:9], v[172:175], v[212:215], v[6:9]
	v_mfma_f32_16x16x32_bf16 v[2:5], v[180:183], v[212:215], v[2:5]
	v_mfma_f32_16x16x32_bf16 v[30:33], v[176:179], v[192:195], v[30:33]
	v_mfma_f32_16x16x32_bf16 v[26:29], v[184:187], v[192:195], v[26:29]
	v_mfma_f32_16x16x32_bf16 v[22:25], v[176:179], v[200:203], v[22:25]
	v_mfma_f32_16x16x32_bf16 v[18:21], v[184:187], v[200:203], v[18:21]
	v_mfma_f32_16x16x32_bf16 v[14:17], v[176:179], v[208:211], v[14:17]
	v_mfma_f32_16x16x32_bf16 v[10:13], v[184:187], v[208:211], v[10:13]
	v_mfma_f32_16x16x32_bf16 v[6:9], v[176:179], v[216:219], v[6:9]
	v_mfma_f32_16x16x32_bf16 v[2:5], v[184:187], v[216:219], v[2:5]
	s_barrier
	s_add_i32 s59, 0, 0x18000
	s_add_i32 s73, 0, 0x1c000
	v_add_u32_e32 v168, s59, v152
	v_add_u32_e32 v184, s73, v152
	ds_read_b128 v[156:159], v168
	ds_read_b128 v[160:163], v168 offset:1024
	ds_read_b128 v[164:167], v168 offset:2048
	ds_read_b128 v[168:171], v168 offset:3072
	ds_read_b128 v[172:175], v184
	ds_read_b128 v[176:179], v184 offset:1024
	ds_read_b128 v[180:183], v184 offset:2048
	ds_read_b128 v[184:187], v184 offset:3072
	s_add_u32 s84, s84, 0x40000
	s_addc_u32 s85, s85, 0
	s_mov_b32 m0, s89
	v_lshl_add_u64 v[226:227], s[84:85], 0, v[130:131]
	ds_read_b128 v[188:191], v154 offset:32768
	ds_read_b128 v[192:195], v154 offset:33792
	ds_read_b128 v[196:199], v154 offset:34816
	ds_read_b128 v[200:203], v154 offset:35840
	ds_read_b128 v[204:207], v154 offset:36864
	ds_read_b128 v[208:211], v154 offset:37888
	ds_read_b128 v[212:215], v154 offset:38912
	ds_read_b128 v[216:219], v154 offset:39936
	s_mov_b64 exec, s[100:101]
	global_load_lds_dwordx4 v[226:227], off
	s_mov_b64 exec, -1
	v_lshl_add_u64 v[226:227], s[84:85], 0, v[134:135]
	s_mov_b32 m0, s90
	s_nop 0
	s_mov_b64 exec, s[100:101]
	global_load_lds_dwordx4 v[226:227], off
	s_mov_b64 exec, -1
	s_waitcnt vmcnt(8)
	s_waitcnt lgkmcnt(0)
	s_barrier
	s_waitcnt lgkmcnt(0)
	v_mfma_f32_16x16x32_bf16 v[126:129], v[156:159], v[188:191], v[126:129]
	v_mfma_f32_16x16x32_bf16 v[122:125], v[164:167], v[188:191], v[122:125]
	v_mfma_f32_16x16x32_bf16 v[118:121], v[156:159], v[196:199], v[118:121]
	v_mfma_f32_16x16x32_bf16 v[114:117], v[164:167], v[196:199], v[114:117]
	v_mfma_f32_16x16x32_bf16 v[110:113], v[156:159], v[204:207], v[110:113]
	v_mfma_f32_16x16x32_bf16 v[106:109], v[164:167], v[204:207], v[106:109]
	v_mfma_f32_16x16x32_bf16 v[102:105], v[156:159], v[212:215], v[102:105]
	v_mfma_f32_16x16x32_bf16 v[98:101], v[164:167], v[212:215], v[98:101]
	v_mfma_f32_16x16x32_bf16 v[126:129], v[160:163], v[192:195], v[126:129]
	v_mfma_f32_16x16x32_bf16 v[122:125], v[168:171], v[192:195], v[122:125]
	v_mfma_f32_16x16x32_bf16 v[118:121], v[160:163], v[200:203], v[118:121]
	v_mfma_f32_16x16x32_bf16 v[114:117], v[168:171], v[200:203], v[114:117]
	v_mfma_f32_16x16x32_bf16 v[110:113], v[160:163], v[208:211], v[110:113]
	v_mfma_f32_16x16x32_bf16 v[106:109], v[168:171], v[208:211], v[106:109]
	v_mfma_f32_16x16x32_bf16 v[102:105], v[160:163], v[216:219], v[102:105]
	v_mfma_f32_16x16x32_bf16 v[98:101], v[168:171], v[216:219], v[98:101]
	v_mfma_f32_16x16x32_bf16 v[94:97], v[172:175], v[188:191], v[94:97]
	v_mfma_f32_16x16x32_bf16 v[90:93], v[180:183], v[188:191], v[90:93]
	v_mfma_f32_16x16x32_bf16 v[86:89], v[172:175], v[196:199], v[86:89]
	v_mfma_f32_16x16x32_bf16 v[82:85], v[180:183], v[196:199], v[82:85]
	v_mfma_f32_16x16x32_bf16 v[78:81], v[172:175], v[204:207], v[78:81]
	v_mfma_f32_16x16x32_bf16 v[74:77], v[180:183], v[204:207], v[74:77]
	v_mfma_f32_16x16x32_bf16 v[70:73], v[172:175], v[212:215], v[70:73]
	v_mfma_f32_16x16x32_bf16 v[66:69], v[180:183], v[212:215], v[66:69]
	v_mfma_f32_16x16x32_bf16 v[94:97], v[176:179], v[192:195], v[94:97]
	v_mfma_f32_16x16x32_bf16 v[90:93], v[184:187], v[192:195], v[90:93]
	v_mfma_f32_16x16x32_bf16 v[86:89], v[176:179], v[200:203], v[86:89]
	v_mfma_f32_16x16x32_bf16 v[82:85], v[184:187], v[200:203], v[82:85]
	v_mfma_f32_16x16x32_bf16 v[78:81], v[176:179], v[208:211], v[78:81]
	v_mfma_f32_16x16x32_bf16 v[74:77], v[184:187], v[208:211], v[74:77]
	v_mfma_f32_16x16x32_bf16 v[70:73], v[176:179], v[216:219], v[70:73]
	v_mfma_f32_16x16x32_bf16 v[66:69], v[184:187], v[216:219], v[66:69]
	s_barrier
; #define PG8_STAGEA(bufoff, gbase) PG8_STAGE_(bufoff, gbase, voffA)
; #define PG8_STAGEB(bufoff, gbase) PG8_STAGE_(bufoff, gbase, voffB)
; #define PG8_LDA(dst, b, h) do { _Pragma("unroll") for (int m = 0; m < 4; ++m) _Pragma("unroll") for (int k = 0; k < 2; ++k) dst[m][k] = *(const LAS bf16x8*)(lds + PG8_SA(b, h) + aoff + m * 2048 + k * 1024); } while (0)
; #define PG8_MMA(ai, bj, At, Bt_) do { __builtin_amdgcn_s_setprio(1); _Pragma("unroll") for (int m = 0; m < 4; ++m) _Pragma("unroll") for (int n = 0; n < 2; ++n) _Pragma("unroll") for (int k = 0; k < 2; ++k) \
;         acc[ai][bj][m][n] = __builtin_amdgcn_mfma_f32_16x16x32_bf16(Bt_[n][k], At[m][k], acc[ai][bj][m][n], 0, 0, 0); __builtin_amdgcn_s_setprio(0); } while (0)
; #define PG8_WAIT_V(n) asm volatile("s_waitcnt vmcnt(" #n ")" ::: "memory")
; #define PG8_WAIT_L(n) asm volatile("s_waitcnt lgkmcnt(" #n ")" ::: "memory")
; #define PG8_BAR __builtin_amdgcn_s_barrier()
; #define PG8_SCHED __builtin_amdgcn_sched_barrier(0)
; template <int EK, int SK = -1>
; __device__ __forceinline__ void gemm_phase(LAS unsigned char* lds, const bf16_t* A, const bf16_t* Bt, int nM, int N, int K, const EpiArgs& E) {
;     ...
;             PG8_LDA(At, 1, 1); PG8_STAGEB(PG8_SB(1, 0), b3); PG8_STAGEB(PG8_SB(1, 1), b3 + hstep); PG8_STAGEA(PG8_SA(1, 0), a3);
;             PG8_WAIT_V(8); PG8_WAIT_L(0); PG8_BAR; PG8_MMA(1, 0, At, B0); PG8_MMA(1, 1, At, B1); PG8_BAR; PG8_SCHED;
	s_add_i32 s59, s59, s88
	v_lshl_add_u64 v[150:151], v[150:151], 0, s[68:69]
	s_mov_b32 m0, s59
	ds_read_b128 v[188:191], v154 offset:49152
	ds_read_b128 v[192:195], v154 offset:50176
	ds_read_b128 v[196:199], v154 offset:51200
	ds_read_b128 v[200:203], v154 offset:52224
	ds_read_b128 v[204:207], v154 offset:53248
	ds_read_b128 v[208:211], v154 offset:54272
	ds_read_b128 v[212:215], v154 offset:55296
	ds_read_b128 v[216:219], v154 offset:56320
	s_mov_b64 exec, s[100:101]
	global_load_lds_dwordx4 v[150:151], off
	s_mov_b64 exec, -1
	s_add_i32 m0, s59, 0x2000
	s_add_u32 s82, s82, 0x40080
	v_lshl_add_u64 v[150:151], v[220:221], 0, s[68:69]
	s_addc_u32 s83, s83, 0
	s_add_i32 s59, s73, s88
	s_mov_b64 exec, s[100:101]
	global_load_lds_dwordx4 v[150:151], off
	s_mov_b64 exec, -1
	v_lshl_add_u64 v[150:151], s[82:83], 0, v[132:133]
	s_mov_b32 m0, s59
	s_nop 0
	s_mov_b64 exec, s[100:101]
	global_load_lds_dwordx4 v[150:151], off
	s_mov_b64 exec, -1
	v_lshl_add_u64 v[150:151], s[82:83], 0, v[136:137]
	s_add_i32 m0, s59, 0x2000
	s_nop 0
	s_mov_b64 exec, s[100:101]
	global_load_lds_dwordx4 v[150:151], off
	s_mov_b64 exec, -1
	v_lshl_add_u64 v[150:151], v[222:223], 0, s[68:69]
	s_mov_b32 m0, s93
	s_nop 0
	s_mov_b64 exec, s[100:101]
	global_load_lds_dwordx4 v[150:151], off
	s_mov_b64 exec, -1
	v_lshl_add_u64 v[150:151], v[224:225], 0, s[68:69]
	s_mov_b32 m0, s94
	s_nop 0
	s_mov_b64 exec, s[100:101]
	global_load_lds_dwordx4 v[150:151], off
	s_mov_b64 exec, -1
	s_waitcnt vmcnt(8)
	s_waitcnt lgkmcnt(0)
	s_barrier
	s_waitcnt lgkmcnt(0)
	v_mfma_f32_16x16x32_bf16 v[62:65], v[156:159], v[188:191], v[62:65]
	v_mfma_f32_16x16x32_bf16 v[58:61], v[164:167], v[188:191], v[58:61]
	v_mfma_f32_16x16x32_bf16 v[54:57], v[156:159], v[196:199], v[54:57]
	v_mfma_f32_16x16x32_bf16 v[50:53], v[164:167], v[196:199], v[50:53]
	v_mfma_f32_16x16x32_bf16 v[46:49], v[156:159], v[204:207], v[46:49]
	v_mfma_f32_16x16x32_bf16 v[42:45], v[164:167], v[204:207], v[42:45]
	v_mfma_f32_16x16x32_bf16 v[38:41], v[156:159], v[212:215], v[38:41]
	v_mfma_f32_16x16x32_bf16 v[34:37], v[164:167], v[212:215], v[34:37]
	v_mfma_f32_16x16x32_bf16 v[62:65], v[160:163], v[192:195], v[62:65]
	v_mfma_f32_16x16x32_bf16 v[58:61], v[168:171], v[192:195], v[58:61]
	v_mfma_f32_16x16x32_bf16 v[54:57], v[160:163], v[200:203], v[54:57]
	v_mfma_f32_16x16x32_bf16 v[50:53], v[168:171], v[200:203], v[50:53]
	v_mfma_f32_16x16x32_bf16 v[46:49], v[160:163], v[208:211], v[46:49]
	v_mfma_f32_16x16x32_bf16 v[42:45], v[168:171], v[208:211], v[42:45]
	v_mfma_f32_16x16x32_bf16 v[38:41], v[160:163], v[216:219], v[38:41]
	v_mfma_f32_16x16x32_bf16 v[34:37], v[168:171], v[216:219], v[34:37]
	v_mfma_f32_16x16x32_bf16 v[30:33], v[172:175], v[188:191], v[30:33]
	v_mfma_f32_16x16x32_bf16 v[26:29], v[180:183], v[188:191], v[26:29]
	v_mfma_f32_16x16x32_bf16 v[22:25], v[172:175], v[196:199], v[22:25]
	v_mfma_f32_16x16x32_bf16 v[18:21], v[180:183], v[196:199], v[18:21]
	v_mfma_f32_16x16x32_bf16 v[14:17], v[172:175], v[204:207], v[14:17]
	v_mfma_f32_16x16x32_bf16 v[10:13], v[180:183], v[204:207], v[10:13]
	v_mfma_f32_16x16x32_bf16 v[6:9], v[172:175], v[212:215], v[6:9]
	v_mfma_f32_16x16x32_bf16 v[2:5], v[180:183], v[212:215], v[2:5]
	v_mfma_f32_16x16x32_bf16 v[30:33], v[176:179], v[192:195], v[30:33]
	v_mfma_f32_16x16x32_bf16 v[26:29], v[184:187], v[192:195], v[26:29]
	v_mfma_f32_16x16x32_bf16 v[22:25], v[176:179], v[200:203], v[22:25]
	v_mfma_f32_16x16x32_bf16 v[18:21], v[184:187], v[200:203], v[18:21]
	v_mfma_f32_16x16x32_bf16 v[14:17], v[176:179], v[208:211], v[14:17]
	v_mfma_f32_16x16x32_bf16 v[10:13], v[184:187], v[208:211], v[10:13]
	v_mfma_f32_16x16x32_bf16 v[6:9], v[176:179], v[216:219], v[6:9]
	v_mfma_f32_16x16x32_bf16 v[2:5], v[184:187], v[216:219], v[2:5]
	s_barrier
	s_add_i32 s58, s58, 2
	s_add_u32 s80, s80, 0x100
	s_addc_u32 s81, s81, 0
	s_cmp_gt_u32 s58, 13
	s_cbranch_scc0 .LBB0_413

; #define PG8_STAGEA(bufoff, gbase) PG8_STAGE_(bufoff, gbase, voffA)
; #define PG8_STAGEB(bufoff, gbase) PG8_STAGE_(bufoff, gbase, voffB)
; #define PG8_LDA(dst, b, h) do { _Pragma("unroll") for (int m = 0; m < 4; ++m) _Pragma("unroll") for (int k = 0; k < 2; ++k) dst[m][k] = *(const LAS bf16x8*)(lds + PG8_SA(b, h) + aoff + m * 2048 + k * 1024); } while (0)
; #define PG8_LDB(dst, b, h) do { _Pragma("unroll") for (int n = 0; n < 2; ++n) _Pragma("unroll") for (int k = 0; k < 2; ++k) dst[n][k] = *(const LAS bf16x8*)(lds + PG8_SB(b, h) + boff + n * 2048 + k * 1024); } while (0)
; #define PG8_MMA(ai, bj, At, Bt_) do { __builtin_amdgcn_s_setprio(1); _Pragma("unroll") for (int m = 0; m < 4; ++m) _Pragma("unroll") for (int n = 0; n < 2; ++n) _Pragma("unroll") for (int k = 0; k < 2; ++k) \
;         acc[ai][bj][m][n] = __builtin_amdgcn_mfma_f32_16x16x32_bf16(Bt_[n][k], At[m][k], acc[ai][bj][m][n], 0, 0, 0); __builtin_amdgcn_s_setprio(0); } while (0)
; #define PG8_WAIT_V(n) asm volatile("s_waitcnt vmcnt(" #n ")" ::: "memory")
; #define PG8_WAIT_L(n) asm volatile("s_waitcnt lgkmcnt(" #n ")" ::: "memory")
; #define PG8_BAR __builtin_amdgcn_s_barrier()
; template <int EK, int SK = -1>
; __device__ __forceinline__ void gemm_phase(LAS unsigned char* lds, const bf16_t* A, const bf16_t* Bt, int nM, int N, int K, const EpiArgs& E) {
;     ...
;         const bool has_next = S.next(ui + 1, nxt);
;         const char* nA = has_next ? (const char*)A + (size_t)nxt.pm * tstep : cA; const char* nB = has_next ? (const char*)Bt + (size_t)nxt.pn * tstep : cB;
;         for (int t = 0; t < nt; t += 2) {
;             const bool last = (t == nt - 2);
;             const char* a1 = cA + (size_t)(t + 1) * kstep;
;             const char* a2 = last ? nA : cA + (size_t)(t + 2) * kstep; const char* b2 = last ? nB : cB + (size_t)(t + 2) * kstep;
;             const char* a3 = a2 + kstep; const char* b3 = b2 + kstep;
;             PG8_LDB(B0, 0, 0); PG8_LDB(B1, 0, 1); PG8_SCHED; PG8_LDA(At, 0, 0); PG8_STAGEA(PG8_SA(1, 1), a1 + hstep);
;             PG8_WAIT_V(8); PG8_WAIT_L(0); PG8_BAR; PG8_MMA(0, 0, At, B0); PG8_MMA(0, 1, At, B1); PG8_BAR; PG8_SCHED;
;             PG8_LDA(At, 0, 1); PG8_STAGEB(PG8_SB(0, 0), b2); PG8_STAGEB(PG8_SB(0, 1), b2 + hstep); PG8_STAGEA(PG8_SA(0, 0), a2);
;             PG8_WAIT_V(8); PG8_WAIT_L(0); PG8_BAR; PG8_MMA(1, 0, At, B0); PG8_MMA(1, 1, At, B1); PG8_BAR; PG8_SCHED;
.LBB0_538:
	v_add_u32_e32 v154, s88, v159
	ds_read_b128 v[150:153], v154
	ds_read_b128 v[164:167], v154 offset:1024
	ds_read_b128 v[168:171], v154 offset:2048
	ds_read_b128 v[172:175], v154 offset:3072
	v_add_u32_e32 v154, s89, v159
	s_add_u32 s69, s38, s74
	ds_read_b128 v[176:179], v154
	ds_read_b128 v[180:183], v154 offset:1024
	ds_read_b128 v[184:187], v154 offset:2048
	ds_read_b128 v[188:191], v154 offset:3072
	s_addc_u32 s76, s39, s75
	s_add_u32 s69, s69, 0x100
	s_addc_u32 s76, s76, 0
	s_add_u32 s91, s54, s74
	s_addc_u32 s77, s55, s75
	s_cmpk_eq_i32 s74, 0x700
	s_cselect_b32 s79, s56, s76
	s_cselect_b32 s78, s57, s69
	s_cselect_b32 s77, s41, s77
	s_cselect_b32 s76, s58, s91
	s_mov_b64 s[100:101], -1
	s_cmpk_lg_i32 s74, 0x700
	s_cbranch_scc1 .Lmy_mk_538
	s_not_b64 s[100:101], s[4:5]
.Lmy_mk_538:
	v_lshl_add_u64 v[154:155], v[146:147], 0, s[74:75]
	s_add_i32 m0, s15, 0xc000
	ds_read_b128 v[192:195], v162
	ds_read_b128 v[196:199], v162 offset:1024
	ds_read_b128 v[200:203], v162 offset:2048
	ds_read_b128 v[204:207], v162 offset:3072
	ds_read_b128 v[208:211], v162 offset:4096
	ds_read_b128 v[212:215], v162 offset:5120
	ds_read_b128 v[216:219], v162 offset:6144
	ds_read_b128 v[220:223], v162 offset:7168
	global_load_lds_dwordx4 v[154:155], off
	v_lshl_add_u64 v[154:155], v[148:149], 0, s[74:75]
	s_add_i32 m0, s15, 0xe000
	s_nop 0
	global_load_lds_dwordx4 v[154:155], off
	s_waitcnt vmcnt(8)
	s_waitcnt lgkmcnt(0)
	s_barrier
	s_waitcnt lgkmcnt(0)
	v_mfma_f32_16x16x32_bf16 v[110:113], v[150:153], v[192:195], v[110:113]
	v_mfma_f32_16x16x32_bf16 v[106:109], v[168:171], v[192:195], v[106:109]
	v_mfma_f32_16x16x32_bf16 v[102:105], v[150:153], v[200:203], v[102:105]
	v_mfma_f32_16x16x32_bf16 v[98:101], v[168:171], v[200:203], v[98:101]
	v_mfma_f32_16x16x32_bf16 v[94:97], v[150:153], v[208:211], v[94:97]
	v_mfma_f32_16x16x32_bf16 v[90:93], v[168:171], v[208:211], v[90:93]
	v_mfma_f32_16x16x32_bf16 v[86:89], v[150:153], v[216:219], v[86:89]
	v_mfma_f32_16x16x32_bf16 v[82:85], v[168:171], v[216:219], v[82:85]
	v_mfma_f32_16x16x32_bf16 v[110:113], v[164:167], v[196:199], v[110:113]
	v_mfma_f32_16x16x32_bf16 v[106:109], v[172:175], v[196:199], v[106:109]
	v_mfma_f32_16x16x32_bf16 v[102:105], v[164:167], v[204:207], v[102:105]
	v_mfma_f32_16x16x32_bf16 v[98:101], v[172:175], v[204:207], v[98:101]
	v_mfma_f32_16x16x32_bf16 v[94:97], v[164:167], v[212:215], v[94:97]
	v_mfma_f32_16x16x32_bf16 v[90:93], v[172:175], v[212:215], v[90:93]
	v_mfma_f32_16x16x32_bf16 v[86:89], v[164:167], v[220:223], v[86:89]
	v_mfma_f32_16x16x32_bf16 v[82:85], v[172:175], v[220:223], v[82:85]
	v_mfma_f32_16x16x32_bf16 v[78:81], v[176:179], v[192:195], v[78:81]
	v_mfma_f32_16x16x32_bf16 v[74:77], v[184:187], v[192:195], v[74:77]
	v_mfma_f32_16x16x32_bf16 v[70:73], v[176:179], v[200:203], v[70:73]
	v_mfma_f32_16x16x32_bf16 v[66:69], v[184:187], v[200:203], v[66:69]
	v_mfma_f32_16x16x32_bf16 v[62:65], v[176:179], v[208:211], v[62:65]
	v_mfma_f32_16x16x32_bf16 v[58:61], v[184:187], v[208:211], v[58:61]
	v_mfma_f32_16x16x32_bf16 v[54:57], v[176:179], v[216:219], v[54:57]
	v_mfma_f32_16x16x32_bf16 v[50:53], v[184:187], v[216:219], v[50:53]
	v_mfma_f32_16x16x32_bf16 v[78:81], v[180:183], v[196:199], v[78:81]
	v_mfma_f32_16x16x32_bf16 v[74:77], v[188:191], v[196:199], v[74:77]
	v_mfma_f32_16x16x32_bf16 v[70:73], v[180:183], v[204:207], v[70:73]
	v_mfma_f32_16x16x32_bf16 v[66:69], v[188:191], v[204:207], v[66:69]
	v_mfma_f32_16x16x32_bf16 v[62:65], v[180:183], v[212:215], v[62:65]
	v_mfma_f32_16x16x32_bf16 v[58:61], v[188:191], v[212:215], v[58:61]
	v_mfma_f32_16x16x32_bf16 v[54:57], v[180:183], v[220:223], v[54:57]
	v_mfma_f32_16x16x32_bf16 v[50:53], v[188:191], v[220:223], v[50:53]
	s_barrier
	s_add_i32 s69, s88, s83
	v_lshl_add_u64 v[154:155], s[76:77], 0, v[132:133]
	s_mov_b32 m0, s69
	ds_read_b128 v[192:195], v162 offset:16384
	ds_read_b128 v[196:199], v162 offset:17408
	ds_read_b128 v[200:203], v162 offset:18432
	ds_read_b128 v[204:207], v162 offset:19456
	ds_read_b128 v[208:211], v162 offset:20480
	ds_read_b128 v[212:215], v162 offset:21504
	ds_read_b128 v[216:219], v162 offset:22528
	ds_read_b128 v[220:223], v162 offset:23552
	s_mov_b64 exec, s[100:101]
	global_load_lds_dwordx4 v[154:155], off
	s_mov_b64 exec, -1
	s_add_i32 m0, s69, 0x2000
	s_add_u32 s92, s76, 0x40000
	v_lshl_add_u64 v[224:225], s[76:77], 0, v[136:137]
	s_addc_u32 s93, s77, 0
	s_add_i32 s69, s89, s83
	s_mov_b64 exec, s[100:101]
	global_load_lds_dwordx4 v[224:225], off
	s_mov_b64 exec, -1
	v_lshl_add_u64 v[226:227], s[92:93], 0, v[132:133]
	s_mov_b32 m0, s69
	v_lshl_add_u64 v[228:229], s[78:79], 0, v[134:135]
	s_mov_b64 exec, s[100:101]
	global_load_lds_dwordx4 v[226:227], off
	s_mov_b64 exec, -1
	v_lshl_add_u64 v[226:227], s[92:93], 0, v[136:137]
	s_add_i32 m0, s69, 0x2000
	s_nop 0
	s_mov_b64 exec, s[100:101]
	global_load_lds_dwordx4 v[226:227], off
	s_mov_b64 exec, -1
	v_lshl_add_u64 v[226:227], s[78:79], 0, v[130:131]
	s_mov_b32 m0, s15
	s_nop 0
	s_mov_b64 exec, s[100:101]
	global_load_lds_dwordx4 v[226:227], off
	s_mov_b64 exec, -1
	s_mov_b32 m0, s17
	s_nop 0
	s_mov_b64 exec, s[100:101]
	global_load_lds_dwordx4 v[228:229], off
	s_mov_b64 exec, -1
	s_waitcnt vmcnt(8)
	s_waitcnt lgkmcnt(0)
	s_barrier
; #define PG8_STAGEA(bufoff, gbase) PG8_STAGE_(bufoff, gbase, voffA)
; #define PG8_LDA(dst, b, h) do { _Pragma("unroll") for (int m = 0; m < 4; ++m) _Pragma("unroll") for (int k = 0; k < 2; ++k) dst[m][k] = *(const LAS bf16x8*)(lds + PG8_SA(b, h) + aoff + m * 2048 + k * 1024); } while (0)
; #define PG8_LDB(dst, b, h) do { _Pragma("unroll") for (int n = 0; n < 2; ++n) _Pragma("unroll") for (int k = 0; k < 2; ++k) dst[n][k] = *(const LAS bf16x8*)(lds + PG8_SB(b, h) + boff + n * 2048 + k * 1024); } while (0)
; #define PG8_MMA(ai, bj, At, Bt_) do { __builtin_amdgcn_s_setprio(1); _Pragma("unroll") for (int m = 0; m < 4; ++m) _Pragma("unroll") for (int n = 0; n < 2; ++n) _Pragma("unroll") for (int k = 0; k < 2; ++k) \
;         acc[ai][bj][m][n] = __builtin_amdgcn_mfma_f32_16x16x32_bf16(Bt_[n][k], At[m][k], acc[ai][bj][m][n], 0, 0, 0); __builtin_amdgcn_s_setprio(0); } while (0)
; #define PG8_WAIT_V(n) asm volatile("s_waitcnt vmcnt(" #n ")" ::: "memory")
; #define PG8_WAIT_L(n) asm volatile("s_waitcnt lgkmcnt(" #n ")" ::: "memory")
; #define PG8_BAR __builtin_amdgcn_s_barrier()
; #define PG8_SCHED __builtin_amdgcn_sched_barrier(0)
; template <int EK, int SK = -1>
; __device__ __forceinline__ void gemm_phase(LAS unsigned char* lds, const bf16_t* A, const bf16_t* Bt, int nM, int N, int K, const EpiArgs& E) {
;     ...
;             PG8_WAIT_V(8); PG8_WAIT_L(0); PG8_BAR; PG8_MMA(1, 0, At, B0); PG8_MMA(1, 1, At, B1); PG8_BAR; PG8_SCHED;
;             PG8_LDB(B0, 1, 0); PG8_LDB(B1, 1, 1); PG8_SCHED; PG8_LDA(At, 1, 0); PG8_STAGEA(PG8_SA(0, 1), a2 + hstep);
;             PG8_WAIT_V(8); PG8_WAIT_L(0); PG8_BAR; PG8_MMA(0, 0, At, B0); PG8_MMA(0, 1, At, B1); PG8_BAR; PG8_SCHED;
	s_waitcnt lgkmcnt(0)
	v_mfma_f32_16x16x32_bf16 v[46:49], v[150:153], v[192:195], v[46:49]
	v_mfma_f32_16x16x32_bf16 v[42:45], v[168:171], v[192:195], v[42:45]
	v_mfma_f32_16x16x32_bf16 v[38:41], v[150:153], v[200:203], v[38:41]
	v_mfma_f32_16x16x32_bf16 v[34:37], v[168:171], v[200:203], v[34:37]
	v_mfma_f32_16x16x32_bf16 v[30:33], v[150:153], v[208:211], v[30:33]
	v_mfma_f32_16x16x32_bf16 v[26:29], v[168:171], v[208:211], v[26:29]
	v_mfma_f32_16x16x32_bf16 v[22:25], v[150:153], v[216:219], v[22:25]
	v_mfma_f32_16x16x32_bf16 v[18:21], v[168:171], v[216:219], v[18:21]
	v_mfma_f32_16x16x32_bf16 v[46:49], v[164:167], v[196:199], v[46:49]
	v_mfma_f32_16x16x32_bf16 v[42:45], v[172:175], v[196:199], v[42:45]
	v_mfma_f32_16x16x32_bf16 v[38:41], v[164:167], v[204:207], v[38:41]
	v_mfma_f32_16x16x32_bf16 v[34:37], v[172:175], v[204:207], v[34:37]
	v_mfma_f32_16x16x32_bf16 v[30:33], v[164:167], v[212:215], v[30:33]
	v_mfma_f32_16x16x32_bf16 v[26:29], v[172:175], v[212:215], v[26:29]
	v_mfma_f32_16x16x32_bf16 v[22:25], v[164:167], v[220:223], v[22:25]
	v_mfma_f32_16x16x32_bf16 v[18:21], v[172:175], v[220:223], v[18:21]
	v_mfma_f32_16x16x32_bf16 v[14:17], v[176:179], v[192:195], v[14:17]
	v_mfma_f32_16x16x32_bf16 v[10:13], v[184:187], v[192:195], v[10:13]
	v_mfma_f32_16x16x32_bf16 v[6:9], v[176:179], v[200:203], v[6:9]
	v_mfma_f32_16x16x32_bf16 v[2:5], v[184:187], v[200:203], v[2:5]
	v_mfma_f32_16x16x32_bf16 v[114:117], v[176:179], v[208:211], v[114:117]
	v_mfma_f32_16x16x32_bf16 v[118:121], v[184:187], v[208:211], v[118:121]
	v_mfma_f32_16x16x32_bf16 v[122:125], v[176:179], v[216:219], v[122:125]
	v_mfma_f32_16x16x32_bf16 v[126:129], v[184:187], v[216:219], v[126:129]
	v_mfma_f32_16x16x32_bf16 v[14:17], v[180:183], v[196:199], v[14:17]
	v_mfma_f32_16x16x32_bf16 v[10:13], v[188:191], v[196:199], v[10:13]
	v_mfma_f32_16x16x32_bf16 v[6:9], v[180:183], v[204:207], v[6:9]
	v_mfma_f32_16x16x32_bf16 v[2:5], v[188:191], v[204:207], v[2:5]
	v_mfma_f32_16x16x32_bf16 v[114:117], v[180:183], v[212:215], v[114:117]
	v_mfma_f32_16x16x32_bf16 v[118:121], v[188:191], v[212:215], v[118:121]
	v_mfma_f32_16x16x32_bf16 v[122:125], v[180:183], v[220:223], v[122:125]
	v_mfma_f32_16x16x32_bf16 v[126:129], v[188:191], v[220:223], v[126:129]
	s_barrier
	s_add_i32 s69, 0, 0x18000
	v_add_u32_e32 v163, s69, v159
	s_add_i32 s91, 0, 0x1c000
	ds_read_b128 v[150:153], v163
	ds_read_b128 v[164:167], v163 offset:1024
	ds_read_b128 v[168:171], v163 offset:2048
	ds_read_b128 v[172:175], v163 offset:3072
	v_add_u32_e32 v163, s91, v159
	ds_read_b128 v[176:179], v163
	ds_read_b128 v[180:183], v163 offset:1024
	ds_read_b128 v[184:187], v163 offset:2048
	ds_read_b128 v[188:191], v163 offset:3072
	s_add_u32 s78, s78, 0x40000
	s_addc_u32 s79, s79, 0
	s_mov_b32 m0, s84
	v_lshl_add_u64 v[230:231], s[78:79], 0, v[130:131]
	ds_read_b128 v[192:195], v162 offset:32768
	ds_read_b128 v[196:199], v162 offset:33792
	ds_read_b128 v[200:203], v162 offset:34816
	ds_read_b128 v[204:207], v162 offset:35840
	ds_read_b128 v[208:211], v162 offset:36864
	ds_read_b128 v[212:215], v162 offset:37888
	ds_read_b128 v[216:219], v162 offset:38912
	ds_read_b128 v[220:223], v162 offset:39936
	s_mov_b64 exec, s[100:101]
	global_load_lds_dwordx4 v[230:231], off
	s_mov_b64 exec, -1
	v_lshl_add_u64 v[230:231], s[78:79], 0, v[134:135]
	s_mov_b32 m0, s85
	s_nop 0
	s_mov_b64 exec, s[100:101]
	global_load_lds_dwordx4 v[230:231], off
	s_mov_b64 exec, -1
	s_waitcnt vmcnt(8)
	s_waitcnt lgkmcnt(0)
	s_barrier
	s_waitcnt lgkmcnt(0)
	v_mfma_f32_16x16x32_bf16 v[110:113], v[150:153], v[192:195], v[110:113]
	v_mfma_f32_16x16x32_bf16 v[106:109], v[168:171], v[192:195], v[106:109]
	v_mfma_f32_16x16x32_bf16 v[102:105], v[150:153], v[200:203], v[102:105]
	v_mfma_f32_16x16x32_bf16 v[98:101], v[168:171], v[200:203], v[98:101]
	v_mfma_f32_16x16x32_bf16 v[94:97], v[150:153], v[208:211], v[94:97]
	v_mfma_f32_16x16x32_bf16 v[90:93], v[168:171], v[208:211], v[90:93]
	v_mfma_f32_16x16x32_bf16 v[86:89], v[150:153], v[216:219], v[86:89]
	v_mfma_f32_16x16x32_bf16 v[82:85], v[168:171], v[216:219], v[82:85]
	v_mfma_f32_16x16x32_bf16 v[110:113], v[164:167], v[196:199], v[110:113]
	v_mfma_f32_16x16x32_bf16 v[106:109], v[172:175], v[196:199], v[106:109]
	v_mfma_f32_16x16x32_bf16 v[102:105], v[164:167], v[204:207], v[102:105]
	v_mfma_f32_16x16x32_bf16 v[98:101], v[172:175], v[204:207], v[98:101]
	v_mfma_f32_16x16x32_bf16 v[94:97], v[164:167], v[212:215], v[94:97]
	v_mfma_f32_16x16x32_bf16 v[90:93], v[172:175], v[212:215], v[90:93]
	v_mfma_f32_16x16x32_bf16 v[86:89], v[164:167], v[220:223], v[86:89]
	v_mfma_f32_16x16x32_bf16 v[82:85], v[172:175], v[220:223], v[82:85]
	v_mfma_f32_16x16x32_bf16 v[78:81], v[176:179], v[192:195], v[78:81]
	v_mfma_f32_16x16x32_bf16 v[74:77], v[184:187], v[192:195], v[74:77]
	v_mfma_f32_16x16x32_bf16 v[70:73], v[176:179], v[200:203], v[70:73]
	v_mfma_f32_16x16x32_bf16 v[66:69], v[184:187], v[200:203], v[66:69]
	v_mfma_f32_16x16x32_bf16 v[62:65], v[176:179], v[208:211], v[62:65]
	v_mfma_f32_16x16x32_bf16 v[58:61], v[184:187], v[208:211], v[58:61]
	v_mfma_f32_16x16x32_bf16 v[54:57], v[176:179], v[216:219], v[54:57]
	v_mfma_f32_16x16x32_bf16 v[50:53], v[184:187], v[216:219], v[50:53]
	v_mfma_f32_16x16x32_bf16 v[78:81], v[180:183], v[196:199], v[78:81]
	v_mfma_f32_16x16x32_bf16 v[74:77], v[188:191], v[196:199], v[74:77]
	v_mfma_f32_16x16x32_bf16 v[70:73], v[180:183], v[204:207], v[70:73]
	v_mfma_f32_16x16x32_bf16 v[66:69], v[188:191], v[204:207], v[66:69]
	v_mfma_f32_16x16x32_bf16 v[62:65], v[180:183], v[212:215], v[62:65]
	v_mfma_f32_16x16x32_bf16 v[58:61], v[188:191], v[212:215], v[58:61]
	v_mfma_f32_16x16x32_bf16 v[54:57], v[180:183], v[220:223], v[54:57]
	v_mfma_f32_16x16x32_bf16 v[50:53], v[188:191], v[220:223], v[50:53]
	s_barrier
; #define PG8_STAGEA(bufoff, gbase) PG8_STAGE_(bufoff, gbase, voffA)
; #define PG8_STAGEB(bufoff, gbase) PG8_STAGE_(bufoff, gbase, voffB)
; #define PG8_LDA(dst, b, h) do { _Pragma("unroll") for (int m = 0; m < 4; ++m) _Pragma("unroll") for (int k = 0; k < 2; ++k) dst[m][k] = *(const LAS bf16x8*)(lds + PG8_SA(b, h) + aoff + m * 2048 + k * 1024); } while (0)
; #define PG8_MMA(ai, bj, At, Bt_) do { __builtin_amdgcn_s_setprio(1); _Pragma("unroll") for (int m = 0; m < 4; ++m) _Pragma("unroll") for (int n = 0; n < 2; ++n) _Pragma("unroll") for (int k = 0; k < 2; ++k) \
;         acc[ai][bj][m][n] = __builtin_amdgcn_mfma_f32_16x16x32_bf16(Bt_[n][k], At[m][k], acc[ai][bj][m][n], 0, 0, 0); __builtin_amdgcn_s_setprio(0); } while (0)
; #define PG8_WAIT_V(n) asm volatile("s_waitcnt vmcnt(" #n ")" ::: "memory")
; #define PG8_WAIT_L(n) asm volatile("s_waitcnt lgkmcnt(" #n ")" ::: "memory")
; #define PG8_BAR __builtin_amdgcn_s_barrier()
; #define PG8_SCHED __builtin_amdgcn_sched_barrier(0)
; template <int EK, int SK = -1>
; __device__ __forceinline__ void gemm_phase(LAS unsigned char* lds, const bf16_t* A, const bf16_t* Bt, int nM, int N, int K, const EpiArgs& E) {
;     ...
;             PG8_LDA(At, 1, 1); PG8_STAGEB(PG8_SB(1, 0), b3); PG8_STAGEB(PG8_SB(1, 1), b3 + hstep); PG8_STAGEA(PG8_SA(1, 0), a3);
;             PG8_WAIT_V(8); PG8_WAIT_L(0); PG8_BAR; PG8_MMA(1, 0, At, B0); PG8_MMA(1, 1, At, B1); PG8_BAR; PG8_SCHED;
	s_add_i32 s69, s69, s83
	v_lshl_add_u64 v[154:155], v[154:155], 0, s[10:11]
	s_mov_b32 m0, s69
	ds_read_b128 v[192:195], v162 offset:49152
	ds_read_b128 v[196:199], v162 offset:50176
	ds_read_b128 v[200:203], v162 offset:51200
	ds_read_b128 v[204:207], v162 offset:52224
	ds_read_b128 v[208:211], v162 offset:53248
	ds_read_b128 v[212:215], v162 offset:54272
	ds_read_b128 v[216:219], v162 offset:55296
	ds_read_b128 v[220:223], v162 offset:56320
	s_mov_b64 exec, s[100:101]
	global_load_lds_dwordx4 v[154:155], off
	s_mov_b64 exec, -1
	s_add_i32 m0, s69, 0x2000
	s_add_u32 s76, s76, 0x40080
	v_lshl_add_u64 v[154:155], v[224:225], 0, s[10:11]
	s_addc_u32 s77, s77, 0
	s_add_i32 s69, s91, s83
	s_mov_b64 exec, s[100:101]
	global_load_lds_dwordx4 v[154:155], off
	s_mov_b64 exec, -1
	v_lshl_add_u64 v[154:155], s[76:77], 0, v[132:133]
	s_mov_b32 m0, s69
	s_nop 0
	s_mov_b64 exec, s[100:101]
	global_load_lds_dwordx4 v[154:155], off
	s_mov_b64 exec, -1
	v_lshl_add_u64 v[154:155], s[76:77], 0, v[136:137]
	s_add_i32 m0, s69, 0x2000
	s_nop 0
	s_mov_b64 exec, s[100:101]
	global_load_lds_dwordx4 v[154:155], off
	s_mov_b64 exec, -1
	v_lshl_add_u64 v[154:155], v[226:227], 0, s[10:11]
	s_mov_b32 m0, s86
	s_nop 0
	s_mov_b64 exec, s[100:101]
	global_load_lds_dwordx4 v[154:155], off
	s_mov_b64 exec, -1
	v_lshl_add_u64 v[154:155], v[228:229], 0, s[10:11]
	s_mov_b32 m0, s87
	s_nop 0
	s_mov_b64 exec, s[100:101]
	global_load_lds_dwordx4 v[154:155], off
	s_mov_b64 exec, -1
	s_waitcnt vmcnt(8)
	s_waitcnt lgkmcnt(0)
	s_barrier
	s_waitcnt lgkmcnt(0)
	v_mfma_f32_16x16x32_bf16 v[46:49], v[150:153], v[192:195], v[46:49]
	v_mfma_f32_16x16x32_bf16 v[42:45], v[168:171], v[192:195], v[42:45]
	v_mfma_f32_16x16x32_bf16 v[38:41], v[150:153], v[200:203], v[38:41]
	v_mfma_f32_16x16x32_bf16 v[34:37], v[168:171], v[200:203], v[34:37]
	v_mfma_f32_16x16x32_bf16 v[30:33], v[150:153], v[208:211], v[30:33]
	v_mfma_f32_16x16x32_bf16 v[26:29], v[168:171], v[208:211], v[26:29]
	v_mfma_f32_16x16x32_bf16 v[22:25], v[150:153], v[216:219], v[22:25]
	v_mfma_f32_16x16x32_bf16 v[18:21], v[168:171], v[216:219], v[18:21]
	v_mfma_f32_16x16x32_bf16 v[46:49], v[164:167], v[196:199], v[46:49]
	v_mfma_f32_16x16x32_bf16 v[42:45], v[172:175], v[196:199], v[42:45]
	v_mfma_f32_16x16x32_bf16 v[38:41], v[164:167], v[204:207], v[38:41]
	v_mfma_f32_16x16x32_bf16 v[34:37], v[172:175], v[204:207], v[34:37]
	v_mfma_f32_16x16x32_bf16 v[30:33], v[164:167], v[212:215], v[30:33]
	v_mfma_f32_16x16x32_bf16 v[26:29], v[172:175], v[212:215], v[26:29]
	v_mfma_f32_16x16x32_bf16 v[22:25], v[164:167], v[220:223], v[22:25]
	v_mfma_f32_16x16x32_bf16 v[18:21], v[172:175], v[220:223], v[18:21]
	v_mfma_f32_16x16x32_bf16 v[14:17], v[176:179], v[192:195], v[14:17]
	v_mfma_f32_16x16x32_bf16 v[10:13], v[184:187], v[192:195], v[10:13]
	v_mfma_f32_16x16x32_bf16 v[6:9], v[176:179], v[200:203], v[6:9]
	v_mfma_f32_16x16x32_bf16 v[2:5], v[184:187], v[200:203], v[2:5]
	v_mfma_f32_16x16x32_bf16 v[114:117], v[176:179], v[208:211], v[114:117]
	v_mfma_f32_16x16x32_bf16 v[118:121], v[184:187], v[208:211], v[118:121]
	v_mfma_f32_16x16x32_bf16 v[122:125], v[176:179], v[216:219], v[122:125]
	v_mfma_f32_16x16x32_bf16 v[126:129], v[184:187], v[216:219], v[126:129]
	v_mfma_f32_16x16x32_bf16 v[14:17], v[180:183], v[196:199], v[14:17]
	v_mfma_f32_16x16x32_bf16 v[10:13], v[188:191], v[196:199], v[10:13]
	v_mfma_f32_16x16x32_bf16 v[6:9], v[180:183], v[204:207], v[6:9]
	v_mfma_f32_16x16x32_bf16 v[2:5], v[188:191], v[204:207], v[2:5]
	v_mfma_f32_16x16x32_bf16 v[114:117], v[180:183], v[212:215], v[114:117]
	v_mfma_f32_16x16x32_bf16 v[118:121], v[188:191], v[212:215], v[118:121]
	v_mfma_f32_16x16x32_bf16 v[122:125], v[180:183], v[220:223], v[122:125]
	v_mfma_f32_16x16x32_bf16 v[126:129], v[188:191], v[220:223], v[126:129]
	s_barrier
	s_add_i32 s59, s59, 2
	s_add_u32 s74, s74, 0x100
	s_addc_u32 s75, s75, 0
	s_cmp_gt_u32 s59, 13
	s_cbranch_scc0 .LBB0_538

; #define PG8_STAGEA(bufoff, gbase) PG8_STAGE_(bufoff, gbase, voffA)
; #define PG8_STAGEB(bufoff, gbase) PG8_STAGE_(bufoff, gbase, voffB)
; #define PG8_LDA(dst, b, h) do { _Pragma("unroll") for (int m = 0; m < 4; ++m) _Pragma("unroll") for (int k = 0; k < 2; ++k) dst[m][k] = *(const LAS bf16x8*)(lds + PG8_SA(b, h) + aoff + m * 2048 + k * 1024); } while (0)
; #define PG8_LDB(dst, b, h) do { _Pragma("unroll") for (int n = 0; n < 2; ++n) _Pragma("unroll") for (int k = 0; k < 2; ++k) dst[n][k] = *(const LAS bf16x8*)(lds + PG8_SB(b, h) + boff + n * 2048 + k * 1024); } while (0)
; #define PG8_MMA(ai, bj, At, Bt_) do { __builtin_amdgcn_s_setprio(1); _Pragma("unroll") for (int m = 0; m < 4; ++m) _Pragma("unroll") for (int n = 0; n < 2; ++n) _Pragma("unroll") for (int k = 0; k < 2; ++k) \
;         acc[ai][bj][m][n] = __builtin_amdgcn_mfma_f32_16x16x32_bf16(Bt_[n][k], At[m][k], acc[ai][bj][m][n], 0, 0, 0); __builtin_amdgcn_s_setprio(0); } while (0)
; #define PG8_WAIT_V(n) asm volatile("s_waitcnt vmcnt(" #n ")" ::: "memory")
; #define PG8_WAIT_L(n) asm volatile("s_waitcnt lgkmcnt(" #n ")" ::: "memory")
; #define PG8_BAR __builtin_amdgcn_s_barrier()
; template <int EK, int SK = -1>
; __device__ __forceinline__ void gemm_phase(LAS unsigned char* lds, const bf16_t* A, const bf16_t* Bt, int nM, int N, int K, const EpiArgs& E) {
;     ...
;         const bool has_next = S.next(ui + 1, nxt);
;         const char* nA = has_next ? (const char*)A + (size_t)nxt.pm * tstep : cA; const char* nB = has_next ? (const char*)Bt + (size_t)nxt.pn * tstep : cB;
;         for (int t = 0; t < nt; t += 2) {
;             const bool last = (t == nt - 2);
;             const char* a1 = cA + (size_t)(t + 1) * kstep;
;             const char* a2 = last ? nA : cA + (size_t)(t + 2) * kstep; const char* b2 = last ? nB : cB + (size_t)(t + 2) * kstep;
;             const char* a3 = a2 + kstep; const char* b3 = b2 + kstep;
;             PG8_LDB(B0, 0, 0); PG8_LDB(B1, 0, 1); PG8_SCHED; PG8_LDA(At, 0, 0); PG8_STAGEA(PG8_SA(1, 1), a1 + hstep);
;             PG8_WAIT_V(8); PG8_WAIT_L(0); PG8_BAR; PG8_MMA(0, 0, At, B0); PG8_MMA(0, 1, At, B1); PG8_BAR; PG8_SCHED;
;             PG8_LDA(At, 0, 1); PG8_STAGEB(PG8_SB(0, 0), b2); PG8_STAGEB(PG8_SB(0, 1), b2 + hstep); PG8_STAGEA(PG8_SA(0, 0), a2);
;             PG8_WAIT_V(8); PG8_WAIT_L(0); PG8_BAR; PG8_MMA(1, 0, At, B0); PG8_MMA(1, 1, At, B1); PG8_BAR; PG8_SCHED;
.LBB0_793:
	v_add_u32_e32 v150, s71, v152
	ds_read_b128 v[156:159], v150
	ds_read_b128 v[160:163], v150 offset:1024
	ds_read_b128 v[164:167], v150 offset:2048
	ds_read_b128 v[168:171], v150 offset:3072
	v_add_u32_e32 v150, s72, v152
	s_add_u32 s40, s14, s38
	ds_read_b128 v[172:175], v150
	ds_read_b128 v[176:179], v150 offset:1024
	ds_read_b128 v[180:183], v150 offset:2048
	ds_read_b128 v[184:187], v150 offset:3072
	s_addc_u32 s41, s15, s39
	s_add_u32 s40, s40, 0x100
	s_addc_u32 s41, s41, 0
	s_add_u32 s79, s77, s38
	s_addc_u32 s80, s78, s39
	s_cmpk_eq_i32 s38, 0x1500
	s_cselect_b32 s43, s37, s41
	s_cselect_b32 s42, s36, s40
	s_cselect_b32 s41, s11, s80
	s_cselect_b32 s40, s10, s79
	s_mov_b64 s[100:101], -1
	s_cmpk_lg_i32 s38, 0x1500
	s_cbranch_scc1 .Lmy_mk_793
	s_not_b64 s[100:101], s[6:7]
.Lmy_mk_793:
	v_lshl_add_u64 v[150:151], v[146:147], 0, s[38:39]
	s_add_i32 m0, s55, 0xc000
	ds_read_b128 v[188:191], v154
	ds_read_b128 v[192:195], v154 offset:1024
	ds_read_b128 v[196:199], v154 offset:2048
	ds_read_b128 v[200:203], v154 offset:3072
	ds_read_b128 v[204:207], v154 offset:4096
	ds_read_b128 v[208:211], v154 offset:5120
	ds_read_b128 v[212:215], v154 offset:6144
	ds_read_b128 v[216:219], v154 offset:7168
	global_load_lds_dwordx4 v[150:151], off
	v_lshl_add_u64 v[150:151], v[148:149], 0, s[38:39]
	s_add_i32 m0, s55, 0xe000
	s_nop 0
	global_load_lds_dwordx4 v[150:151], off
	s_waitcnt vmcnt(8)
	s_waitcnt lgkmcnt(0)
	s_barrier
	s_waitcnt lgkmcnt(0)
	v_mfma_f32_16x16x32_bf16 v[126:129], v[156:159], v[188:191], v[126:129]
	v_mfma_f32_16x16x32_bf16 v[122:125], v[164:167], v[188:191], v[122:125]
	v_mfma_f32_16x16x32_bf16 v[118:121], v[156:159], v[196:199], v[118:121]
	v_mfma_f32_16x16x32_bf16 v[114:117], v[164:167], v[196:199], v[114:117]
	v_mfma_f32_16x16x32_bf16 v[110:113], v[156:159], v[204:207], v[110:113]
	v_mfma_f32_16x16x32_bf16 v[106:109], v[164:167], v[204:207], v[106:109]
	v_mfma_f32_16x16x32_bf16 v[102:105], v[156:159], v[212:215], v[102:105]
	v_mfma_f32_16x16x32_bf16 v[98:101], v[164:167], v[212:215], v[98:101]
	v_mfma_f32_16x16x32_bf16 v[126:129], v[160:163], v[192:195], v[126:129]
	v_mfma_f32_16x16x32_bf16 v[122:125], v[168:171], v[192:195], v[122:125]
	v_mfma_f32_16x16x32_bf16 v[118:121], v[160:163], v[200:203], v[118:121]
	v_mfma_f32_16x16x32_bf16 v[114:117], v[168:171], v[200:203], v[114:117]
	v_mfma_f32_16x16x32_bf16 v[110:113], v[160:163], v[208:211], v[110:113]
	v_mfma_f32_16x16x32_bf16 v[106:109], v[168:171], v[208:211], v[106:109]
	v_mfma_f32_16x16x32_bf16 v[102:105], v[160:163], v[216:219], v[102:105]
	v_mfma_f32_16x16x32_bf16 v[98:101], v[168:171], v[216:219], v[98:101]
	v_mfma_f32_16x16x32_bf16 v[94:97], v[172:175], v[188:191], v[94:97]
	v_mfma_f32_16x16x32_bf16 v[90:93], v[180:183], v[188:191], v[90:93]
	v_mfma_f32_16x16x32_bf16 v[86:89], v[172:175], v[196:199], v[86:89]
	v_mfma_f32_16x16x32_bf16 v[82:85], v[180:183], v[196:199], v[82:85]
	v_mfma_f32_16x16x32_bf16 v[78:81], v[172:175], v[204:207], v[78:81]
	v_mfma_f32_16x16x32_bf16 v[74:77], v[180:183], v[204:207], v[74:77]
	v_mfma_f32_16x16x32_bf16 v[70:73], v[172:175], v[212:215], v[70:73]
	v_mfma_f32_16x16x32_bf16 v[66:69], v[180:183], v[212:215], v[66:69]
	v_mfma_f32_16x16x32_bf16 v[94:97], v[176:179], v[192:195], v[94:97]
	v_mfma_f32_16x16x32_bf16 v[90:93], v[184:187], v[192:195], v[90:93]
	v_mfma_f32_16x16x32_bf16 v[86:89], v[176:179], v[200:203], v[86:89]
	v_mfma_f32_16x16x32_bf16 v[82:85], v[184:187], v[200:203], v[82:85]
	v_mfma_f32_16x16x32_bf16 v[78:81], v[176:179], v[208:211], v[78:81]
	v_mfma_f32_16x16x32_bf16 v[74:77], v[184:187], v[208:211], v[74:77]
	v_mfma_f32_16x16x32_bf16 v[70:73], v[176:179], v[216:219], v[70:73]
	v_mfma_f32_16x16x32_bf16 v[66:69], v[184:187], v[216:219], v[66:69]
	s_barrier
	s_add_i32 s79, s71, s54
	v_lshl_add_u64 v[150:151], s[40:41], 0, v[132:133]
	s_mov_b32 m0, s79
	ds_read_b128 v[188:191], v154 offset:16384
	ds_read_b128 v[192:195], v154 offset:17408
	ds_read_b128 v[196:199], v154 offset:18432
	ds_read_b128 v[200:203], v154 offset:19456
	ds_read_b128 v[204:207], v154 offset:20480
	ds_read_b128 v[208:211], v154 offset:21504
	ds_read_b128 v[212:215], v154 offset:22528
	ds_read_b128 v[216:219], v154 offset:23552
	s_mov_b64 exec, s[100:101]
	global_load_lds_dwordx4 v[150:151], off
	s_mov_b64 exec, -1
	s_add_i32 m0, s79, 0x2000
	s_add_u32 s80, s40, 0xb0000
	v_lshl_add_u64 v[220:221], s[40:41], 0, v[136:137]
	s_addc_u32 s81, s41, 0
	s_add_i32 s79, s72, s54
	s_mov_b64 exec, s[100:101]
	global_load_lds_dwordx4 v[220:221], off
	s_mov_b64 exec, -1
	v_lshl_add_u64 v[222:223], s[80:81], 0, v[132:133]
	s_mov_b32 m0, s79
	v_lshl_add_u64 v[224:225], s[42:43], 0, v[134:135]
	s_mov_b64 exec, s[100:101]
	global_load_lds_dwordx4 v[222:223], off
	s_mov_b64 exec, -1
	v_lshl_add_u64 v[222:223], s[80:81], 0, v[136:137]
	s_add_i32 m0, s79, 0x2000
	s_nop 0
	s_mov_b64 exec, s[100:101]
	global_load_lds_dwordx4 v[222:223], off
	s_mov_b64 exec, -1
	v_lshl_add_u64 v[222:223], s[42:43], 0, v[130:131]
	s_mov_b32 m0, s55
	s_nop 0
	s_mov_b64 exec, s[100:101]
	global_load_lds_dwordx4 v[222:223], off
	s_mov_b64 exec, -1
	s_mov_b32 m0, s56
	s_nop 0
	s_mov_b64 exec, s[100:101]
	global_load_lds_dwordx4 v[224:225], off
	s_mov_b64 exec, -1
	s_waitcnt vmcnt(8)
	s_waitcnt lgkmcnt(0)
	s_barrier
; #define PG8_STAGEA(bufoff, gbase) PG8_STAGE_(bufoff, gbase, voffA)
; #define PG8_LDA(dst, b, h) do { _Pragma("unroll") for (int m = 0; m < 4; ++m) _Pragma("unroll") for (int k = 0; k < 2; ++k) dst[m][k] = *(const LAS bf16x8*)(lds + PG8_SA(b, h) + aoff + m * 2048 + k * 1024); } while (0)
; #define PG8_LDB(dst, b, h) do { _Pragma("unroll") for (int n = 0; n < 2; ++n) _Pragma("unroll") for (int k = 0; k < 2; ++k) dst[n][k] = *(const LAS bf16x8*)(lds + PG8_SB(b, h) + boff + n * 2048 + k * 1024); } while (0)
; #define PG8_MMA(ai, bj, At, Bt_) do { __builtin_amdgcn_s_setprio(1); _Pragma("unroll") for (int m = 0; m < 4; ++m) _Pragma("unroll") for (int n = 0; n < 2; ++n) _Pragma("unroll") for (int k = 0; k < 2; ++k) \
;         acc[ai][bj][m][n] = __builtin_amdgcn_mfma_f32_16x16x32_bf16(Bt_[n][k], At[m][k], acc[ai][bj][m][n], 0, 0, 0); __builtin_amdgcn_s_setprio(0); } while (0)
; #define PG8_WAIT_V(n) asm volatile("s_waitcnt vmcnt(" #n ")" ::: "memory")
; #define PG8_WAIT_L(n) asm volatile("s_waitcnt lgkmcnt(" #n ")" ::: "memory")
; #define PG8_BAR __builtin_amdgcn_s_barrier()
; #define PG8_SCHED __builtin_amdgcn_sched_barrier(0)
; template <int EK, int SK = -1>
; __device__ __forceinline__ void gemm_phase(LAS unsigned char* lds, const bf16_t* A, const bf16_t* Bt, int nM, int N, int K, const EpiArgs& E) {
;     ...
;             PG8_WAIT_V(8); PG8_WAIT_L(0); PG8_BAR; PG8_MMA(1, 0, At, B0); PG8_MMA(1, 1, At, B1); PG8_BAR; PG8_SCHED;
;             PG8_LDB(B0, 1, 0); PG8_LDB(B1, 1, 1); PG8_SCHED; PG8_LDA(At, 1, 0); PG8_STAGEA(PG8_SA(0, 1), a2 + hstep);
;             PG8_WAIT_V(8); PG8_WAIT_L(0); PG8_BAR; PG8_MMA(0, 0, At, B0); PG8_MMA(0, 1, At, B1); PG8_BAR; PG8_SCHED;
	s_waitcnt lgkmcnt(0)
	v_mfma_f32_16x16x32_bf16 v[62:65], v[156:159], v[188:191], v[62:65]
	v_mfma_f32_16x16x32_bf16 v[58:61], v[164:167], v[188:191], v[58:61]
	v_mfma_f32_16x16x32_bf16 v[54:57], v[156:159], v[196:199], v[54:57]
	v_mfma_f32_16x16x32_bf16 v[50:53], v[164:167], v[196:199], v[50:53]
	v_mfma_f32_16x16x32_bf16 v[46:49], v[156:159], v[204:207], v[46:49]
	v_mfma_f32_16x16x32_bf16 v[42:45], v[164:167], v[204:207], v[42:45]
	v_mfma_f32_16x16x32_bf16 v[38:41], v[156:159], v[212:215], v[38:41]
	v_mfma_f32_16x16x32_bf16 v[34:37], v[164:167], v[212:215], v[34:37]
	v_mfma_f32_16x16x32_bf16 v[62:65], v[160:163], v[192:195], v[62:65]
	v_mfma_f32_16x16x32_bf16 v[58:61], v[168:171], v[192:195], v[58:61]
	v_mfma_f32_16x16x32_bf16 v[54:57], v[160:163], v[200:203], v[54:57]
	v_mfma_f32_16x16x32_bf16 v[50:53], v[168:171], v[200:203], v[50:53]
	v_mfma_f32_16x16x32_bf16 v[46:49], v[160:163], v[208:211], v[46:49]
	v_mfma_f32_16x16x32_bf16 v[42:45], v[168:171], v[208:211], v[42:45]
	v_mfma_f32_16x16x32_bf16 v[38:41], v[160:163], v[216:219], v[38:41]
	v_mfma_f32_16x16x32_bf16 v[34:37], v[168:171], v[216:219], v[34:37]
	v_mfma_f32_16x16x32_bf16 v[30:33], v[172:175], v[188:191], v[30:33]
	v_mfma_f32_16x16x32_bf16 v[26:29], v[180:183], v[188:191], v[26:29]
	v_mfma_f32_16x16x32_bf16 v[22:25], v[172:175], v[196:199], v[22:25]
	v_mfma_f32_16x16x32_bf16 v[18:21], v[180:183], v[196:199], v[18:21]
	v_mfma_f32_16x16x32_bf16 v[14:17], v[172:175], v[204:207], v[14:17]
	v_mfma_f32_16x16x32_bf16 v[10:13], v[180:183], v[204:207], v[10:13]
	v_mfma_f32_16x16x32_bf16 v[6:9], v[172:175], v[212:215], v[6:9]
	v_mfma_f32_16x16x32_bf16 v[2:5], v[180:183], v[212:215], v[2:5]
	v_mfma_f32_16x16x32_bf16 v[30:33], v[176:179], v[192:195], v[30:33]
	v_mfma_f32_16x16x32_bf16 v[26:29], v[184:187], v[192:195], v[26:29]
	v_mfma_f32_16x16x32_bf16 v[22:25], v[176:179], v[200:203], v[22:25]
	v_mfma_f32_16x16x32_bf16 v[18:21], v[184:187], v[200:203], v[18:21]
	v_mfma_f32_16x16x32_bf16 v[14:17], v[176:179], v[208:211], v[14:17]
	v_mfma_f32_16x16x32_bf16 v[10:13], v[184:187], v[208:211], v[10:13]
	v_mfma_f32_16x16x32_bf16 v[6:9], v[176:179], v[216:219], v[6:9]
	v_mfma_f32_16x16x32_bf16 v[2:5], v[184:187], v[216:219], v[2:5]
	s_barrier
	s_add_i32 s79, 0, 0x18000
	s_add_i32 s80, 0, 0x1c000
	v_add_u32_e32 v168, s79, v152
	v_add_u32_e32 v184, s80, v152
	ds_read_b128 v[156:159], v168
	ds_read_b128 v[160:163], v168 offset:1024
	ds_read_b128 v[164:167], v168 offset:2048
	ds_read_b128 v[168:171], v168 offset:3072
	ds_read_b128 v[172:175], v184
	ds_read_b128 v[176:179], v184 offset:1024
	ds_read_b128 v[180:183], v184 offset:2048
	ds_read_b128 v[184:187], v184 offset:3072
	s_add_u32 s42, s42, 0xb0000
	s_addc_u32 s43, s43, 0
	s_mov_b32 m0, s57
	v_lshl_add_u64 v[226:227], s[42:43], 0, v[130:131]
	ds_read_b128 v[188:191], v154 offset:32768
	ds_read_b128 v[192:195], v154 offset:33792
	ds_read_b128 v[196:199], v154 offset:34816
	ds_read_b128 v[200:203], v154 offset:35840
	ds_read_b128 v[204:207], v154 offset:36864
	ds_read_b128 v[208:211], v154 offset:37888
	ds_read_b128 v[212:215], v154 offset:38912
	ds_read_b128 v[216:219], v154 offset:39936
	s_mov_b64 exec, s[100:101]
	global_load_lds_dwordx4 v[226:227], off
	s_mov_b64 exec, -1
	v_lshl_add_u64 v[226:227], s[42:43], 0, v[134:135]
	s_mov_b32 m0, s58
	s_nop 0
	s_mov_b64 exec, s[100:101]
	global_load_lds_dwordx4 v[226:227], off
	s_mov_b64 exec, -1
	s_waitcnt vmcnt(8)
	s_waitcnt lgkmcnt(0)
	s_barrier
	s_waitcnt lgkmcnt(0)
	v_mfma_f32_16x16x32_bf16 v[126:129], v[156:159], v[188:191], v[126:129]
	v_mfma_f32_16x16x32_bf16 v[122:125], v[164:167], v[188:191], v[122:125]
	v_mfma_f32_16x16x32_bf16 v[118:121], v[156:159], v[196:199], v[118:121]
	v_mfma_f32_16x16x32_bf16 v[114:117], v[164:167], v[196:199], v[114:117]
	v_mfma_f32_16x16x32_bf16 v[110:113], v[156:159], v[204:207], v[110:113]
	v_mfma_f32_16x16x32_bf16 v[106:109], v[164:167], v[204:207], v[106:109]
	v_mfma_f32_16x16x32_bf16 v[102:105], v[156:159], v[212:215], v[102:105]
	v_mfma_f32_16x16x32_bf16 v[98:101], v[164:167], v[212:215], v[98:101]
	v_mfma_f32_16x16x32_bf16 v[126:129], v[160:163], v[192:195], v[126:129]
	v_mfma_f32_16x16x32_bf16 v[122:125], v[168:171], v[192:195], v[122:125]
	v_mfma_f32_16x16x32_bf16 v[118:121], v[160:163], v[200:203], v[118:121]
	v_mfma_f32_16x16x32_bf16 v[114:117], v[168:171], v[200:203], v[114:117]
	v_mfma_f32_16x16x32_bf16 v[110:113], v[160:163], v[208:211], v[110:113]
	v_mfma_f32_16x16x32_bf16 v[106:109], v[168:171], v[208:211], v[106:109]
	v_mfma_f32_16x16x32_bf16 v[102:105], v[160:163], v[216:219], v[102:105]
	v_mfma_f32_16x16x32_bf16 v[98:101], v[168:171], v[216:219], v[98:101]
	v_mfma_f32_16x16x32_bf16 v[94:97], v[172:175], v[188:191], v[94:97]
	v_mfma_f32_16x16x32_bf16 v[90:93], v[180:183], v[188:191], v[90:93]
	v_mfma_f32_16x16x32_bf16 v[86:89], v[172:175], v[196:199], v[86:89]
	v_mfma_f32_16x16x32_bf16 v[82:85], v[180:183], v[196:199], v[82:85]
	v_mfma_f32_16x16x32_bf16 v[78:81], v[172:175], v[204:207], v[78:81]
	v_mfma_f32_16x16x32_bf16 v[74:77], v[180:183], v[204:207], v[74:77]
	v_mfma_f32_16x16x32_bf16 v[70:73], v[172:175], v[212:215], v[70:73]
	v_mfma_f32_16x16x32_bf16 v[66:69], v[180:183], v[212:215], v[66:69]
	v_mfma_f32_16x16x32_bf16 v[94:97], v[176:179], v[192:195], v[94:97]
	v_mfma_f32_16x16x32_bf16 v[90:93], v[184:187], v[192:195], v[90:93]
	v_mfma_f32_16x16x32_bf16 v[86:89], v[176:179], v[200:203], v[86:89]
	v_mfma_f32_16x16x32_bf16 v[82:85], v[184:187], v[200:203], v[82:85]
	v_mfma_f32_16x16x32_bf16 v[78:81], v[176:179], v[208:211], v[78:81]
	v_mfma_f32_16x16x32_bf16 v[74:77], v[184:187], v[208:211], v[74:77]
	v_mfma_f32_16x16x32_bf16 v[70:73], v[176:179], v[216:219], v[70:73]
	v_mfma_f32_16x16x32_bf16 v[66:69], v[184:187], v[216:219], v[66:69]
	s_barrier
; #define PG8_STAGEA(bufoff, gbase) PG8_STAGE_(bufoff, gbase, voffA)
; #define PG8_STAGEB(bufoff, gbase) PG8_STAGE_(bufoff, gbase, voffB)
; #define PG8_LDA(dst, b, h) do { _Pragma("unroll") for (int m = 0; m < 4; ++m) _Pragma("unroll") for (int k = 0; k < 2; ++k) dst[m][k] = *(const LAS bf16x8*)(lds + PG8_SA(b, h) + aoff + m * 2048 + k * 1024); } while (0)
; #define PG8_MMA(ai, bj, At, Bt_) do { __builtin_amdgcn_s_setprio(1); _Pragma("unroll") for (int m = 0; m < 4; ++m) _Pragma("unroll") for (int n = 0; n < 2; ++n) _Pragma("unroll") for (int k = 0; k < 2; ++k) \
;         acc[ai][bj][m][n] = __builtin_amdgcn_mfma_f32_16x16x32_bf16(Bt_[n][k], At[m][k], acc[ai][bj][m][n], 0, 0, 0); __builtin_amdgcn_s_setprio(0); } while (0)
; #define PG8_WAIT_V(n) asm volatile("s_waitcnt vmcnt(" #n ")" ::: "memory")
; #define PG8_WAIT_L(n) asm volatile("s_waitcnt lgkmcnt(" #n ")" ::: "memory")
; #define PG8_BAR __builtin_amdgcn_s_barrier()
; #define PG8_SCHED __builtin_amdgcn_sched_barrier(0)
; template <int EK, int SK = -1>
; __device__ __forceinline__ void gemm_phase(LAS unsigned char* lds, const bf16_t* A, const bf16_t* Bt, int nM, int N, int K, const EpiArgs& E) {
;     ...
;             PG8_LDA(At, 1, 1); PG8_STAGEB(PG8_SB(1, 0), b3); PG8_STAGEB(PG8_SB(1, 1), b3 + hstep); PG8_STAGEA(PG8_SA(1, 0), a3);
;             PG8_WAIT_V(8); PG8_WAIT_L(0); PG8_BAR; PG8_MMA(1, 0, At, B0); PG8_MMA(1, 1, At, B1); PG8_BAR; PG8_SCHED;
	s_add_i32 s42, s79, s54
	v_lshl_add_u64 v[150:151], v[150:151], 0, s[22:23]
	s_mov_b32 m0, s42
	ds_read_b128 v[188:191], v154 offset:49152
	ds_read_b128 v[192:195], v154 offset:50176
	ds_read_b128 v[196:199], v154 offset:51200
	ds_read_b128 v[200:203], v154 offset:52224
	ds_read_b128 v[204:207], v154 offset:53248
	ds_read_b128 v[208:211], v154 offset:54272
	ds_read_b128 v[212:215], v154 offset:55296
	ds_read_b128 v[216:219], v154 offset:56320
	s_mov_b64 exec, s[100:101]
	global_load_lds_dwordx4 v[150:151], off
	s_mov_b64 exec, -1
	s_add_i32 m0, s42, 0x2000
	s_add_u32 s40, s40, 0xb0080
	v_lshl_add_u64 v[150:151], v[220:221], 0, s[22:23]
	s_addc_u32 s41, s41, 0
	s_add_i32 s42, s80, s54
	s_mov_b64 exec, s[100:101]
	global_load_lds_dwordx4 v[150:151], off
	s_mov_b64 exec, -1
	v_lshl_add_u64 v[150:151], s[40:41], 0, v[132:133]
	s_mov_b32 m0, s42
	s_nop 0
	s_mov_b64 exec, s[100:101]
	global_load_lds_dwordx4 v[150:151], off
	s_mov_b64 exec, -1
	v_lshl_add_u64 v[150:151], s[40:41], 0, v[136:137]
	s_add_i32 m0, s42, 0x2000
	s_nop 0
	s_mov_b64 exec, s[100:101]
	global_load_lds_dwordx4 v[150:151], off
	s_mov_b64 exec, -1
	v_lshl_add_u64 v[150:151], v[222:223], 0, s[22:23]
	s_mov_b32 m0, s69
	s_nop 0
	s_mov_b64 exec, s[100:101]
	global_load_lds_dwordx4 v[150:151], off
	s_mov_b64 exec, -1
	v_lshl_add_u64 v[150:151], v[224:225], 0, s[22:23]
	s_mov_b32 m0, s70
	s_nop 0
	s_mov_b64 exec, s[100:101]
	global_load_lds_dwordx4 v[150:151], off
	s_mov_b64 exec, -1
	s_waitcnt vmcnt(8)
	s_waitcnt lgkmcnt(0)
	s_barrier
	s_waitcnt lgkmcnt(0)
	v_mfma_f32_16x16x32_bf16 v[62:65], v[156:159], v[188:191], v[62:65]
	v_mfma_f32_16x16x32_bf16 v[58:61], v[164:167], v[188:191], v[58:61]
	v_mfma_f32_16x16x32_bf16 v[54:57], v[156:159], v[196:199], v[54:57]
	v_mfma_f32_16x16x32_bf16 v[50:53], v[164:167], v[196:199], v[50:53]
	v_mfma_f32_16x16x32_bf16 v[46:49], v[156:159], v[204:207], v[46:49]
	v_mfma_f32_16x16x32_bf16 v[42:45], v[164:167], v[204:207], v[42:45]
	v_mfma_f32_16x16x32_bf16 v[38:41], v[156:159], v[212:215], v[38:41]
	v_mfma_f32_16x16x32_bf16 v[34:37], v[164:167], v[212:215], v[34:37]
	v_mfma_f32_16x16x32_bf16 v[62:65], v[160:163], v[192:195], v[62:65]
	v_mfma_f32_16x16x32_bf16 v[58:61], v[168:171], v[192:195], v[58:61]
	v_mfma_f32_16x16x32_bf16 v[54:57], v[160:163], v[200:203], v[54:57]
	v_mfma_f32_16x16x32_bf16 v[50:53], v[168:171], v[200:203], v[50:53]
	v_mfma_f32_16x16x32_bf16 v[46:49], v[160:163], v[208:211], v[46:49]
	v_mfma_f32_16x16x32_bf16 v[42:45], v[168:171], v[208:211], v[42:45]
	v_mfma_f32_16x16x32_bf16 v[38:41], v[160:163], v[216:219], v[38:41]
	v_mfma_f32_16x16x32_bf16 v[34:37], v[168:171], v[216:219], v[34:37]
	v_mfma_f32_16x16x32_bf16 v[30:33], v[172:175], v[188:191], v[30:33]
	v_mfma_f32_16x16x32_bf16 v[26:29], v[180:183], v[188:191], v[26:29]
	v_mfma_f32_16x16x32_bf16 v[22:25], v[172:175], v[196:199], v[22:25]
	v_mfma_f32_16x16x32_bf16 v[18:21], v[180:183], v[196:199], v[18:21]
	v_mfma_f32_16x16x32_bf16 v[14:17], v[172:175], v[204:207], v[14:17]
	v_mfma_f32_16x16x32_bf16 v[10:13], v[180:183], v[204:207], v[10:13]
	v_mfma_f32_16x16x32_bf16 v[6:9], v[172:175], v[212:215], v[6:9]
	v_mfma_f32_16x16x32_bf16 v[2:5], v[180:183], v[212:215], v[2:5]
	v_mfma_f32_16x16x32_bf16 v[30:33], v[176:179], v[192:195], v[30:33]
	v_mfma_f32_16x16x32_bf16 v[26:29], v[184:187], v[192:195], v[26:29]
	v_mfma_f32_16x16x32_bf16 v[22:25], v[176:179], v[200:203], v[22:25]
	v_mfma_f32_16x16x32_bf16 v[18:21], v[184:187], v[200:203], v[18:21]
	v_mfma_f32_16x16x32_bf16 v[14:17], v[176:179], v[208:211], v[14:17]
	v_mfma_f32_16x16x32_bf16 v[10:13], v[184:187], v[208:211], v[10:13]
	v_mfma_f32_16x16x32_bf16 v[6:9], v[176:179], v[216:219], v[6:9]
	v_mfma_f32_16x16x32_bf16 v[2:5], v[184:187], v[216:219], v[2:5]
	s_barrier
	s_add_i32 s20, s20, 2
	s_add_u32 s38, s38, 0x100
	s_addc_u32 s39, s39, 0
	s_cmp_gt_u32 s20, 41
	s_cbranch_scc0 .LBB0_793

; #define PG8_STAGEA(bufoff, gbase) PG8_STAGE_(bufoff, gbase, voffA)
; #define PG8_STAGEB(bufoff, gbase) PG8_STAGE_(bufoff, gbase, voffB)
; #define PG8_LDA(dst, b, h) do { _Pragma("unroll") for (int m = 0; m < 4; ++m) _Pragma("unroll") for (int k = 0; k < 2; ++k) dst[m][k] = *(const LAS bf16x8*)(lds + PG8_SA(b, h) + aoff + m * 2048 + k * 1024); } while (0)
; #define PG8_LDB(dst, b, h) do { _Pragma("unroll") for (int n = 0; n < 2; ++n) _Pragma("unroll") for (int k = 0; k < 2; ++k) dst[n][k] = *(const LAS bf16x8*)(lds + PG8_SB(b, h) + boff + n * 2048 + k * 1024); } while (0)
; #define PG8_MMA(ai, bj, At, Bt_) do { __builtin_amdgcn_s_setprio(1); _Pragma("unroll") for (int m = 0; m < 4; ++m) _Pragma("unroll") for (int n = 0; n < 2; ++n) _Pragma("unroll") for (int k = 0; k < 2; ++k) \
;         acc[ai][bj][m][n] = __builtin_amdgcn_mfma_f32_16x16x32_bf16(Bt_[n][k], At[m][k], acc[ai][bj][m][n], 0, 0, 0); __builtin_amdgcn_s_setprio(0); } while (0)
; #define PG8_WAIT_V(n) asm volatile("s_waitcnt vmcnt(" #n ")" ::: "memory")
; #define PG8_WAIT_L(n) asm volatile("s_waitcnt lgkmcnt(" #n ")" ::: "memory")
; #define PG8_BAR __builtin_amdgcn_s_barrier()
; template <int EK, int SK = -1>
; __device__ __forceinline__ void gemm_phase(LAS unsigned char* lds, const bf16_t* A, const bf16_t* Bt, int nM, int N, int K, const EpiArgs& E) {
;     ...
;         const bool has_next = S.next(ui + 1, nxt);
;         const char* nA = has_next ? (const char*)A + (size_t)nxt.pm * tstep : cA; const char* nB = has_next ? (const char*)Bt + (size_t)nxt.pn * tstep : cB;
;         for (int t = 0; t < nt; t += 2) {
;             const bool last = (t == nt - 2);
;             const char* a1 = cA + (size_t)(t + 1) * kstep;
;             const char* a2 = last ? nA : cA + (size_t)(t + 2) * kstep; const char* b2 = last ? nB : cB + (size_t)(t + 2) * kstep;
;             const char* a3 = a2 + kstep; const char* b3 = b2 + kstep;
;             PG8_LDB(B0, 0, 0); PG8_LDB(B1, 0, 1); PG8_SCHED; PG8_LDA(At, 0, 0); PG8_STAGEA(PG8_SA(1, 1), a1 + hstep);
;             PG8_WAIT_V(8); PG8_WAIT_L(0); PG8_BAR; PG8_MMA(0, 0, At, B0); PG8_MMA(0, 1, At, B1); PG8_BAR; PG8_SCHED;
;             PG8_LDA(At, 0, 1); PG8_STAGEB(PG8_SB(0, 0), b2); PG8_STAGEB(PG8_SB(0, 1), b2 + hstep); PG8_STAGEA(PG8_SA(0, 0), a2);
;             PG8_WAIT_V(8); PG8_WAIT_L(0); PG8_BAR; PG8_MMA(1, 0, At, B0); PG8_MMA(1, 1, At, B1); PG8_BAR; PG8_SCHED;
.LBB0_929:
	v_add_u32_e32 v158, s82, v160
	ds_read_b128 v[150:153], v158
	ds_read_b128 v[154:157], v158 offset:1024
	ds_read_b128 v[166:169], v158 offset:2048
	ds_read_b128 v[170:173], v158 offset:3072
	v_add_u32_e32 v158, s83, v160
	s_add_u32 s76, s36, s10
	ds_read_b128 v[174:177], v158
	ds_read_b128 v[178:181], v158 offset:1024
	ds_read_b128 v[182:185], v158 offset:2048
	ds_read_b128 v[186:189], v158 offset:3072
	s_addc_u32 s77, s37, s11
	s_add_u32 s76, s76, 0x100
	s_addc_u32 s77, s77, 0
	s_add_u32 s90, s86, s10
	s_addc_u32 s91, s87, s11
	s_cmpk_eq_i32 s10, 0x700
	s_cselect_b32 s79, s14, s77
	s_cselect_b32 s78, s71, s76
	s_cselect_b32 s77, s69, s91
	s_cselect_b32 s76, s88, s90
	s_mov_b64 s[100:101], -1
	s_cmpk_lg_i32 s10, 0x700
	s_cbranch_scc1 .Lmy_mk_929
	s_not_b64 s[100:101], s[6:7]
.Lmy_mk_929:
	v_lshl_add_u64 v[158:159], v[146:147], 0, s[10:11]
	s_add_i32 m0, s23, 0xc000
	ds_read_b128 v[190:193], v163
	ds_read_b128 v[194:197], v163 offset:1024
	ds_read_b128 v[198:201], v163 offset:2048
	ds_read_b128 v[202:205], v163 offset:3072
	ds_read_b128 v[206:209], v163 offset:4096
	ds_read_b128 v[210:213], v163 offset:5120
	ds_read_b128 v[214:217], v163 offset:6144
	ds_read_b128 v[218:221], v163 offset:7168
	global_load_lds_dwordx4 v[158:159], off
	v_lshl_add_u64 v[158:159], v[148:149], 0, s[10:11]
	s_add_i32 m0, s23, 0xe000
	s_nop 0
	global_load_lds_dwordx4 v[158:159], off
	s_waitcnt vmcnt(8)
	s_waitcnt lgkmcnt(0)
	s_barrier
	s_waitcnt lgkmcnt(0)
	v_mfma_f32_16x16x32_bf16 v[110:113], v[150:153], v[190:193], v[110:113]
	v_mfma_f32_16x16x32_bf16 v[106:109], v[166:169], v[190:193], v[106:109]
	v_mfma_f32_16x16x32_bf16 v[102:105], v[150:153], v[198:201], v[102:105]
	v_mfma_f32_16x16x32_bf16 v[98:101], v[166:169], v[198:201], v[98:101]
	v_mfma_f32_16x16x32_bf16 v[94:97], v[150:153], v[206:209], v[94:97]
	v_mfma_f32_16x16x32_bf16 v[90:93], v[166:169], v[206:209], v[90:93]
	v_mfma_f32_16x16x32_bf16 v[86:89], v[150:153], v[214:217], v[86:89]
	v_mfma_f32_16x16x32_bf16 v[82:85], v[166:169], v[214:217], v[82:85]
	v_mfma_f32_16x16x32_bf16 v[110:113], v[154:157], v[194:197], v[110:113]
	v_mfma_f32_16x16x32_bf16 v[106:109], v[170:173], v[194:197], v[106:109]
	v_mfma_f32_16x16x32_bf16 v[102:105], v[154:157], v[202:205], v[102:105]
	v_mfma_f32_16x16x32_bf16 v[98:101], v[170:173], v[202:205], v[98:101]
	v_mfma_f32_16x16x32_bf16 v[94:97], v[154:157], v[210:213], v[94:97]
	v_mfma_f32_16x16x32_bf16 v[90:93], v[170:173], v[210:213], v[90:93]
	v_mfma_f32_16x16x32_bf16 v[86:89], v[154:157], v[218:221], v[86:89]
	v_mfma_f32_16x16x32_bf16 v[82:85], v[170:173], v[218:221], v[82:85]
	v_mfma_f32_16x16x32_bf16 v[78:81], v[174:177], v[190:193], v[78:81]
	v_mfma_f32_16x16x32_bf16 v[74:77], v[182:185], v[190:193], v[74:77]
	v_mfma_f32_16x16x32_bf16 v[70:73], v[174:177], v[198:201], v[70:73]
	v_mfma_f32_16x16x32_bf16 v[66:69], v[182:185], v[198:201], v[66:69]
	v_mfma_f32_16x16x32_bf16 v[62:65], v[174:177], v[206:209], v[62:65]
	v_mfma_f32_16x16x32_bf16 v[58:61], v[182:185], v[206:209], v[58:61]
	v_mfma_f32_16x16x32_bf16 v[54:57], v[174:177], v[214:217], v[54:57]
	v_mfma_f32_16x16x32_bf16 v[50:53], v[182:185], v[214:217], v[50:53]
	v_mfma_f32_16x16x32_bf16 v[78:81], v[178:181], v[194:197], v[78:81]
	v_mfma_f32_16x16x32_bf16 v[74:77], v[186:189], v[194:197], v[74:77]
	v_mfma_f32_16x16x32_bf16 v[70:73], v[178:181], v[202:205], v[70:73]
	v_mfma_f32_16x16x32_bf16 v[66:69], v[186:189], v[202:205], v[66:69]
	v_mfma_f32_16x16x32_bf16 v[62:65], v[178:181], v[210:213], v[62:65]
	v_mfma_f32_16x16x32_bf16 v[58:61], v[186:189], v[210:213], v[58:61]
	v_mfma_f32_16x16x32_bf16 v[54:57], v[178:181], v[218:221], v[54:57]
	v_mfma_f32_16x16x32_bf16 v[50:53], v[186:189], v[218:221], v[50:53]
	s_barrier
	s_add_i32 s90, s82, s53
	v_lshl_add_u64 v[158:159], s[76:77], 0, v[132:133]
	s_mov_b32 m0, s90
	ds_read_b128 v[190:193], v163 offset:16384
	ds_read_b128 v[194:197], v163 offset:17408
	ds_read_b128 v[198:201], v163 offset:18432
	ds_read_b128 v[202:205], v163 offset:19456
	ds_read_b128 v[206:209], v163 offset:20480
	ds_read_b128 v[210:213], v163 offset:21504
	ds_read_b128 v[214:217], v163 offset:22528
	ds_read_b128 v[218:221], v163 offset:23552
	s_mov_b64 exec, s[100:101]
	global_load_lds_dwordx4 v[158:159], off
	s_mov_b64 exec, -1
	s_add_i32 m0, s90, 0x2000
	s_add_u32 s90, s76, 0x40000
	v_lshl_add_u64 v[222:223], s[76:77], 0, v[136:137]
	s_addc_u32 s91, s77, 0
	s_add_i32 s92, s83, s53
	s_mov_b64 exec, s[100:101]
	global_load_lds_dwordx4 v[222:223], off
	s_mov_b64 exec, -1
	v_lshl_add_u64 v[224:225], s[90:91], 0, v[132:133]
	s_mov_b32 m0, s92
	v_lshl_add_u64 v[226:227], s[78:79], 0, v[134:135]
	s_mov_b64 exec, s[100:101]
	global_load_lds_dwordx4 v[224:225], off
	s_mov_b64 exec, -1
	v_lshl_add_u64 v[224:225], s[90:91], 0, v[136:137]
	s_add_i32 m0, s92, 0x2000
	s_nop 0
	s_mov_b64 exec, s[100:101]
	global_load_lds_dwordx4 v[224:225], off
	s_mov_b64 exec, -1
	v_lshl_add_u64 v[224:225], s[78:79], 0, v[130:131]
	s_mov_b32 m0, s23
	s_nop 0
	s_mov_b64 exec, s[100:101]
	global_load_lds_dwordx4 v[224:225], off
	s_mov_b64 exec, -1
	s_mov_b32 m0, s27
	s_nop 0
	s_mov_b64 exec, s[100:101]
	global_load_lds_dwordx4 v[226:227], off
	s_mov_b64 exec, -1
	s_waitcnt vmcnt(8)
	s_waitcnt lgkmcnt(0)
	s_barrier
; #define PG8_STAGEA(bufoff, gbase) PG8_STAGE_(bufoff, gbase, voffA)
; #define PG8_LDA(dst, b, h) do { _Pragma("unroll") for (int m = 0; m < 4; ++m) _Pragma("unroll") for (int k = 0; k < 2; ++k) dst[m][k] = *(const LAS bf16x8*)(lds + PG8_SA(b, h) + aoff + m * 2048 + k * 1024); } while (0)
; #define PG8_LDB(dst, b, h) do { _Pragma("unroll") for (int n = 0; n < 2; ++n) _Pragma("unroll") for (int k = 0; k < 2; ++k) dst[n][k] = *(const LAS bf16x8*)(lds + PG8_SB(b, h) + boff + n * 2048 + k * 1024); } while (0)
; #define PG8_MMA(ai, bj, At, Bt_) do { __builtin_amdgcn_s_setprio(1); _Pragma("unroll") for (int m = 0; m < 4; ++m) _Pragma("unroll") for (int n = 0; n < 2; ++n) _Pragma("unroll") for (int k = 0; k < 2; ++k) \
;         acc[ai][bj][m][n] = __builtin_amdgcn_mfma_f32_16x16x32_bf16(Bt_[n][k], At[m][k], acc[ai][bj][m][n], 0, 0, 0); __builtin_amdgcn_s_setprio(0); } while (0)
; #define PG8_WAIT_V(n) asm volatile("s_waitcnt vmcnt(" #n ")" ::: "memory")
; #define PG8_WAIT_L(n) asm volatile("s_waitcnt lgkmcnt(" #n ")" ::: "memory")
; #define PG8_BAR __builtin_amdgcn_s_barrier()
; #define PG8_SCHED __builtin_amdgcn_sched_barrier(0)
; template <int EK, int SK = -1>
; __device__ __forceinline__ void gemm_phase(LAS unsigned char* lds, const bf16_t* A, const bf16_t* Bt, int nM, int N, int K, const EpiArgs& E) {
;     ...
;             PG8_WAIT_V(8); PG8_WAIT_L(0); PG8_BAR; PG8_MMA(1, 0, At, B0); PG8_MMA(1, 1, At, B1); PG8_BAR; PG8_SCHED;
;             PG8_LDB(B0, 1, 0); PG8_LDB(B1, 1, 1); PG8_SCHED; PG8_LDA(At, 1, 0); PG8_STAGEA(PG8_SA(0, 1), a2 + hstep);
;             PG8_WAIT_V(8); PG8_WAIT_L(0); PG8_BAR; PG8_MMA(0, 0, At, B0); PG8_MMA(0, 1, At, B1); PG8_BAR; PG8_SCHED;
	s_waitcnt lgkmcnt(0)
	v_mfma_f32_16x16x32_bf16 v[46:49], v[150:153], v[190:193], v[46:49]
	v_mfma_f32_16x16x32_bf16 v[42:45], v[166:169], v[190:193], v[42:45]
	v_mfma_f32_16x16x32_bf16 v[38:41], v[150:153], v[198:201], v[38:41]
	v_mfma_f32_16x16x32_bf16 v[34:37], v[166:169], v[198:201], v[34:37]
	v_mfma_f32_16x16x32_bf16 v[30:33], v[150:153], v[206:209], v[30:33]
	v_mfma_f32_16x16x32_bf16 v[26:29], v[166:169], v[206:209], v[26:29]
	v_mfma_f32_16x16x32_bf16 v[22:25], v[150:153], v[214:217], v[22:25]
	v_mfma_f32_16x16x32_bf16 v[18:21], v[166:169], v[214:217], v[18:21]
	v_mfma_f32_16x16x32_bf16 v[46:49], v[154:157], v[194:197], v[46:49]
	v_mfma_f32_16x16x32_bf16 v[42:45], v[170:173], v[194:197], v[42:45]
	v_mfma_f32_16x16x32_bf16 v[38:41], v[154:157], v[202:205], v[38:41]
	v_mfma_f32_16x16x32_bf16 v[34:37], v[170:173], v[202:205], v[34:37]
	v_mfma_f32_16x16x32_bf16 v[30:33], v[154:157], v[210:213], v[30:33]
	v_mfma_f32_16x16x32_bf16 v[26:29], v[170:173], v[210:213], v[26:29]
	v_mfma_f32_16x16x32_bf16 v[22:25], v[154:157], v[218:221], v[22:25]
	v_mfma_f32_16x16x32_bf16 v[18:21], v[170:173], v[218:221], v[18:21]
	v_mfma_f32_16x16x32_bf16 v[14:17], v[174:177], v[190:193], v[14:17]
	v_mfma_f32_16x16x32_bf16 v[10:13], v[182:185], v[190:193], v[10:13]
	v_mfma_f32_16x16x32_bf16 v[6:9], v[174:177], v[198:201], v[6:9]
	v_mfma_f32_16x16x32_bf16 v[2:5], v[182:185], v[198:201], v[2:5]
	v_mfma_f32_16x16x32_bf16 v[114:117], v[174:177], v[206:209], v[114:117]
	v_mfma_f32_16x16x32_bf16 v[118:121], v[182:185], v[206:209], v[118:121]
	v_mfma_f32_16x16x32_bf16 v[122:125], v[174:177], v[214:217], v[122:125]
	v_mfma_f32_16x16x32_bf16 v[126:129], v[182:185], v[214:217], v[126:129]
	v_mfma_f32_16x16x32_bf16 v[14:17], v[178:181], v[194:197], v[14:17]
	v_mfma_f32_16x16x32_bf16 v[10:13], v[186:189], v[194:197], v[10:13]
	v_mfma_f32_16x16x32_bf16 v[6:9], v[178:181], v[202:205], v[6:9]
	v_mfma_f32_16x16x32_bf16 v[2:5], v[186:189], v[202:205], v[2:5]
	v_mfma_f32_16x16x32_bf16 v[114:117], v[178:181], v[210:213], v[114:117]
	v_mfma_f32_16x16x32_bf16 v[118:121], v[186:189], v[210:213], v[118:121]
	v_mfma_f32_16x16x32_bf16 v[122:125], v[178:181], v[218:221], v[122:125]
	v_mfma_f32_16x16x32_bf16 v[126:129], v[186:189], v[218:221], v[126:129]
	s_barrier
	s_add_i32 s90, 0, 0x18000
	v_add_u32_e32 v165, s90, v160
	s_add_i32 s91, 0, 0x1c000
	ds_read_b128 v[150:153], v165
	ds_read_b128 v[154:157], v165 offset:1024
	ds_read_b128 v[166:169], v165 offset:2048
	ds_read_b128 v[170:173], v165 offset:3072
	v_add_u32_e32 v165, s91, v160
	ds_read_b128 v[174:177], v165
	ds_read_b128 v[178:181], v165 offset:1024
	ds_read_b128 v[182:185], v165 offset:2048
	ds_read_b128 v[186:189], v165 offset:3072
	s_add_u32 s78, s78, 0x40000
	s_addc_u32 s79, s79, 0
	s_mov_b32 m0, s55
	v_lshl_add_u64 v[228:229], s[78:79], 0, v[130:131]
	ds_read_b128 v[190:193], v163 offset:32768
	ds_read_b128 v[194:197], v163 offset:33792
	ds_read_b128 v[198:201], v163 offset:34816
	ds_read_b128 v[202:205], v163 offset:35840
	ds_read_b128 v[206:209], v163 offset:36864
	ds_read_b128 v[210:213], v163 offset:37888
	ds_read_b128 v[214:217], v163 offset:38912
	ds_read_b128 v[218:221], v163 offset:39936
	s_mov_b64 exec, s[100:101]
	global_load_lds_dwordx4 v[228:229], off
	s_mov_b64 exec, -1
	v_lshl_add_u64 v[228:229], s[78:79], 0, v[134:135]
	s_mov_b32 m0, s57
	s_nop 0
	s_mov_b64 exec, s[100:101]
	global_load_lds_dwordx4 v[228:229], off
	s_mov_b64 exec, -1
	s_waitcnt vmcnt(8)
	s_waitcnt lgkmcnt(0)
	s_barrier
	s_waitcnt lgkmcnt(0)
	v_mfma_f32_16x16x32_bf16 v[110:113], v[150:153], v[190:193], v[110:113]
	v_mfma_f32_16x16x32_bf16 v[106:109], v[166:169], v[190:193], v[106:109]
	v_mfma_f32_16x16x32_bf16 v[102:105], v[150:153], v[198:201], v[102:105]
	v_mfma_f32_16x16x32_bf16 v[98:101], v[166:169], v[198:201], v[98:101]
	v_mfma_f32_16x16x32_bf16 v[94:97], v[150:153], v[206:209], v[94:97]
	v_mfma_f32_16x16x32_bf16 v[90:93], v[166:169], v[206:209], v[90:93]
	v_mfma_f32_16x16x32_bf16 v[86:89], v[150:153], v[214:217], v[86:89]
	v_mfma_f32_16x16x32_bf16 v[82:85], v[166:169], v[214:217], v[82:85]
	v_mfma_f32_16x16x32_bf16 v[110:113], v[154:157], v[194:197], v[110:113]
	v_mfma_f32_16x16x32_bf16 v[106:109], v[170:173], v[194:197], v[106:109]
	v_mfma_f32_16x16x32_bf16 v[102:105], v[154:157], v[202:205], v[102:105]
	v_mfma_f32_16x16x32_bf16 v[98:101], v[170:173], v[202:205], v[98:101]
	v_mfma_f32_16x16x32_bf16 v[94:97], v[154:157], v[210:213], v[94:97]
	v_mfma_f32_16x16x32_bf16 v[90:93], v[170:173], v[210:213], v[90:93]
	v_mfma_f32_16x16x32_bf16 v[86:89], v[154:157], v[218:221], v[86:89]
	v_mfma_f32_16x16x32_bf16 v[82:85], v[170:173], v[218:221], v[82:85]
	v_mfma_f32_16x16x32_bf16 v[78:81], v[174:177], v[190:193], v[78:81]
	v_mfma_f32_16x16x32_bf16 v[74:77], v[182:185], v[190:193], v[74:77]
	v_mfma_f32_16x16x32_bf16 v[70:73], v[174:177], v[198:201], v[70:73]
	v_mfma_f32_16x16x32_bf16 v[66:69], v[182:185], v[198:201], v[66:69]
	v_mfma_f32_16x16x32_bf16 v[62:65], v[174:177], v[206:209], v[62:65]
	v_mfma_f32_16x16x32_bf16 v[58:61], v[182:185], v[206:209], v[58:61]
	v_mfma_f32_16x16x32_bf16 v[54:57], v[174:177], v[214:217], v[54:57]
	v_mfma_f32_16x16x32_bf16 v[50:53], v[182:185], v[214:217], v[50:53]
	v_mfma_f32_16x16x32_bf16 v[78:81], v[178:181], v[194:197], v[78:81]
	v_mfma_f32_16x16x32_bf16 v[74:77], v[186:189], v[194:197], v[74:77]
	v_mfma_f32_16x16x32_bf16 v[70:73], v[178:181], v[202:205], v[70:73]
	v_mfma_f32_16x16x32_bf16 v[66:69], v[186:189], v[202:205], v[66:69]
	v_mfma_f32_16x16x32_bf16 v[62:65], v[178:181], v[210:213], v[62:65]
	v_mfma_f32_16x16x32_bf16 v[58:61], v[186:189], v[210:213], v[58:61]
	v_mfma_f32_16x16x32_bf16 v[54:57], v[178:181], v[218:221], v[54:57]
	v_mfma_f32_16x16x32_bf16 v[50:53], v[186:189], v[218:221], v[50:53]
	s_barrier
; #define PG8_STAGEA(bufoff, gbase) PG8_STAGE_(bufoff, gbase, voffA)
; #define PG8_STAGEB(bufoff, gbase) PG8_STAGE_(bufoff, gbase, voffB)
; #define PG8_LDA(dst, b, h) do { _Pragma("unroll") for (int m = 0; m < 4; ++m) _Pragma("unroll") for (int k = 0; k < 2; ++k) dst[m][k] = *(const LAS bf16x8*)(lds + PG8_SA(b, h) + aoff + m * 2048 + k * 1024); } while (0)
; #define PG8_MMA(ai, bj, At, Bt_) do { __builtin_amdgcn_s_setprio(1); _Pragma("unroll") for (int m = 0; m < 4; ++m) _Pragma("unroll") for (int n = 0; n < 2; ++n) _Pragma("unroll") for (int k = 0; k < 2; ++k) \
;         acc[ai][bj][m][n] = __builtin_amdgcn_mfma_f32_16x16x32_bf16(Bt_[n][k], At[m][k], acc[ai][bj][m][n], 0, 0, 0); __builtin_amdgcn_s_setprio(0); } while (0)
; #define PG8_WAIT_V(n) asm volatile("s_waitcnt vmcnt(" #n ")" ::: "memory")
; #define PG8_WAIT_L(n) asm volatile("s_waitcnt lgkmcnt(" #n ")" ::: "memory")
; #define PG8_BAR __builtin_amdgcn_s_barrier()
; #define PG8_SCHED __builtin_amdgcn_sched_barrier(0)
; template <int EK, int SK = -1>
; __device__ __forceinline__ void gemm_phase(LAS unsigned char* lds, const bf16_t* A, const bf16_t* Bt, int nM, int N, int K, const EpiArgs& E) {
;     ...
;             PG8_LDA(At, 1, 1); PG8_STAGEB(PG8_SB(1, 0), b3); PG8_STAGEB(PG8_SB(1, 1), b3 + hstep); PG8_STAGEA(PG8_SA(1, 0), a3);
;             PG8_WAIT_V(8); PG8_WAIT_L(0); PG8_BAR; PG8_MMA(1, 0, At, B0); PG8_MMA(1, 1, At, B1); PG8_BAR; PG8_SCHED;
	s_add_i32 s78, s90, s53
	v_lshl_add_u64 v[158:159], v[158:159], 0, s[16:17]
	s_mov_b32 m0, s78
	ds_read_b128 v[190:193], v163 offset:49152
	ds_read_b128 v[194:197], v163 offset:50176
	ds_read_b128 v[198:201], v163 offset:51200
	ds_read_b128 v[202:205], v163 offset:52224
	ds_read_b128 v[206:209], v163 offset:53248
	ds_read_b128 v[210:213], v163 offset:54272
	ds_read_b128 v[214:217], v163 offset:55296
	ds_read_b128 v[218:221], v163 offset:56320
	s_mov_b64 exec, s[100:101]
	global_load_lds_dwordx4 v[158:159], off
	s_mov_b64 exec, -1
	s_add_i32 m0, s78, 0x2000
	s_add_u32 s76, s76, 0x40080
	v_lshl_add_u64 v[158:159], v[222:223], 0, s[16:17]
	s_addc_u32 s77, s77, 0
	s_add_i32 s78, s91, s53
	s_mov_b64 exec, s[100:101]
	global_load_lds_dwordx4 v[158:159], off
	s_mov_b64 exec, -1
	v_lshl_add_u64 v[158:159], s[76:77], 0, v[132:133]
	s_mov_b32 m0, s78
	s_nop 0
	s_mov_b64 exec, s[100:101]
	global_load_lds_dwordx4 v[158:159], off
	s_mov_b64 exec, -1
	v_lshl_add_u64 v[158:159], s[76:77], 0, v[136:137]
	s_add_i32 m0, s78, 0x2000
	s_nop 0
	s_mov_b64 exec, s[100:101]
	global_load_lds_dwordx4 v[158:159], off
	s_mov_b64 exec, -1
	v_lshl_add_u64 v[158:159], v[224:225], 0, s[16:17]
	s_mov_b32 m0, s80
	s_nop 0
	s_mov_b64 exec, s[100:101]
	global_load_lds_dwordx4 v[158:159], off
	s_mov_b64 exec, -1
	v_lshl_add_u64 v[158:159], v[226:227], 0, s[16:17]
	s_mov_b32 m0, s81
	s_nop 0
	s_mov_b64 exec, s[100:101]
	global_load_lds_dwordx4 v[158:159], off
	s_mov_b64 exec, -1
	s_waitcnt vmcnt(8)
	s_waitcnt lgkmcnt(0)
	s_barrier
	s_waitcnt lgkmcnt(0)
	v_mfma_f32_16x16x32_bf16 v[46:49], v[150:153], v[190:193], v[46:49]
	v_mfma_f32_16x16x32_bf16 v[42:45], v[166:169], v[190:193], v[42:45]
	v_mfma_f32_16x16x32_bf16 v[38:41], v[150:153], v[198:201], v[38:41]
	v_mfma_f32_16x16x32_bf16 v[34:37], v[166:169], v[198:201], v[34:37]
	v_mfma_f32_16x16x32_bf16 v[30:33], v[150:153], v[206:209], v[30:33]
	v_mfma_f32_16x16x32_bf16 v[26:29], v[166:169], v[206:209], v[26:29]
	v_mfma_f32_16x16x32_bf16 v[22:25], v[150:153], v[214:217], v[22:25]
	v_mfma_f32_16x16x32_bf16 v[18:21], v[166:169], v[214:217], v[18:21]
	v_mfma_f32_16x16x32_bf16 v[46:49], v[154:157], v[194:197], v[46:49]
	v_mfma_f32_16x16x32_bf16 v[42:45], v[170:173], v[194:197], v[42:45]
	v_mfma_f32_16x16x32_bf16 v[38:41], v[154:157], v[202:205], v[38:41]
	v_mfma_f32_16x16x32_bf16 v[34:37], v[170:173], v[202:205], v[34:37]
	v_mfma_f32_16x16x32_bf16 v[30:33], v[154:157], v[210:213], v[30:33]
	v_mfma_f32_16x16x32_bf16 v[26:29], v[170:173], v[210:213], v[26:29]
	v_mfma_f32_16x16x32_bf16 v[22:25], v[154:157], v[218:221], v[22:25]
	v_mfma_f32_16x16x32_bf16 v[18:21], v[170:173], v[218:221], v[18:21]
	v_mfma_f32_16x16x32_bf16 v[14:17], v[174:177], v[190:193], v[14:17]
	v_mfma_f32_16x16x32_bf16 v[10:13], v[182:185], v[190:193], v[10:13]
	v_mfma_f32_16x16x32_bf16 v[6:9], v[174:177], v[198:201], v[6:9]
	v_mfma_f32_16x16x32_bf16 v[2:5], v[182:185], v[198:201], v[2:5]
	v_mfma_f32_16x16x32_bf16 v[114:117], v[174:177], v[206:209], v[114:117]
	v_mfma_f32_16x16x32_bf16 v[118:121], v[182:185], v[206:209], v[118:121]
	v_mfma_f32_16x16x32_bf16 v[122:125], v[174:177], v[214:217], v[122:125]
	v_mfma_f32_16x16x32_bf16 v[126:129], v[182:185], v[214:217], v[126:129]
	v_mfma_f32_16x16x32_bf16 v[14:17], v[178:181], v[194:197], v[14:17]
	v_mfma_f32_16x16x32_bf16 v[10:13], v[186:189], v[194:197], v[10:13]
	v_mfma_f32_16x16x32_bf16 v[6:9], v[178:181], v[202:205], v[6:9]
	v_mfma_f32_16x16x32_bf16 v[2:5], v[186:189], v[202:205], v[2:5]
	v_mfma_f32_16x16x32_bf16 v[114:117], v[178:181], v[210:213], v[114:117]
	v_mfma_f32_16x16x32_bf16 v[118:121], v[186:189], v[210:213], v[118:121]
	v_mfma_f32_16x16x32_bf16 v[122:125], v[178:181], v[218:221], v[122:125]
	v_mfma_f32_16x16x32_bf16 v[126:129], v[186:189], v[218:221], v[126:129]
	s_barrier
	s_add_i32 s89, s89, 2
	s_add_u32 s10, s10, 0x100
	s_addc_u32 s11, s11, 0
	s_cmp_gt_u32 s89, 13
	s_cbranch_scc0 .LBB0_929

; #define PG8_STAGEA(bufoff, gbase) PG8_STAGE_(bufoff, gbase, voffA)
; #define PG8_STAGEB(bufoff, gbase) PG8_STAGE_(bufoff, gbase, voffB)
; #define PG8_LDA(dst, b, h) do { _Pragma("unroll") for (int m = 0; m < 4; ++m) _Pragma("unroll") for (int k = 0; k < 2; ++k) dst[m][k] = *(const LAS bf16x8*)(lds + PG8_SA(b, h) + aoff + m * 2048 + k * 1024); } while (0)
; #define PG8_LDB(dst, b, h) do { _Pragma("unroll") for (int n = 0; n < 2; ++n) _Pragma("unroll") for (int k = 0; k < 2; ++k) dst[n][k] = *(const LAS bf16x8*)(lds + PG8_SB(b, h) + boff + n * 2048 + k * 1024); } while (0)
; #define PG8_MMA(ai, bj, At, Bt_) do { __builtin_amdgcn_s_setprio(1); _Pragma("unroll") for (int m = 0; m < 4; ++m) _Pragma("unroll") for (int n = 0; n < 2; ++n) _Pragma("unroll") for (int k = 0; k < 2; ++k) \
;         acc[ai][bj][m][n] = __builtin_amdgcn_mfma_f32_16x16x32_bf16(Bt_[n][k], At[m][k], acc[ai][bj][m][n], 0, 0, 0); __builtin_amdgcn_s_setprio(0); } while (0)
; #define PG8_WAIT_V(n) asm volatile("s_waitcnt vmcnt(" #n ")" ::: "memory")
; #define PG8_WAIT_L(n) asm volatile("s_waitcnt lgkmcnt(" #n ")" ::: "memory")
; #define PG8_BAR __builtin_amdgcn_s_barrier()
; template <int EK, int SK = -1>
; __device__ __forceinline__ void gemm_phase(LAS unsigned char* lds, const bf16_t* A, const bf16_t* Bt, int nM, int N, int K, const EpiArgs& E) {
;     ...
;         const bool has_next = S.next(ui + 1, nxt);
;         const char* nA = has_next ? (const char*)A + (size_t)nxt.pm * tstep : cA; const char* nB = has_next ? (const char*)Bt + (size_t)nxt.pn * tstep : cB;
;         for (int t = 0; t < nt; t += 2) {
;             const bool last = (t == nt - 2);
;             const char* a1 = cA + (size_t)(t + 1) * kstep;
;             const char* a2 = last ? nA : cA + (size_t)(t + 2) * kstep; const char* b2 = last ? nB : cB + (size_t)(t + 2) * kstep;
;             const char* a3 = a2 + kstep; const char* b3 = b2 + kstep;
;             PG8_LDB(B0, 0, 0); PG8_LDB(B1, 0, 1); PG8_SCHED; PG8_LDA(At, 0, 0); PG8_STAGEA(PG8_SA(1, 1), a1 + hstep);
;             PG8_WAIT_V(8); PG8_WAIT_L(0); PG8_BAR; PG8_MMA(0, 0, At, B0); PG8_MMA(0, 1, At, B1); PG8_BAR; PG8_SCHED;
;             PG8_LDA(At, 0, 1); PG8_STAGEB(PG8_SB(0, 0), b2); PG8_STAGEB(PG8_SB(0, 1), b2 + hstep); PG8_STAGEA(PG8_SA(0, 0), a2);
;             PG8_WAIT_V(8); PG8_WAIT_L(0); PG8_BAR; PG8_MMA(1, 0, At, B0); PG8_MMA(1, 1, At, B1); PG8_BAR; PG8_SCHED;
.LBB0_1120:
	v_add_u32_e32 v150, s69, v152
	ds_read_b128 v[156:159], v150
	ds_read_b128 v[160:163], v150 offset:1024
	ds_read_b128 v[164:167], v150 offset:2048
	ds_read_b128 v[168:171], v150 offset:3072
	v_add_u32_e32 v150, s70, v152
	s_add_u32 s48, s18, s46
	ds_read_b128 v[172:175], v150
	ds_read_b128 v[176:179], v150 offset:1024
	ds_read_b128 v[180:183], v150 offset:2048
	ds_read_b128 v[184:187], v150 offset:3072
	s_addc_u32 s49, s19, s47
	s_add_u32 s48, s48, 0x100
	s_addc_u32 s49, s49, 0
	s_add_u32 s77, s73, s46
	s_addc_u32 s78, s74, s47
	s_cmpk_eq_i32 s46, 0x700
	s_cselect_b32 s51, s22, s49
	s_cselect_b32 s50, s41, s48
	s_cselect_b32 s49, s39, s78
	s_cselect_b32 s48, s75, s77
	s_mov_b64 s[100:101], -1
	s_cmpk_lg_i32 s46, 0x700
	s_cbranch_scc1 .Lmy_mk_1120
	s_not_b64 s[100:101], s[6:7]
.Lmy_mk_1120:
	v_lshl_add_u64 v[150:151], v[146:147], 0, s[46:47]
	s_add_i32 m0, s15, 0xc000
	ds_read_b128 v[188:191], v154
	ds_read_b128 v[192:195], v154 offset:1024
	ds_read_b128 v[196:199], v154 offset:2048
	ds_read_b128 v[200:203], v154 offset:3072
	ds_read_b128 v[204:207], v154 offset:4096
	ds_read_b128 v[208:211], v154 offset:5120
	ds_read_b128 v[212:215], v154 offset:6144
	ds_read_b128 v[216:219], v154 offset:7168
	global_load_lds_dwordx4 v[150:151], off
	v_lshl_add_u64 v[150:151], v[148:149], 0, s[46:47]
	s_add_i32 m0, s15, 0xe000
	s_nop 0
	global_load_lds_dwordx4 v[150:151], off
	s_waitcnt vmcnt(8)
	s_waitcnt lgkmcnt(0)
	s_barrier
	s_waitcnt lgkmcnt(0)
	v_mfma_f32_16x16x32_bf16 v[126:129], v[156:159], v[188:191], v[126:129]
	v_mfma_f32_16x16x32_bf16 v[122:125], v[164:167], v[188:191], v[122:125]
	v_mfma_f32_16x16x32_bf16 v[118:121], v[156:159], v[196:199], v[118:121]
	v_mfma_f32_16x16x32_bf16 v[114:117], v[164:167], v[196:199], v[114:117]
	v_mfma_f32_16x16x32_bf16 v[110:113], v[156:159], v[204:207], v[110:113]
	v_mfma_f32_16x16x32_bf16 v[106:109], v[164:167], v[204:207], v[106:109]
	v_mfma_f32_16x16x32_bf16 v[102:105], v[156:159], v[212:215], v[102:105]
	v_mfma_f32_16x16x32_bf16 v[98:101], v[164:167], v[212:215], v[98:101]
	v_mfma_f32_16x16x32_bf16 v[126:129], v[160:163], v[192:195], v[126:129]
	v_mfma_f32_16x16x32_bf16 v[122:125], v[168:171], v[192:195], v[122:125]
	v_mfma_f32_16x16x32_bf16 v[118:121], v[160:163], v[200:203], v[118:121]
	v_mfma_f32_16x16x32_bf16 v[114:117], v[168:171], v[200:203], v[114:117]
	v_mfma_f32_16x16x32_bf16 v[110:113], v[160:163], v[208:211], v[110:113]
	v_mfma_f32_16x16x32_bf16 v[106:109], v[168:171], v[208:211], v[106:109]
	v_mfma_f32_16x16x32_bf16 v[102:105], v[160:163], v[216:219], v[102:105]
	v_mfma_f32_16x16x32_bf16 v[98:101], v[168:171], v[216:219], v[98:101]
	v_mfma_f32_16x16x32_bf16 v[94:97], v[172:175], v[188:191], v[94:97]
	v_mfma_f32_16x16x32_bf16 v[90:93], v[180:183], v[188:191], v[90:93]
	v_mfma_f32_16x16x32_bf16 v[86:89], v[172:175], v[196:199], v[86:89]
	v_mfma_f32_16x16x32_bf16 v[82:85], v[180:183], v[196:199], v[82:85]
	v_mfma_f32_16x16x32_bf16 v[78:81], v[172:175], v[204:207], v[78:81]
	v_mfma_f32_16x16x32_bf16 v[74:77], v[180:183], v[204:207], v[74:77]
	v_mfma_f32_16x16x32_bf16 v[70:73], v[172:175], v[212:215], v[70:73]
	v_mfma_f32_16x16x32_bf16 v[66:69], v[180:183], v[212:215], v[66:69]
	v_mfma_f32_16x16x32_bf16 v[94:97], v[176:179], v[192:195], v[94:97]
	v_mfma_f32_16x16x32_bf16 v[90:93], v[184:187], v[192:195], v[90:93]
	v_mfma_f32_16x16x32_bf16 v[86:89], v[176:179], v[200:203], v[86:89]
	v_mfma_f32_16x16x32_bf16 v[82:85], v[184:187], v[200:203], v[82:85]
	v_mfma_f32_16x16x32_bf16 v[78:81], v[176:179], v[208:211], v[78:81]
	v_mfma_f32_16x16x32_bf16 v[74:77], v[184:187], v[208:211], v[74:77]
	v_mfma_f32_16x16x32_bf16 v[70:73], v[176:179], v[216:219], v[70:73]
	v_mfma_f32_16x16x32_bf16 v[66:69], v[184:187], v[216:219], v[66:69]
	s_barrier
	s_add_i32 s77, s69, s54
	v_lshl_add_u64 v[150:151], s[48:49], 0, v[132:133]
	s_mov_b32 m0, s77
	ds_read_b128 v[188:191], v154 offset:16384
	ds_read_b128 v[192:195], v154 offset:17408
	ds_read_b128 v[196:199], v154 offset:18432
	ds_read_b128 v[200:203], v154 offset:19456
	ds_read_b128 v[204:207], v154 offset:20480
	ds_read_b128 v[208:211], v154 offset:21504
	ds_read_b128 v[212:215], v154 offset:22528
	ds_read_b128 v[216:219], v154 offset:23552
	s_mov_b64 exec, s[100:101]
	global_load_lds_dwordx4 v[150:151], off
	s_mov_b64 exec, -1
	s_add_i32 m0, s77, 0x2000
	s_add_u32 s78, s48, 0x40000
	v_lshl_add_u64 v[220:221], s[48:49], 0, v[136:137]
	s_addc_u32 s79, s49, 0
	s_add_i32 s77, s70, s54
	s_mov_b64 exec, s[100:101]
	global_load_lds_dwordx4 v[220:221], off
	s_mov_b64 exec, -1
	v_lshl_add_u64 v[222:223], s[78:79], 0, v[132:133]
	s_mov_b32 m0, s77
	v_lshl_add_u64 v[224:225], s[50:51], 0, v[134:135]
	s_mov_b64 exec, s[100:101]
	global_load_lds_dwordx4 v[222:223], off
	s_mov_b64 exec, -1
	v_lshl_add_u64 v[222:223], s[78:79], 0, v[136:137]
	s_add_i32 m0, s77, 0x2000
	s_nop 0
	s_mov_b64 exec, s[100:101]
	global_load_lds_dwordx4 v[222:223], off
	s_mov_b64 exec, -1
	v_lshl_add_u64 v[222:223], s[50:51], 0, v[130:131]
	s_mov_b32 m0, s15
	s_nop 0
	s_mov_b64 exec, s[100:101]
	global_load_lds_dwordx4 v[222:223], off
	s_mov_b64 exec, -1
	s_mov_b32 m0, s17
	s_nop 0
	s_mov_b64 exec, s[100:101]
	global_load_lds_dwordx4 v[224:225], off
	s_mov_b64 exec, -1
	s_waitcnt vmcnt(8)
	s_waitcnt lgkmcnt(0)
	s_barrier
; #define PG8_STAGEA(bufoff, gbase) PG8_STAGE_(bufoff, gbase, voffA)
; #define PG8_LDA(dst, b, h) do { _Pragma("unroll") for (int m = 0; m < 4; ++m) _Pragma("unroll") for (int k = 0; k < 2; ++k) dst[m][k] = *(const LAS bf16x8*)(lds + PG8_SA(b, h) + aoff + m * 2048 + k * 1024); } while (0)
; #define PG8_LDB(dst, b, h) do { _Pragma("unroll") for (int n = 0; n < 2; ++n) _Pragma("unroll") for (int k = 0; k < 2; ++k) dst[n][k] = *(const LAS bf16x8*)(lds + PG8_SB(b, h) + boff + n * 2048 + k * 1024); } while (0)
; #define PG8_MMA(ai, bj, At, Bt_) do { __builtin_amdgcn_s_setprio(1); _Pragma("unroll") for (int m = 0; m < 4; ++m) _Pragma("unroll") for (int n = 0; n < 2; ++n) _Pragma("unroll") for (int k = 0; k < 2; ++k) \
;         acc[ai][bj][m][n] = __builtin_amdgcn_mfma_f32_16x16x32_bf16(Bt_[n][k], At[m][k], acc[ai][bj][m][n], 0, 0, 0); __builtin_amdgcn_s_setprio(0); } while (0)
; #define PG8_WAIT_V(n) asm volatile("s_waitcnt vmcnt(" #n ")" ::: "memory")
; #define PG8_WAIT_L(n) asm volatile("s_waitcnt lgkmcnt(" #n ")" ::: "memory")
; #define PG8_BAR __builtin_amdgcn_s_barrier()
; #define PG8_SCHED __builtin_amdgcn_sched_barrier(0)
; template <int EK, int SK = -1>
; __device__ __forceinline__ void gemm_phase(LAS unsigned char* lds, const bf16_t* A, const bf16_t* Bt, int nM, int N, int K, const EpiArgs& E) {
;     ...
;             PG8_WAIT_V(8); PG8_WAIT_L(0); PG8_BAR; PG8_MMA(1, 0, At, B0); PG8_MMA(1, 1, At, B1); PG8_BAR; PG8_SCHED;
;             PG8_LDB(B0, 1, 0); PG8_LDB(B1, 1, 1); PG8_SCHED; PG8_LDA(At, 1, 0); PG8_STAGEA(PG8_SA(0, 1), a2 + hstep);
;             PG8_WAIT_V(8); PG8_WAIT_L(0); PG8_BAR; PG8_MMA(0, 0, At, B0); PG8_MMA(0, 1, At, B1); PG8_BAR; PG8_SCHED;
	s_waitcnt lgkmcnt(0)
	v_mfma_f32_16x16x32_bf16 v[62:65], v[156:159], v[188:191], v[62:65]
	v_mfma_f32_16x16x32_bf16 v[58:61], v[164:167], v[188:191], v[58:61]
	v_mfma_f32_16x16x32_bf16 v[54:57], v[156:159], v[196:199], v[54:57]
	v_mfma_f32_16x16x32_bf16 v[50:53], v[164:167], v[196:199], v[50:53]
	v_mfma_f32_16x16x32_bf16 v[46:49], v[156:159], v[204:207], v[46:49]
	v_mfma_f32_16x16x32_bf16 v[42:45], v[164:167], v[204:207], v[42:45]
	v_mfma_f32_16x16x32_bf16 v[38:41], v[156:159], v[212:215], v[38:41]
	v_mfma_f32_16x16x32_bf16 v[34:37], v[164:167], v[212:215], v[34:37]
	v_mfma_f32_16x16x32_bf16 v[62:65], v[160:163], v[192:195], v[62:65]
	v_mfma_f32_16x16x32_bf16 v[58:61], v[168:171], v[192:195], v[58:61]
	v_mfma_f32_16x16x32_bf16 v[54:57], v[160:163], v[200:203], v[54:57]
	v_mfma_f32_16x16x32_bf16 v[50:53], v[168:171], v[200:203], v[50:53]
	v_mfma_f32_16x16x32_bf16 v[46:49], v[160:163], v[208:211], v[46:49]
	v_mfma_f32_16x16x32_bf16 v[42:45], v[168:171], v[208:211], v[42:45]
	v_mfma_f32_16x16x32_bf16 v[38:41], v[160:163], v[216:219], v[38:41]
	v_mfma_f32_16x16x32_bf16 v[34:37], v[168:171], v[216:219], v[34:37]
	v_mfma_f32_16x16x32_bf16 v[30:33], v[172:175], v[188:191], v[30:33]
	v_mfma_f32_16x16x32_bf16 v[26:29], v[180:183], v[188:191], v[26:29]
	v_mfma_f32_16x16x32_bf16 v[22:25], v[172:175], v[196:199], v[22:25]
	v_mfma_f32_16x16x32_bf16 v[18:21], v[180:183], v[196:199], v[18:21]
	v_mfma_f32_16x16x32_bf16 v[14:17], v[172:175], v[204:207], v[14:17]
	v_mfma_f32_16x16x32_bf16 v[10:13], v[180:183], v[204:207], v[10:13]
	v_mfma_f32_16x16x32_bf16 v[6:9], v[172:175], v[212:215], v[6:9]
	v_mfma_f32_16x16x32_bf16 v[2:5], v[180:183], v[212:215], v[2:5]
	v_mfma_f32_16x16x32_bf16 v[30:33], v[176:179], v[192:195], v[30:33]
	v_mfma_f32_16x16x32_bf16 v[26:29], v[184:187], v[192:195], v[26:29]
	v_mfma_f32_16x16x32_bf16 v[22:25], v[176:179], v[200:203], v[22:25]
	v_mfma_f32_16x16x32_bf16 v[18:21], v[184:187], v[200:203], v[18:21]
	v_mfma_f32_16x16x32_bf16 v[14:17], v[176:179], v[208:211], v[14:17]
	v_mfma_f32_16x16x32_bf16 v[10:13], v[184:187], v[208:211], v[10:13]
	v_mfma_f32_16x16x32_bf16 v[6:9], v[176:179], v[216:219], v[6:9]
	v_mfma_f32_16x16x32_bf16 v[2:5], v[184:187], v[216:219], v[2:5]
	s_barrier
	s_add_i32 s77, 0, 0x18000
	s_add_i32 s78, 0, 0x1c000
	v_add_u32_e32 v168, s77, v152
	v_add_u32_e32 v184, s78, v152
	ds_read_b128 v[156:159], v168
	ds_read_b128 v[160:163], v168 offset:1024
	ds_read_b128 v[164:167], v168 offset:2048
	ds_read_b128 v[168:171], v168 offset:3072
	ds_read_b128 v[172:175], v184
	ds_read_b128 v[176:179], v184 offset:1024
	ds_read_b128 v[180:183], v184 offset:2048
	ds_read_b128 v[184:187], v184 offset:3072
	s_add_u32 s50, s50, 0x40000
	s_addc_u32 s51, s51, 0
	s_mov_b32 m0, s55
	v_lshl_add_u64 v[226:227], s[50:51], 0, v[130:131]
	ds_read_b128 v[188:191], v154 offset:32768
	ds_read_b128 v[192:195], v154 offset:33792
	ds_read_b128 v[196:199], v154 offset:34816
	ds_read_b128 v[200:203], v154 offset:35840
	ds_read_b128 v[204:207], v154 offset:36864
	ds_read_b128 v[208:211], v154 offset:37888
	ds_read_b128 v[212:215], v154 offset:38912
	ds_read_b128 v[216:219], v154 offset:39936
	s_mov_b64 exec, s[100:101]
	global_load_lds_dwordx4 v[226:227], off
	s_mov_b64 exec, -1
	v_lshl_add_u64 v[226:227], s[50:51], 0, v[134:135]
	s_mov_b32 m0, s56
	s_nop 0
	s_mov_b64 exec, s[100:101]
	global_load_lds_dwordx4 v[226:227], off
	s_mov_b64 exec, -1
	s_waitcnt vmcnt(8)
	s_waitcnt lgkmcnt(0)
	s_barrier
	s_waitcnt lgkmcnt(0)
	v_mfma_f32_16x16x32_bf16 v[126:129], v[156:159], v[188:191], v[126:129]
	v_mfma_f32_16x16x32_bf16 v[122:125], v[164:167], v[188:191], v[122:125]
	v_mfma_f32_16x16x32_bf16 v[118:121], v[156:159], v[196:199], v[118:121]
	v_mfma_f32_16x16x32_bf16 v[114:117], v[164:167], v[196:199], v[114:117]
	v_mfma_f32_16x16x32_bf16 v[110:113], v[156:159], v[204:207], v[110:113]
	v_mfma_f32_16x16x32_bf16 v[106:109], v[164:167], v[204:207], v[106:109]
	v_mfma_f32_16x16x32_bf16 v[102:105], v[156:159], v[212:215], v[102:105]
	v_mfma_f32_16x16x32_bf16 v[98:101], v[164:167], v[212:215], v[98:101]
	v_mfma_f32_16x16x32_bf16 v[126:129], v[160:163], v[192:195], v[126:129]
	v_mfma_f32_16x16x32_bf16 v[122:125], v[168:171], v[192:195], v[122:125]
	v_mfma_f32_16x16x32_bf16 v[118:121], v[160:163], v[200:203], v[118:121]
	v_mfma_f32_16x16x32_bf16 v[114:117], v[168:171], v[200:203], v[114:117]
	v_mfma_f32_16x16x32_bf16 v[110:113], v[160:163], v[208:211], v[110:113]
	v_mfma_f32_16x16x32_bf16 v[106:109], v[168:171], v[208:211], v[106:109]
	v_mfma_f32_16x16x32_bf16 v[102:105], v[160:163], v[216:219], v[102:105]
	v_mfma_f32_16x16x32_bf16 v[98:101], v[168:171], v[216:219], v[98:101]
	v_mfma_f32_16x16x32_bf16 v[94:97], v[172:175], v[188:191], v[94:97]
	v_mfma_f32_16x16x32_bf16 v[90:93], v[180:183], v[188:191], v[90:93]
	v_mfma_f32_16x16x32_bf16 v[86:89], v[172:175], v[196:199], v[86:89]
	v_mfma_f32_16x16x32_bf16 v[82:85], v[180:183], v[196:199], v[82:85]
	v_mfma_f32_16x16x32_bf16 v[78:81], v[172:175], v[204:207], v[78:81]
	v_mfma_f32_16x16x32_bf16 v[74:77], v[180:183], v[204:207], v[74:77]
	v_mfma_f32_16x16x32_bf16 v[70:73], v[172:175], v[212:215], v[70:73]
	v_mfma_f32_16x16x32_bf16 v[66:69], v[180:183], v[212:215], v[66:69]
	v_mfma_f32_16x16x32_bf16 v[94:97], v[176:179], v[192:195], v[94:97]
	v_mfma_f32_16x16x32_bf16 v[90:93], v[184:187], v[192:195], v[90:93]
	v_mfma_f32_16x16x32_bf16 v[86:89], v[176:179], v[200:203], v[86:89]
	v_mfma_f32_16x16x32_bf16 v[82:85], v[184:187], v[200:203], v[82:85]
	v_mfma_f32_16x16x32_bf16 v[78:81], v[176:179], v[208:211], v[78:81]
	v_mfma_f32_16x16x32_bf16 v[74:77], v[184:187], v[208:211], v[74:77]
	v_mfma_f32_16x16x32_bf16 v[70:73], v[176:179], v[216:219], v[70:73]
	v_mfma_f32_16x16x32_bf16 v[66:69], v[184:187], v[216:219], v[66:69]
	s_barrier
; #define PG8_STAGEA(bufoff, gbase) PG8_STAGE_(bufoff, gbase, voffA)
; #define PG8_STAGEB(bufoff, gbase) PG8_STAGE_(bufoff, gbase, voffB)
; #define PG8_LDA(dst, b, h) do { _Pragma("unroll") for (int m = 0; m < 4; ++m) _Pragma("unroll") for (int k = 0; k < 2; ++k) dst[m][k] = *(const LAS bf16x8*)(lds + PG8_SA(b, h) + aoff + m * 2048 + k * 1024); } while (0)
; #define PG8_MMA(ai, bj, At, Bt_) do { __builtin_amdgcn_s_setprio(1); _Pragma("unroll") for (int m = 0; m < 4; ++m) _Pragma("unroll") for (int n = 0; n < 2; ++n) _Pragma("unroll") for (int k = 0; k < 2; ++k) \
;         acc[ai][bj][m][n] = __builtin_amdgcn_mfma_f32_16x16x32_bf16(Bt_[n][k], At[m][k], acc[ai][bj][m][n], 0, 0, 0); __builtin_amdgcn_s_setprio(0); } while (0)
; #define PG8_WAIT_V(n) asm volatile("s_waitcnt vmcnt(" #n ")" ::: "memory")
; #define PG8_WAIT_L(n) asm volatile("s_waitcnt lgkmcnt(" #n ")" ::: "memory")
; #define PG8_BAR __builtin_amdgcn_s_barrier()
; #define PG8_SCHED __builtin_amdgcn_sched_barrier(0)
; template <int EK, int SK = -1>
; __device__ __forceinline__ void gemm_phase(LAS unsigned char* lds, const bf16_t* A, const bf16_t* Bt, int nM, int N, int K, const EpiArgs& E) {
;     ...
;             PG8_LDA(At, 1, 1); PG8_STAGEB(PG8_SB(1, 0), b3); PG8_STAGEB(PG8_SB(1, 1), b3 + hstep); PG8_STAGEA(PG8_SA(1, 0), a3);
;             PG8_WAIT_V(8); PG8_WAIT_L(0); PG8_BAR; PG8_MMA(1, 0, At, B0); PG8_MMA(1, 1, At, B1); PG8_BAR; PG8_SCHED;
	s_add_i32 s50, s77, s54
	v_lshl_add_u64 v[150:151], v[150:151], 0, s[26:27]
	s_mov_b32 m0, s50
	ds_read_b128 v[188:191], v154 offset:49152
	ds_read_b128 v[192:195], v154 offset:50176
	ds_read_b128 v[196:199], v154 offset:51200
	ds_read_b128 v[200:203], v154 offset:52224
	ds_read_b128 v[204:207], v154 offset:53248
	ds_read_b128 v[208:211], v154 offset:54272
	ds_read_b128 v[212:215], v154 offset:55296
	ds_read_b128 v[216:219], v154 offset:56320
	s_mov_b64 exec, s[100:101]
	global_load_lds_dwordx4 v[150:151], off
	s_mov_b64 exec, -1
	s_add_i32 m0, s50, 0x2000
	s_add_u32 s48, s48, 0x40080
	v_lshl_add_u64 v[150:151], v[220:221], 0, s[26:27]
	s_addc_u32 s49, s49, 0
	s_add_i32 s50, s78, s54
	s_mov_b64 exec, s[100:101]
	global_load_lds_dwordx4 v[150:151], off
	s_mov_b64 exec, -1
	v_lshl_add_u64 v[150:151], s[48:49], 0, v[132:133]
	s_mov_b32 m0, s50
	s_nop 0
	s_mov_b64 exec, s[100:101]
	global_load_lds_dwordx4 v[150:151], off
	s_mov_b64 exec, -1
	v_lshl_add_u64 v[150:151], s[48:49], 0, v[136:137]
	s_add_i32 m0, s50, 0x2000
	s_nop 0
	s_mov_b64 exec, s[100:101]
	global_load_lds_dwordx4 v[150:151], off
	s_mov_b64 exec, -1
	v_lshl_add_u64 v[150:151], v[222:223], 0, s[26:27]
	s_mov_b32 m0, s59
	s_nop 0
	s_mov_b64 exec, s[100:101]
	global_load_lds_dwordx4 v[150:151], off
	s_mov_b64 exec, -1
	v_lshl_add_u64 v[150:151], v[224:225], 0, s[26:27]
	s_mov_b32 m0, s68
	s_nop 0
	s_mov_b64 exec, s[100:101]
	global_load_lds_dwordx4 v[150:151], off
	s_mov_b64 exec, -1
	s_waitcnt vmcnt(8)
	s_waitcnt lgkmcnt(0)
	s_barrier
	s_waitcnt lgkmcnt(0)
	v_mfma_f32_16x16x32_bf16 v[62:65], v[156:159], v[188:191], v[62:65]
	v_mfma_f32_16x16x32_bf16 v[58:61], v[164:167], v[188:191], v[58:61]
	v_mfma_f32_16x16x32_bf16 v[54:57], v[156:159], v[196:199], v[54:57]
	v_mfma_f32_16x16x32_bf16 v[50:53], v[164:167], v[196:199], v[50:53]
	v_mfma_f32_16x16x32_bf16 v[46:49], v[156:159], v[204:207], v[46:49]
	v_mfma_f32_16x16x32_bf16 v[42:45], v[164:167], v[204:207], v[42:45]
	v_mfma_f32_16x16x32_bf16 v[38:41], v[156:159], v[212:215], v[38:41]
	v_mfma_f32_16x16x32_bf16 v[34:37], v[164:167], v[212:215], v[34:37]
	v_mfma_f32_16x16x32_bf16 v[62:65], v[160:163], v[192:195], v[62:65]
	v_mfma_f32_16x16x32_bf16 v[58:61], v[168:171], v[192:195], v[58:61]
	v_mfma_f32_16x16x32_bf16 v[54:57], v[160:163], v[200:203], v[54:57]
	v_mfma_f32_16x16x32_bf16 v[50:53], v[168:171], v[200:203], v[50:53]
	v_mfma_f32_16x16x32_bf16 v[46:49], v[160:163], v[208:211], v[46:49]
	v_mfma_f32_16x16x32_bf16 v[42:45], v[168:171], v[208:211], v[42:45]
	v_mfma_f32_16x16x32_bf16 v[38:41], v[160:163], v[216:219], v[38:41]
	v_mfma_f32_16x16x32_bf16 v[34:37], v[168:171], v[216:219], v[34:37]
	v_mfma_f32_16x16x32_bf16 v[30:33], v[172:175], v[188:191], v[30:33]
	v_mfma_f32_16x16x32_bf16 v[26:29], v[180:183], v[188:191], v[26:29]
	v_mfma_f32_16x16x32_bf16 v[22:25], v[172:175], v[196:199], v[22:25]
	v_mfma_f32_16x16x32_bf16 v[18:21], v[180:183], v[196:199], v[18:21]
	v_mfma_f32_16x16x32_bf16 v[14:17], v[172:175], v[204:207], v[14:17]
	v_mfma_f32_16x16x32_bf16 v[10:13], v[180:183], v[204:207], v[10:13]
	v_mfma_f32_16x16x32_bf16 v[6:9], v[172:175], v[212:215], v[6:9]
	v_mfma_f32_16x16x32_bf16 v[2:5], v[180:183], v[212:215], v[2:5]
	v_mfma_f32_16x16x32_bf16 v[30:33], v[176:179], v[192:195], v[30:33]
	v_mfma_f32_16x16x32_bf16 v[26:29], v[184:187], v[192:195], v[26:29]
	v_mfma_f32_16x16x32_bf16 v[22:25], v[176:179], v[200:203], v[22:25]
	v_mfma_f32_16x16x32_bf16 v[18:21], v[184:187], v[200:203], v[18:21]
	v_mfma_f32_16x16x32_bf16 v[14:17], v[176:179], v[208:211], v[14:17]
	v_mfma_f32_16x16x32_bf16 v[10:13], v[184:187], v[208:211], v[10:13]
	v_mfma_f32_16x16x32_bf16 v[6:9], v[176:179], v[216:219], v[6:9]
	v_mfma_f32_16x16x32_bf16 v[2:5], v[184:187], v[216:219], v[2:5]
	s_barrier
	s_add_i32 s76, s76, 2
	s_add_u32 s46, s46, 0x100
	s_addc_u32 s47, s47, 0
	s_cmp_gt_u32 s76, 13
	s_cbranch_scc0 .LBB0_1120

; #define PG8_STAGEA(bufoff, gbase) PG8_STAGE_(bufoff, gbase, voffA)
; #define PG8_STAGEB(bufoff, gbase) PG8_STAGE_(bufoff, gbase, voffB)
; #define PG8_LDA(dst, b, h) do { _Pragma("unroll") for (int m = 0; m < 4; ++m) _Pragma("unroll") for (int k = 0; k < 2; ++k) dst[m][k] = *(const LAS bf16x8*)(lds + PG8_SA(b, h) + aoff + m * 2048 + k * 1024); } while (0)
; #define PG8_LDB(dst, b, h) do { _Pragma("unroll") for (int n = 0; n < 2; ++n) _Pragma("unroll") for (int k = 0; k < 2; ++k) dst[n][k] = *(const LAS bf16x8*)(lds + PG8_SB(b, h) + boff + n * 2048 + k * 1024); } while (0)
; #define PG8_MMA(ai, bj, At, Bt_) do { __builtin_amdgcn_s_setprio(1); _Pragma("unroll") for (int m = 0; m < 4; ++m) _Pragma("unroll") for (int n = 0; n < 2; ++n) _Pragma("unroll") for (int k = 0; k < 2; ++k) \
;         acc[ai][bj][m][n] = __builtin_amdgcn_mfma_f32_16x16x32_bf16(Bt_[n][k], At[m][k], acc[ai][bj][m][n], 0, 0, 0); __builtin_amdgcn_s_setprio(0); } while (0)
; #define PG8_WAIT_V(n) asm volatile("s_waitcnt vmcnt(" #n ")" ::: "memory")
; #define PG8_WAIT_L(n) asm volatile("s_waitcnt lgkmcnt(" #n ")" ::: "memory")
; #define PG8_BAR __builtin_amdgcn_s_barrier()
; template <int EK, int SK = -1>
; __device__ __forceinline__ void gemm_phase(LAS unsigned char* lds, const bf16_t* A, const bf16_t* Bt, int nM, int N, int K, const EpiArgs& E) {
;     ...
;         const bool has_next = S.next(ui + 1, nxt);
;         const char* nA = has_next ? (const char*)A + (size_t)nxt.pm * tstep : cA; const char* nB = has_next ? (const char*)Bt + (size_t)nxt.pn * tstep : cB;
;         for (int t = 0; t < nt; t += 2) {
;             const bool last = (t == nt - 2);
;             const char* a1 = cA + (size_t)(t + 1) * kstep;
;             const char* a2 = last ? nA : cA + (size_t)(t + 2) * kstep; const char* b2 = last ? nB : cB + (size_t)(t + 2) * kstep;
;             const char* a3 = a2 + kstep; const char* b3 = b2 + kstep;
;             PG8_LDB(B0, 0, 0); PG8_LDB(B1, 0, 1); PG8_SCHED; PG8_LDA(At, 0, 0); PG8_STAGEA(PG8_SA(1, 1), a1 + hstep);
;             PG8_WAIT_V(8); PG8_WAIT_L(0); PG8_BAR; PG8_MMA(0, 0, At, B0); PG8_MMA(0, 1, At, B1); PG8_BAR; PG8_SCHED;
;             PG8_LDA(At, 0, 1); PG8_STAGEB(PG8_SB(0, 0), b2); PG8_STAGEB(PG8_SB(0, 1), b2 + hstep); PG8_STAGEA(PG8_SA(0, 0), a2);
;             PG8_WAIT_V(8); PG8_WAIT_L(0); PG8_BAR; PG8_MMA(1, 0, At, B0); PG8_MMA(1, 1, At, B1); PG8_BAR; PG8_SCHED;
.LBB0_1245:
	v_add_u32_e32 v154, s54, v156
	ds_read_b128 v[150:153], v154
	ds_read_b128 v[160:163], v154 offset:1024
	ds_read_b128 v[164:167], v154 offset:2048
	ds_read_b128 v[168:171], v154 offset:3072
	v_add_u32_e32 v154, s55, v156
	s_add_u32 s42, s20, s40
	ds_read_b128 v[172:175], v154
	ds_read_b128 v[176:179], v154 offset:1024
	ds_read_b128 v[180:183], v154 offset:2048
	ds_read_b128 v[184:187], v154 offset:3072
	s_addc_u32 s43, s21, s41
	s_add_u32 s42, s42, 0x100
	s_addc_u32 s43, s43, 0
	s_add_u32 s70, s59, s40
	s_addc_u32 s71, s66, s41
	s_cmpk_eq_i32 s40, 0x700
	s_cselect_b32 s45, s27, s43
	s_cselect_b32 s44, s67, s42
	s_cselect_b32 s43, s23, s71
	s_cselect_b32 s42, s68, s70
	s_mov_b64 s[100:101], -1
	s_cmpk_lg_i32 s40, 0x700
	s_cbranch_scc1 .Lmy_mk_1245
	s_not_b64 s[100:101], s[4:5]
.Lmy_mk_1245:
	v_lshl_add_u64 v[154:155], v[146:147], 0, s[40:41]
	s_add_i32 m0, s17, 0xc000
	ds_read_b128 v[188:191], v159
	ds_read_b128 v[192:195], v159 offset:1024
	ds_read_b128 v[196:199], v159 offset:2048
	ds_read_b128 v[200:203], v159 offset:3072
	ds_read_b128 v[204:207], v159 offset:4096
	ds_read_b128 v[208:211], v159 offset:5120
	ds_read_b128 v[212:215], v159 offset:6144
	ds_read_b128 v[216:219], v159 offset:7168
	global_load_lds_dwordx4 v[154:155], off
	v_lshl_add_u64 v[154:155], v[148:149], 0, s[40:41]
	s_add_i32 m0, s17, 0xe000
	s_nop 0
	global_load_lds_dwordx4 v[154:155], off
	s_waitcnt vmcnt(8)
	s_waitcnt lgkmcnt(0)
	s_barrier
	s_waitcnt lgkmcnt(0)
	v_mfma_f32_16x16x32_bf16 v[110:113], v[150:153], v[188:191], v[110:113]
	v_mfma_f32_16x16x32_bf16 v[106:109], v[164:167], v[188:191], v[106:109]
	v_mfma_f32_16x16x32_bf16 v[102:105], v[150:153], v[196:199], v[102:105]
	v_mfma_f32_16x16x32_bf16 v[98:101], v[164:167], v[196:199], v[98:101]
	v_mfma_f32_16x16x32_bf16 v[94:97], v[150:153], v[204:207], v[94:97]
	v_mfma_f32_16x16x32_bf16 v[90:93], v[164:167], v[204:207], v[90:93]
	v_mfma_f32_16x16x32_bf16 v[86:89], v[150:153], v[212:215], v[86:89]
	v_mfma_f32_16x16x32_bf16 v[82:85], v[164:167], v[212:215], v[82:85]
	v_mfma_f32_16x16x32_bf16 v[110:113], v[160:163], v[192:195], v[110:113]
	v_mfma_f32_16x16x32_bf16 v[106:109], v[168:171], v[192:195], v[106:109]
	v_mfma_f32_16x16x32_bf16 v[102:105], v[160:163], v[200:203], v[102:105]
	v_mfma_f32_16x16x32_bf16 v[98:101], v[168:171], v[200:203], v[98:101]
	v_mfma_f32_16x16x32_bf16 v[94:97], v[160:163], v[208:211], v[94:97]
	v_mfma_f32_16x16x32_bf16 v[90:93], v[168:171], v[208:211], v[90:93]
	v_mfma_f32_16x16x32_bf16 v[86:89], v[160:163], v[216:219], v[86:89]
	v_mfma_f32_16x16x32_bf16 v[82:85], v[168:171], v[216:219], v[82:85]
	v_mfma_f32_16x16x32_bf16 v[78:81], v[172:175], v[188:191], v[78:81]
	v_mfma_f32_16x16x32_bf16 v[74:77], v[180:183], v[188:191], v[74:77]
	v_mfma_f32_16x16x32_bf16 v[70:73], v[172:175], v[196:199], v[70:73]
	v_mfma_f32_16x16x32_bf16 v[66:69], v[180:183], v[196:199], v[66:69]
	v_mfma_f32_16x16x32_bf16 v[62:65], v[172:175], v[204:207], v[62:65]
	v_mfma_f32_16x16x32_bf16 v[58:61], v[180:183], v[204:207], v[58:61]
	v_mfma_f32_16x16x32_bf16 v[54:57], v[172:175], v[212:215], v[54:57]
	v_mfma_f32_16x16x32_bf16 v[50:53], v[180:183], v[212:215], v[50:53]
	v_mfma_f32_16x16x32_bf16 v[78:81], v[176:179], v[192:195], v[78:81]
	v_mfma_f32_16x16x32_bf16 v[74:77], v[184:187], v[192:195], v[74:77]
	v_mfma_f32_16x16x32_bf16 v[70:73], v[176:179], v[200:203], v[70:73]
	v_mfma_f32_16x16x32_bf16 v[66:69], v[184:187], v[200:203], v[66:69]
	v_mfma_f32_16x16x32_bf16 v[62:65], v[176:179], v[208:211], v[62:65]
	v_mfma_f32_16x16x32_bf16 v[58:61], v[184:187], v[208:211], v[58:61]
	v_mfma_f32_16x16x32_bf16 v[54:57], v[176:179], v[216:219], v[54:57]
	v_mfma_f32_16x16x32_bf16 v[50:53], v[184:187], v[216:219], v[50:53]
	s_barrier
	s_add_i32 s70, s54, s49
	v_lshl_add_u64 v[154:155], s[42:43], 0, v[132:133]
	s_mov_b32 m0, s70
	ds_read_b128 v[188:191], v159 offset:16384
	ds_read_b128 v[192:195], v159 offset:17408
	ds_read_b128 v[196:199], v159 offset:18432
	ds_read_b128 v[200:203], v159 offset:19456
	ds_read_b128 v[204:207], v159 offset:20480
	ds_read_b128 v[208:211], v159 offset:21504
	ds_read_b128 v[212:215], v159 offset:22528
	ds_read_b128 v[216:219], v159 offset:23552
	s_mov_b64 exec, s[100:101]
	global_load_lds_dwordx4 v[154:155], off
	s_mov_b64 exec, -1
	s_add_i32 m0, s70, 0x2000
	s_add_u32 s70, s42, 0x40000
	v_lshl_add_u64 v[220:221], s[42:43], 0, v[136:137]
	s_addc_u32 s71, s43, 0
	s_add_i32 s72, s55, s49
	s_mov_b64 exec, s[100:101]
	global_load_lds_dwordx4 v[220:221], off
	s_mov_b64 exec, -1
	v_lshl_add_u64 v[222:223], s[70:71], 0, v[132:133]
	s_mov_b32 m0, s72
	v_lshl_add_u64 v[224:225], s[44:45], 0, v[134:135]
	s_mov_b64 exec, s[100:101]
	global_load_lds_dwordx4 v[222:223], off
	s_mov_b64 exec, -1
	v_lshl_add_u64 v[222:223], s[70:71], 0, v[136:137]
	s_add_i32 m0, s72, 0x2000
	s_nop 0
	s_mov_b64 exec, s[100:101]
	global_load_lds_dwordx4 v[222:223], off
	s_mov_b64 exec, -1
	v_lshl_add_u64 v[222:223], s[44:45], 0, v[130:131]
	s_mov_b32 m0, s17
	s_nop 0
	s_mov_b64 exec, s[100:101]
	global_load_lds_dwordx4 v[222:223], off
	s_mov_b64 exec, -1
	s_mov_b32 m0, s19
	s_nop 0
	s_mov_b64 exec, s[100:101]
	global_load_lds_dwordx4 v[224:225], off
	s_mov_b64 exec, -1
	s_waitcnt vmcnt(8)
	s_waitcnt lgkmcnt(0)
	s_barrier
; #define PG8_STAGEA(bufoff, gbase) PG8_STAGE_(bufoff, gbase, voffA)
; #define PG8_STAGEB(bufoff, gbase) PG8_STAGE_(bufoff, gbase, voffB)
; #define PG8_LDA(dst, b, h) do { _Pragma("unroll") for (int m = 0; m < 4; ++m) _Pragma("unroll") for (int k = 0; k < 2; ++k) dst[m][k] = *(const LAS bf16x8*)(lds + PG8_SA(b, h) + aoff + m * 2048 + k * 1024); } while (0)
; #define PG8_LDB(dst, b, h) do { _Pragma("unroll") for (int n = 0; n < 2; ++n) _Pragma("unroll") for (int k = 0; k < 2; ++k) dst[n][k] = *(const LAS bf16x8*)(lds + PG8_SB(b, h) + boff + n * 2048 + k * 1024); } while (0)
; #define PG8_MMA(ai, bj, At, Bt_) do { __builtin_amdgcn_s_setprio(1); _Pragma("unroll") for (int m = 0; m < 4; ++m) _Pragma("unroll") for (int n = 0; n < 2; ++n) _Pragma("unroll") for (int k = 0; k < 2; ++k) \
;         acc[ai][bj][m][n] = __builtin_amdgcn_mfma_f32_16x16x32_bf16(Bt_[n][k], At[m][k], acc[ai][bj][m][n], 0, 0, 0); __builtin_amdgcn_s_setprio(0); } while (0)
; #define PG8_WAIT_V(n) asm volatile("s_waitcnt vmcnt(" #n ")" ::: "memory")
; #define PG8_WAIT_L(n) asm volatile("s_waitcnt lgkmcnt(" #n ")" ::: "memory")
; #define PG8_BAR __builtin_amdgcn_s_barrier()
; #define PG8_SCHED __builtin_amdgcn_sched_barrier(0)
; template <int EK, int SK = -1>
; __device__ __forceinline__ void gemm_phase(LAS unsigned char* lds, const bf16_t* A, const bf16_t* Bt, int nM, int N, int K, const EpiArgs& E) {
;     ...
;             PG8_WAIT_V(8); PG8_WAIT_L(0); PG8_BAR; PG8_MMA(1, 0, At, B0); PG8_MMA(1, 1, At, B1); PG8_BAR; PG8_SCHED;
;             PG8_LDB(B0, 1, 0); PG8_LDB(B1, 1, 1); PG8_SCHED; PG8_LDA(At, 1, 0); PG8_STAGEA(PG8_SA(0, 1), a2 + hstep);
;             PG8_WAIT_V(8); PG8_WAIT_L(0); PG8_BAR; PG8_MMA(0, 0, At, B0); PG8_MMA(0, 1, At, B1); PG8_BAR; PG8_SCHED;
;             PG8_LDA(At, 1, 1); PG8_STAGEB(PG8_SB(1, 0), b3); PG8_STAGEB(PG8_SB(1, 1), b3 + hstep); PG8_STAGEA(PG8_SA(1, 0), a3);
	s_waitcnt lgkmcnt(0)
	v_mfma_f32_16x16x32_bf16 v[46:49], v[150:153], v[188:191], v[46:49]
	v_mfma_f32_16x16x32_bf16 v[42:45], v[164:167], v[188:191], v[42:45]
	v_mfma_f32_16x16x32_bf16 v[38:41], v[150:153], v[196:199], v[38:41]
	v_mfma_f32_16x16x32_bf16 v[34:37], v[164:167], v[196:199], v[34:37]
	v_mfma_f32_16x16x32_bf16 v[30:33], v[150:153], v[204:207], v[30:33]
	v_mfma_f32_16x16x32_bf16 v[26:29], v[164:167], v[204:207], v[26:29]
	v_mfma_f32_16x16x32_bf16 v[22:25], v[150:153], v[212:215], v[22:25]
	v_mfma_f32_16x16x32_bf16 v[18:21], v[164:167], v[212:215], v[18:21]
	v_mfma_f32_16x16x32_bf16 v[46:49], v[160:163], v[192:195], v[46:49]
	v_mfma_f32_16x16x32_bf16 v[42:45], v[168:171], v[192:195], v[42:45]
	v_mfma_f32_16x16x32_bf16 v[38:41], v[160:163], v[200:203], v[38:41]
	v_mfma_f32_16x16x32_bf16 v[34:37], v[168:171], v[200:203], v[34:37]
	v_mfma_f32_16x16x32_bf16 v[30:33], v[160:163], v[208:211], v[30:33]
	v_mfma_f32_16x16x32_bf16 v[26:29], v[168:171], v[208:211], v[26:29]
	v_mfma_f32_16x16x32_bf16 v[22:25], v[160:163], v[216:219], v[22:25]
	v_mfma_f32_16x16x32_bf16 v[18:21], v[168:171], v[216:219], v[18:21]
	v_mfma_f32_16x16x32_bf16 v[14:17], v[172:175], v[188:191], v[14:17]
	v_mfma_f32_16x16x32_bf16 v[10:13], v[180:183], v[188:191], v[10:13]
	v_mfma_f32_16x16x32_bf16 v[6:9], v[172:175], v[196:199], v[6:9]
	v_mfma_f32_16x16x32_bf16 v[2:5], v[180:183], v[196:199], v[2:5]
	v_mfma_f32_16x16x32_bf16 v[114:117], v[172:175], v[204:207], v[114:117]
	v_mfma_f32_16x16x32_bf16 v[118:121], v[180:183], v[204:207], v[118:121]
	v_mfma_f32_16x16x32_bf16 v[122:125], v[172:175], v[212:215], v[122:125]
	v_mfma_f32_16x16x32_bf16 v[126:129], v[180:183], v[212:215], v[126:129]
	v_mfma_f32_16x16x32_bf16 v[14:17], v[176:179], v[192:195], v[14:17]
	v_mfma_f32_16x16x32_bf16 v[10:13], v[184:187], v[192:195], v[10:13]
	v_mfma_f32_16x16x32_bf16 v[6:9], v[176:179], v[200:203], v[6:9]
	v_mfma_f32_16x16x32_bf16 v[2:5], v[184:187], v[200:203], v[2:5]
	v_mfma_f32_16x16x32_bf16 v[114:117], v[176:179], v[208:211], v[114:117]
	v_mfma_f32_16x16x32_bf16 v[118:121], v[184:187], v[208:211], v[118:121]
	v_mfma_f32_16x16x32_bf16 v[122:125], v[176:179], v[216:219], v[122:125]
	v_mfma_f32_16x16x32_bf16 v[126:129], v[184:187], v[216:219], v[126:129]
	s_barrier
	s_add_i32 s70, 0, 0x18000
	s_add_i32 s71, 0, 0x1c000
	v_add_u32_e32 v168, s70, v156
	v_add_u32_e32 v184, s71, v156
	ds_read_b128 v[150:153], v168
	ds_read_b128 v[160:163], v168 offset:1024
	ds_read_b128 v[164:167], v168 offset:2048
	ds_read_b128 v[168:171], v168 offset:3072
	ds_read_b128 v[172:175], v184
	ds_read_b128 v[176:179], v184 offset:1024
	ds_read_b128 v[180:183], v184 offset:2048
	ds_read_b128 v[184:187], v184 offset:3072
	s_add_u32 s44, s44, 0x40000
	s_addc_u32 s45, s45, 0
	s_mov_b32 m0, s50
	v_lshl_add_u64 v[226:227], s[44:45], 0, v[130:131]
	ds_read_b128 v[188:191], v159 offset:32768
	ds_read_b128 v[192:195], v159 offset:33792
	ds_read_b128 v[196:199], v159 offset:34816
	ds_read_b128 v[200:203], v159 offset:35840
	ds_read_b128 v[204:207], v159 offset:36864
	ds_read_b128 v[208:211], v159 offset:37888
	ds_read_b128 v[212:215], v159 offset:38912
	ds_read_b128 v[216:219], v159 offset:39936
	s_mov_b64 exec, s[100:101]
	global_load_lds_dwordx4 v[226:227], off
	s_mov_b64 exec, -1
	v_lshl_add_u64 v[226:227], s[44:45], 0, v[134:135]
	s_mov_b32 m0, s51
	s_nop 0
	s_mov_b64 exec, s[100:101]
	global_load_lds_dwordx4 v[226:227], off
	s_mov_b64 exec, -1
	s_waitcnt vmcnt(8)
	s_waitcnt lgkmcnt(0)
	s_barrier
	s_waitcnt lgkmcnt(0)
	v_mfma_f32_16x16x32_bf16 v[110:113], v[150:153], v[188:191], v[110:113]
	v_mfma_f32_16x16x32_bf16 v[106:109], v[164:167], v[188:191], v[106:109]
	v_mfma_f32_16x16x32_bf16 v[102:105], v[150:153], v[196:199], v[102:105]
	v_mfma_f32_16x16x32_bf16 v[98:101], v[164:167], v[196:199], v[98:101]
	v_mfma_f32_16x16x32_bf16 v[94:97], v[150:153], v[204:207], v[94:97]
	v_mfma_f32_16x16x32_bf16 v[90:93], v[164:167], v[204:207], v[90:93]
	v_mfma_f32_16x16x32_bf16 v[86:89], v[150:153], v[212:215], v[86:89]
	v_mfma_f32_16x16x32_bf16 v[82:85], v[164:167], v[212:215], v[82:85]
	v_mfma_f32_16x16x32_bf16 v[110:113], v[160:163], v[192:195], v[110:113]
	v_mfma_f32_16x16x32_bf16 v[106:109], v[168:171], v[192:195], v[106:109]
	v_mfma_f32_16x16x32_bf16 v[102:105], v[160:163], v[200:203], v[102:105]
	v_mfma_f32_16x16x32_bf16 v[98:101], v[168:171], v[200:203], v[98:101]
	v_mfma_f32_16x16x32_bf16 v[94:97], v[160:163], v[208:211], v[94:97]
	v_mfma_f32_16x16x32_bf16 v[90:93], v[168:171], v[208:211], v[90:93]
	v_mfma_f32_16x16x32_bf16 v[86:89], v[160:163], v[216:219], v[86:89]
	v_mfma_f32_16x16x32_bf16 v[82:85], v[168:171], v[216:219], v[82:85]
	v_mfma_f32_16x16x32_bf16 v[78:81], v[172:175], v[188:191], v[78:81]
	v_mfma_f32_16x16x32_bf16 v[74:77], v[180:183], v[188:191], v[74:77]
	v_mfma_f32_16x16x32_bf16 v[70:73], v[172:175], v[196:199], v[70:73]
	v_mfma_f32_16x16x32_bf16 v[66:69], v[180:183], v[196:199], v[66:69]
	v_mfma_f32_16x16x32_bf16 v[62:65], v[172:175], v[204:207], v[62:65]
	v_mfma_f32_16x16x32_bf16 v[58:61], v[180:183], v[204:207], v[58:61]
	v_mfma_f32_16x16x32_bf16 v[54:57], v[172:175], v[212:215], v[54:57]
	v_mfma_f32_16x16x32_bf16 v[50:53], v[180:183], v[212:215], v[50:53]
	v_mfma_f32_16x16x32_bf16 v[78:81], v[176:179], v[192:195], v[78:81]
	v_mfma_f32_16x16x32_bf16 v[74:77], v[184:187], v[192:195], v[74:77]
	v_mfma_f32_16x16x32_bf16 v[70:73], v[176:179], v[200:203], v[70:73]
	v_mfma_f32_16x16x32_bf16 v[66:69], v[184:187], v[200:203], v[66:69]
	v_mfma_f32_16x16x32_bf16 v[62:65], v[176:179], v[208:211], v[62:65]
	v_mfma_f32_16x16x32_bf16 v[58:61], v[184:187], v[208:211], v[58:61]
	v_mfma_f32_16x16x32_bf16 v[54:57], v[176:179], v[216:219], v[54:57]
	v_mfma_f32_16x16x32_bf16 v[50:53], v[184:187], v[216:219], v[50:53]
	s_barrier
; #define PG8_STAGEA(bufoff, gbase) PG8_STAGE_(bufoff, gbase, voffA)
; #define PG8_STAGEB(bufoff, gbase) PG8_STAGE_(bufoff, gbase, voffB)
; #define PG8_LDA(dst, b, h) do { _Pragma("unroll") for (int m = 0; m < 4; ++m) _Pragma("unroll") for (int k = 0; k < 2; ++k) dst[m][k] = *(const LAS bf16x8*)(lds + PG8_SA(b, h) + aoff + m * 2048 + k * 1024); } while (0)
; #define PG8_MMA(ai, bj, At, Bt_) do { __builtin_amdgcn_s_setprio(1); _Pragma("unroll") for (int m = 0; m < 4; ++m) _Pragma("unroll") for (int n = 0; n < 2; ++n) _Pragma("unroll") for (int k = 0; k < 2; ++k) \
;         acc[ai][bj][m][n] = __builtin_amdgcn_mfma_f32_16x16x32_bf16(Bt_[n][k], At[m][k], acc[ai][bj][m][n], 0, 0, 0); __builtin_amdgcn_s_setprio(0); } while (0)
; #define PG8_WAIT_V(n) asm volatile("s_waitcnt vmcnt(" #n ")" ::: "memory")
; #define PG8_WAIT_L(n) asm volatile("s_waitcnt lgkmcnt(" #n ")" ::: "memory")
; #define PG8_BAR __builtin_amdgcn_s_barrier()
; #define PG8_SCHED __builtin_amdgcn_sched_barrier(0)
; template <int EK, int SK = -1>
; __device__ __forceinline__ void gemm_phase(LAS unsigned char* lds, const bf16_t* A, const bf16_t* Bt, int nM, int N, int K, const EpiArgs& E) {
;     ...
;             PG8_LDA(At, 1, 1); PG8_STAGEB(PG8_SB(1, 0), b3); PG8_STAGEB(PG8_SB(1, 1), b3 + hstep); PG8_STAGEA(PG8_SA(1, 0), a3);
;             PG8_WAIT_V(8); PG8_WAIT_L(0); PG8_BAR; PG8_MMA(1, 0, At, B0); PG8_MMA(1, 1, At, B1); PG8_BAR; PG8_SCHED;
;         }
	s_add_i32 s44, s70, s49
	v_lshl_add_u64 v[154:155], v[154:155], 0, s[10:11]
	s_mov_b32 m0, s44
	ds_read_b128 v[188:191], v159 offset:49152
	ds_read_b128 v[192:195], v159 offset:50176
	ds_read_b128 v[196:199], v159 offset:51200
	ds_read_b128 v[200:203], v159 offset:52224
	ds_read_b128 v[204:207], v159 offset:53248
	ds_read_b128 v[208:211], v159 offset:54272
	ds_read_b128 v[212:215], v159 offset:55296
	ds_read_b128 v[216:219], v159 offset:56320
	s_mov_b64 exec, s[100:101]
	global_load_lds_dwordx4 v[154:155], off
	s_mov_b64 exec, -1
	s_add_i32 m0, s44, 0x2000
	s_add_u32 s42, s42, 0x40080
	v_lshl_add_u64 v[154:155], v[220:221], 0, s[10:11]
	s_addc_u32 s43, s43, 0
	s_add_i32 s44, s71, s49
	s_mov_b64 exec, s[100:101]
	global_load_lds_dwordx4 v[154:155], off
	s_mov_b64 exec, -1
	v_lshl_add_u64 v[154:155], s[42:43], 0, v[132:133]
	s_mov_b32 m0, s44
	s_nop 0
	s_mov_b64 exec, s[100:101]
	global_load_lds_dwordx4 v[154:155], off
	s_mov_b64 exec, -1
	v_lshl_add_u64 v[154:155], s[42:43], 0, v[136:137]
	s_add_i32 m0, s44, 0x2000
	s_nop 0
	s_mov_b64 exec, s[100:101]
	global_load_lds_dwordx4 v[154:155], off
	s_mov_b64 exec, -1
	v_lshl_add_u64 v[154:155], v[222:223], 0, s[10:11]
	s_mov_b32 m0, s52
	s_nop 0
	s_mov_b64 exec, s[100:101]
	global_load_lds_dwordx4 v[154:155], off
	s_mov_b64 exec, -1
	v_lshl_add_u64 v[154:155], v[224:225], 0, s[10:11]
	s_mov_b32 m0, s53
	s_nop 0
	s_mov_b64 exec, s[100:101]
	global_load_lds_dwordx4 v[154:155], off
	s_mov_b64 exec, -1
	s_waitcnt vmcnt(8)
	s_waitcnt lgkmcnt(0)
	s_barrier
	s_waitcnt lgkmcnt(0)
	v_mfma_f32_16x16x32_bf16 v[46:49], v[150:153], v[188:191], v[46:49]
	v_mfma_f32_16x16x32_bf16 v[42:45], v[164:167], v[188:191], v[42:45]
	v_mfma_f32_16x16x32_bf16 v[38:41], v[150:153], v[196:199], v[38:41]
	v_mfma_f32_16x16x32_bf16 v[34:37], v[164:167], v[196:199], v[34:37]
	v_mfma_f32_16x16x32_bf16 v[30:33], v[150:153], v[204:207], v[30:33]
	v_mfma_f32_16x16x32_bf16 v[26:29], v[164:167], v[204:207], v[26:29]
	v_mfma_f32_16x16x32_bf16 v[22:25], v[150:153], v[212:215], v[22:25]
	v_mfma_f32_16x16x32_bf16 v[18:21], v[164:167], v[212:215], v[18:21]
	v_mfma_f32_16x16x32_bf16 v[46:49], v[160:163], v[192:195], v[46:49]
	v_mfma_f32_16x16x32_bf16 v[42:45], v[168:171], v[192:195], v[42:45]
	v_mfma_f32_16x16x32_bf16 v[38:41], v[160:163], v[200:203], v[38:41]
	v_mfma_f32_16x16x32_bf16 v[34:37], v[168:171], v[200:203], v[34:37]
	v_mfma_f32_16x16x32_bf16 v[30:33], v[160:163], v[208:211], v[30:33]
	v_mfma_f32_16x16x32_bf16 v[26:29], v[168:171], v[208:211], v[26:29]
	v_mfma_f32_16x16x32_bf16 v[22:25], v[160:163], v[216:219], v[22:25]
	v_mfma_f32_16x16x32_bf16 v[18:21], v[168:171], v[216:219], v[18:21]
	v_mfma_f32_16x16x32_bf16 v[14:17], v[172:175], v[188:191], v[14:17]
	v_mfma_f32_16x16x32_bf16 v[10:13], v[180:183], v[188:191], v[10:13]
	v_mfma_f32_16x16x32_bf16 v[6:9], v[172:175], v[196:199], v[6:9]
	v_mfma_f32_16x16x32_bf16 v[2:5], v[180:183], v[196:199], v[2:5]
	v_mfma_f32_16x16x32_bf16 v[114:117], v[172:175], v[204:207], v[114:117]
	v_mfma_f32_16x16x32_bf16 v[118:121], v[180:183], v[204:207], v[118:121]
	v_mfma_f32_16x16x32_bf16 v[122:125], v[172:175], v[212:215], v[122:125]
	v_mfma_f32_16x16x32_bf16 v[126:129], v[180:183], v[212:215], v[126:129]
	v_mfma_f32_16x16x32_bf16 v[14:17], v[176:179], v[192:195], v[14:17]
	v_mfma_f32_16x16x32_bf16 v[10:13], v[184:187], v[192:195], v[10:13]
	v_mfma_f32_16x16x32_bf16 v[6:9], v[176:179], v[200:203], v[6:9]
	v_mfma_f32_16x16x32_bf16 v[2:5], v[184:187], v[200:203], v[2:5]
	v_mfma_f32_16x16x32_bf16 v[114:117], v[176:179], v[208:211], v[114:117]
	v_mfma_f32_16x16x32_bf16 v[118:121], v[184:187], v[208:211], v[118:121]
	v_mfma_f32_16x16x32_bf16 v[122:125], v[176:179], v[216:219], v[122:125]
	v_mfma_f32_16x16x32_bf16 v[126:129], v[184:187], v[216:219], v[126:129]
	s_barrier
	s_add_i32 s69, s69, 2
	s_add_u32 s40, s40, 0x100
	s_addc_u32 s41, s41, 0
	s_cmp_gt_u32 s69, 13
	s_cbranch_scc0 .LBB0_1245

; #define PG8_STAGEA(bufoff, gbase) PG8_STAGE_(bufoff, gbase, voffA)
; #define PG8_STAGEB(bufoff, gbase) PG8_STAGE_(bufoff, gbase, voffB)
; #define PG8_LDA(dst, b, h) do { _Pragma("unroll") for (int m = 0; m < 4; ++m) _Pragma("unroll") for (int k = 0; k < 2; ++k) dst[m][k] = *(const LAS bf16x8*)(lds + PG8_SA(b, h) + aoff + m * 2048 + k * 1024); } while (0)
; #define PG8_LDB(dst, b, h) do { _Pragma("unroll") for (int n = 0; n < 2; ++n) _Pragma("unroll") for (int k = 0; k < 2; ++k) dst[n][k] = *(const LAS bf16x8*)(lds + PG8_SB(b, h) + boff + n * 2048 + k * 1024); } while (0)
; #define PG8_MMA(ai, bj, At, Bt_) do { __builtin_amdgcn_s_setprio(1); _Pragma("unroll") for (int m = 0; m < 4; ++m) _Pragma("unroll") for (int n = 0; n < 2; ++n) _Pragma("unroll") for (int k = 0; k < 2; ++k) \
;         acc[ai][bj][m][n] = __builtin_amdgcn_mfma_f32_16x16x32_bf16(Bt_[n][k], At[m][k], acc[ai][bj][m][n], 0, 0, 0); __builtin_amdgcn_s_setprio(0); } while (0)
; #define PG8_WAIT_V(n) asm volatile("s_waitcnt vmcnt(" #n ")" ::: "memory")
; #define PG8_WAIT_L(n) asm volatile("s_waitcnt lgkmcnt(" #n ")" ::: "memory")
; #define PG8_BAR __builtin_amdgcn_s_barrier()
; template <int EK, int SK = -1>
; __device__ __forceinline__ void gemm_phase(LAS unsigned char* lds, const bf16_t* A, const bf16_t* Bt, int nM, int N, int K, const EpiArgs& E) {
;     ...
;         const bool has_next = S.next(ui + 1, nxt);
;         const char* nA = has_next ? (const char*)A + (size_t)nxt.pm * tstep : cA; const char* nB = has_next ? (const char*)Bt + (size_t)nxt.pn * tstep : cB;
;         for (int t = 0; t < nt; t += 2) {
;             const bool last = (t == nt - 2);
;             const char* a1 = cA + (size_t)(t + 1) * kstep;
;             const char* a2 = last ? nA : cA + (size_t)(t + 2) * kstep; const char* b2 = last ? nB : cB + (size_t)(t + 2) * kstep;
;             const char* a3 = a2 + kstep; const char* b3 = b2 + kstep;
;             PG8_LDB(B0, 0, 0); PG8_LDB(B1, 0, 1); PG8_SCHED; PG8_LDA(At, 0, 0); PG8_STAGEA(PG8_SA(1, 1), a1 + hstep);
;             PG8_WAIT_V(8); PG8_WAIT_L(0); PG8_BAR; PG8_MMA(0, 0, At, B0); PG8_MMA(0, 1, At, B1); PG8_BAR; PG8_SCHED;
;             PG8_LDA(At, 0, 1); PG8_STAGEB(PG8_SB(0, 0), b2); PG8_STAGEB(PG8_SB(0, 1), b2 + hstep); PG8_STAGEA(PG8_SA(0, 0), a2);
;             PG8_WAIT_V(8); PG8_WAIT_L(0); PG8_BAR; PG8_MMA(1, 0, At, B0); PG8_MMA(1, 1, At, B1); PG8_BAR; PG8_SCHED;
.LBB0_1401:
	v_add_u32_e32 v168, s66, v154
	v_add_u32_e32 v184, s67, v154
	s_add_u32 s42, s20, s40
	ds_read_b128 v[156:159], v168
	ds_read_b128 v[160:163], v168 offset:1024
	ds_read_b128 v[164:167], v168 offset:2048
	ds_read_b128 v[168:171], v168 offset:3072
	ds_read_b128 v[172:175], v184
	ds_read_b128 v[176:179], v184 offset:1024
	ds_read_b128 v[180:183], v184 offset:2048
	ds_read_b128 v[184:187], v184 offset:3072
	s_addc_u32 s43, s21, s41
	s_add_u32 s42, s42, 0x100
	s_addc_u32 s43, s43, 0
	s_add_u32 s73, s37, s40
	s_addc_u32 s74, s71, s41
	s_cmpk_eq_i32 s40, 0x1500
	s_cselect_b32 s45, s7, s43
	s_cselect_b32 s44, s6, s42
	s_cselect_b32 s43, s39, s74
	s_cselect_b32 s42, s38, s73
	s_mov_b64 s[100:101], -1
	s_cmpk_lg_i32 s40, 0x1500
	s_cbranch_scc1 .Lmy_mk_1401
	s_not_b64 s[100:101], s[0:1]
.Lmy_mk_1401:
	v_lshl_add_u64 v[220:221], v[146:147], 0, s[40:41]
	s_add_i32 m0, s53, 0xc000
	ds_read_b128 v[188:191], v155
	ds_read_b128 v[192:195], v155 offset:1024
	ds_read_b128 v[196:199], v155 offset:2048
	ds_read_b128 v[200:203], v155 offset:3072
	ds_read_b128 v[204:207], v155 offset:4096
	ds_read_b128 v[208:211], v155 offset:5120
	ds_read_b128 v[212:215], v155 offset:6144
	ds_read_b128 v[216:219], v155 offset:7168
	global_load_lds_dwordx4 v[220:221], off
	v_lshl_add_u64 v[220:221], v[148:149], 0, s[40:41]
	s_add_i32 m0, s53, 0xe000
	s_nop 0
	global_load_lds_dwordx4 v[220:221], off
	s_waitcnt vmcnt(8)
	s_waitcnt lgkmcnt(0)
	s_barrier
	s_waitcnt lgkmcnt(0)
	v_mfma_f32_16x16x32_bf16 v[126:129], v[156:159], v[188:191], v[126:129]
	v_mfma_f32_16x16x32_bf16 v[122:125], v[164:167], v[188:191], v[122:125]
	v_mfma_f32_16x16x32_bf16 v[110:113], v[156:159], v[196:199], v[110:113]
	v_mfma_f32_16x16x32_bf16 v[106:109], v[164:167], v[196:199], v[106:109]
	v_mfma_f32_16x16x32_bf16 v[94:97], v[156:159], v[204:207], v[94:97]
	v_mfma_f32_16x16x32_bf16 v[90:93], v[164:167], v[204:207], v[90:93]
	v_mfma_f32_16x16x32_bf16 v[78:81], v[156:159], v[212:215], v[78:81]
	v_mfma_f32_16x16x32_bf16 v[74:77], v[164:167], v[212:215], v[74:77]
	v_mfma_f32_16x16x32_bf16 v[126:129], v[160:163], v[192:195], v[126:129]
	v_mfma_f32_16x16x32_bf16 v[122:125], v[168:171], v[192:195], v[122:125]
	v_mfma_f32_16x16x32_bf16 v[110:113], v[160:163], v[200:203], v[110:113]
	v_mfma_f32_16x16x32_bf16 v[106:109], v[168:171], v[200:203], v[106:109]
	v_mfma_f32_16x16x32_bf16 v[94:97], v[160:163], v[208:211], v[94:97]
	v_mfma_f32_16x16x32_bf16 v[90:93], v[168:171], v[208:211], v[90:93]
	v_mfma_f32_16x16x32_bf16 v[78:81], v[160:163], v[216:219], v[78:81]
	v_mfma_f32_16x16x32_bf16 v[74:77], v[168:171], v[216:219], v[74:77]
	v_mfma_f32_16x16x32_bf16 v[118:121], v[172:175], v[188:191], v[118:121]
	v_mfma_f32_16x16x32_bf16 v[114:117], v[180:183], v[188:191], v[114:117]
	v_mfma_f32_16x16x32_bf16 v[102:105], v[172:175], v[196:199], v[102:105]
	v_mfma_f32_16x16x32_bf16 v[98:101], v[180:183], v[196:199], v[98:101]
	v_mfma_f32_16x16x32_bf16 v[86:89], v[172:175], v[204:207], v[86:89]
	v_mfma_f32_16x16x32_bf16 v[82:85], v[180:183], v[204:207], v[82:85]
	v_mfma_f32_16x16x32_bf16 v[70:73], v[172:175], v[212:215], v[70:73]
	v_mfma_f32_16x16x32_bf16 v[66:69], v[180:183], v[212:215], v[66:69]
	v_mfma_f32_16x16x32_bf16 v[118:121], v[176:179], v[192:195], v[118:121]
	v_mfma_f32_16x16x32_bf16 v[114:117], v[184:187], v[192:195], v[114:117]
	v_mfma_f32_16x16x32_bf16 v[102:105], v[176:179], v[200:203], v[102:105]
	v_mfma_f32_16x16x32_bf16 v[98:101], v[184:187], v[200:203], v[98:101]
	v_mfma_f32_16x16x32_bf16 v[86:89], v[176:179], v[208:211], v[86:89]
	v_mfma_f32_16x16x32_bf16 v[82:85], v[184:187], v[208:211], v[82:85]
	v_mfma_f32_16x16x32_bf16 v[70:73], v[176:179], v[216:219], v[70:73]
	v_mfma_f32_16x16x32_bf16 v[66:69], v[184:187], v[216:219], v[66:69]
	s_barrier
	s_add_i32 s73, s66, s52
	v_lshl_add_u64 v[220:221], s[42:43], 0, v[132:133]
	s_mov_b32 m0, s73
	ds_read_b128 v[188:191], v155 offset:16384
	ds_read_b128 v[192:195], v155 offset:17408
	ds_read_b128 v[196:199], v155 offset:18432
	ds_read_b128 v[200:203], v155 offset:19456
	ds_read_b128 v[204:207], v155 offset:20480
	ds_read_b128 v[208:211], v155 offset:21504
	ds_read_b128 v[212:215], v155 offset:22528
	ds_read_b128 v[216:219], v155 offset:23552
	s_mov_b64 exec, s[100:101]
	global_load_lds_dwordx4 v[220:221], off
	s_mov_b64 exec, -1
	s_add_i32 m0, s73, 0x2000
	s_add_u32 s74, s42, 0xb0000
	v_lshl_add_u64 v[222:223], s[42:43], 0, v[136:137]
	s_addc_u32 s75, s43, 0
	s_add_i32 s73, s67, s52
	s_mov_b64 exec, s[100:101]
	global_load_lds_dwordx4 v[222:223], off
	s_mov_b64 exec, -1
	v_lshl_add_u64 v[224:225], s[74:75], 0, v[132:133]
	s_mov_b32 m0, s73
	v_lshl_add_u64 v[226:227], s[44:45], 0, v[134:135]
	s_mov_b64 exec, s[100:101]
	global_load_lds_dwordx4 v[224:225], off
	s_mov_b64 exec, -1
	v_lshl_add_u64 v[224:225], s[74:75], 0, v[136:137]
	s_add_i32 m0, s73, 0x2000
	s_nop 0
	s_mov_b64 exec, s[100:101]
	global_load_lds_dwordx4 v[224:225], off
	s_mov_b64 exec, -1
	v_lshl_add_u64 v[224:225], s[44:45], 0, v[130:131]
	s_mov_b32 m0, s53
	s_nop 0
	s_mov_b64 exec, s[100:101]
	global_load_lds_dwordx4 v[224:225], off
	s_mov_b64 exec, -1
	s_mov_b32 m0, s54
	s_nop 0
	s_mov_b64 exec, s[100:101]
	global_load_lds_dwordx4 v[226:227], off
	s_mov_b64 exec, -1
	s_waitcnt vmcnt(8)
	s_waitcnt lgkmcnt(0)
	s_barrier
; #define PG8_STAGEA(bufoff, gbase) PG8_STAGE_(bufoff, gbase, voffA)
; #define PG8_STAGEB(bufoff, gbase) PG8_STAGE_(bufoff, gbase, voffB)
; #define PG8_LDA(dst, b, h) do { _Pragma("unroll") for (int m = 0; m < 4; ++m) _Pragma("unroll") for (int k = 0; k < 2; ++k) dst[m][k] = *(const LAS bf16x8*)(lds + PG8_SA(b, h) + aoff + m * 2048 + k * 1024); } while (0)
; #define PG8_LDB(dst, b, h) do { _Pragma("unroll") for (int n = 0; n < 2; ++n) _Pragma("unroll") for (int k = 0; k < 2; ++k) dst[n][k] = *(const LAS bf16x8*)(lds + PG8_SB(b, h) + boff + n * 2048 + k * 1024); } while (0)
; #define PG8_MMA(ai, bj, At, Bt_) do { __builtin_amdgcn_s_setprio(1); _Pragma("unroll") for (int m = 0; m < 4; ++m) _Pragma("unroll") for (int n = 0; n < 2; ++n) _Pragma("unroll") for (int k = 0; k < 2; ++k) \
;         acc[ai][bj][m][n] = __builtin_amdgcn_mfma_f32_16x16x32_bf16(Bt_[n][k], At[m][k], acc[ai][bj][m][n], 0, 0, 0); __builtin_amdgcn_s_setprio(0); } while (0)
; #define PG8_WAIT_V(n) asm volatile("s_waitcnt vmcnt(" #n ")" ::: "memory")
; #define PG8_WAIT_L(n) asm volatile("s_waitcnt lgkmcnt(" #n ")" ::: "memory")
; #define PG8_BAR __builtin_amdgcn_s_barrier()
; #define PG8_SCHED __builtin_amdgcn_sched_barrier(0)
; template <int EK, int SK = -1>
; __device__ __forceinline__ void gemm_phase(LAS unsigned char* lds, const bf16_t* A, const bf16_t* Bt, int nM, int N, int K, const EpiArgs& E) {
;     ...
;             PG8_WAIT_V(8); PG8_WAIT_L(0); PG8_BAR; PG8_MMA(1, 0, At, B0); PG8_MMA(1, 1, At, B1); PG8_BAR; PG8_SCHED;
;             PG8_LDB(B0, 1, 0); PG8_LDB(B1, 1, 1); PG8_SCHED; PG8_LDA(At, 1, 0); PG8_STAGEA(PG8_SA(0, 1), a2 + hstep);
;             PG8_WAIT_V(8); PG8_WAIT_L(0); PG8_BAR; PG8_MMA(0, 0, At, B0); PG8_MMA(0, 1, At, B1); PG8_BAR; PG8_SCHED;
;             PG8_LDA(At, 1, 1); PG8_STAGEB(PG8_SB(1, 0), b3); PG8_STAGEB(PG8_SB(1, 1), b3 + hstep); PG8_STAGEA(PG8_SA(1, 0), a3);
	s_waitcnt lgkmcnt(0)
	v_mfma_f32_16x16x32_bf16 v[62:65], v[156:159], v[188:191], v[62:65]
	v_mfma_f32_16x16x32_bf16 v[58:61], v[164:167], v[188:191], v[58:61]
	v_mfma_f32_16x16x32_bf16 v[46:49], v[156:159], v[196:199], v[46:49]
	v_mfma_f32_16x16x32_bf16 v[42:45], v[164:167], v[196:199], v[42:45]
	v_mfma_f32_16x16x32_bf16 v[30:33], v[156:159], v[204:207], v[30:33]
	v_mfma_f32_16x16x32_bf16 v[26:29], v[164:167], v[204:207], v[26:29]
	v_mfma_f32_16x16x32_bf16 v[14:17], v[156:159], v[212:215], v[14:17]
	v_mfma_f32_16x16x32_bf16 v[10:13], v[164:167], v[212:215], v[10:13]
	v_mfma_f32_16x16x32_bf16 v[62:65], v[160:163], v[192:195], v[62:65]
	v_mfma_f32_16x16x32_bf16 v[58:61], v[168:171], v[192:195], v[58:61]
	v_mfma_f32_16x16x32_bf16 v[46:49], v[160:163], v[200:203], v[46:49]
	v_mfma_f32_16x16x32_bf16 v[42:45], v[168:171], v[200:203], v[42:45]
	v_mfma_f32_16x16x32_bf16 v[30:33], v[160:163], v[208:211], v[30:33]
	v_mfma_f32_16x16x32_bf16 v[26:29], v[168:171], v[208:211], v[26:29]
	v_mfma_f32_16x16x32_bf16 v[14:17], v[160:163], v[216:219], v[14:17]
	v_mfma_f32_16x16x32_bf16 v[10:13], v[168:171], v[216:219], v[10:13]
	v_mfma_f32_16x16x32_bf16 v[54:57], v[172:175], v[188:191], v[54:57]
	v_mfma_f32_16x16x32_bf16 v[50:53], v[180:183], v[188:191], v[50:53]
	v_mfma_f32_16x16x32_bf16 v[38:41], v[172:175], v[196:199], v[38:41]
	v_mfma_f32_16x16x32_bf16 v[34:37], v[180:183], v[196:199], v[34:37]
	v_mfma_f32_16x16x32_bf16 v[22:25], v[172:175], v[204:207], v[22:25]
	v_mfma_f32_16x16x32_bf16 v[18:21], v[180:183], v[204:207], v[18:21]
	v_mfma_f32_16x16x32_bf16 v[6:9], v[172:175], v[212:215], v[6:9]
	v_mfma_f32_16x16x32_bf16 v[2:5], v[180:183], v[212:215], v[2:5]
	v_mfma_f32_16x16x32_bf16 v[54:57], v[176:179], v[192:195], v[54:57]
	v_mfma_f32_16x16x32_bf16 v[50:53], v[184:187], v[192:195], v[50:53]
	v_mfma_f32_16x16x32_bf16 v[38:41], v[176:179], v[200:203], v[38:41]
	v_mfma_f32_16x16x32_bf16 v[34:37], v[184:187], v[200:203], v[34:37]
	v_mfma_f32_16x16x32_bf16 v[22:25], v[176:179], v[208:211], v[22:25]
	v_mfma_f32_16x16x32_bf16 v[18:21], v[184:187], v[208:211], v[18:21]
	v_mfma_f32_16x16x32_bf16 v[6:9], v[176:179], v[216:219], v[6:9]
	v_mfma_f32_16x16x32_bf16 v[2:5], v[184:187], v[216:219], v[2:5]
	s_barrier
	s_add_i32 s73, 0, 0x18000
	s_add_i32 s74, 0, 0x1c000
	v_add_u32_e32 v168, s73, v154
	v_add_u32_e32 v184, s74, v154
	ds_read_b128 v[156:159], v168
	ds_read_b128 v[160:163], v168 offset:1024
	ds_read_b128 v[164:167], v168 offset:2048
	ds_read_b128 v[168:171], v168 offset:3072
	ds_read_b128 v[172:175], v184
	ds_read_b128 v[176:179], v184 offset:1024
	ds_read_b128 v[180:183], v184 offset:2048
	ds_read_b128 v[184:187], v184 offset:3072
	s_add_u32 s44, s44, 0xb0000
	s_addc_u32 s45, s45, 0
	s_mov_b32 m0, s55
	v_lshl_add_u64 v[228:229], s[44:45], 0, v[130:131]
	ds_read_b128 v[188:191], v155 offset:32768
	ds_read_b128 v[192:195], v155 offset:33792
	ds_read_b128 v[196:199], v155 offset:34816
	ds_read_b128 v[200:203], v155 offset:35840
	ds_read_b128 v[204:207], v155 offset:36864
	ds_read_b128 v[208:211], v155 offset:37888
	ds_read_b128 v[212:215], v155 offset:38912
	ds_read_b128 v[216:219], v155 offset:39936
	s_mov_b64 exec, s[100:101]
	global_load_lds_dwordx4 v[228:229], off
	s_mov_b64 exec, -1
	v_lshl_add_u64 v[228:229], s[44:45], 0, v[134:135]
	s_mov_b32 m0, s56
	s_nop 0
	s_mov_b64 exec, s[100:101]
	global_load_lds_dwordx4 v[228:229], off
	s_mov_b64 exec, -1
	s_waitcnt vmcnt(8)
	s_waitcnt lgkmcnt(0)
	s_barrier
	s_waitcnt lgkmcnt(0)
	v_mfma_f32_16x16x32_bf16 v[126:129], v[156:159], v[188:191], v[126:129]
	v_mfma_f32_16x16x32_bf16 v[122:125], v[164:167], v[188:191], v[122:125]
	v_mfma_f32_16x16x32_bf16 v[110:113], v[156:159], v[196:199], v[110:113]
	v_mfma_f32_16x16x32_bf16 v[106:109], v[164:167], v[196:199], v[106:109]
	v_mfma_f32_16x16x32_bf16 v[94:97], v[156:159], v[204:207], v[94:97]
	v_mfma_f32_16x16x32_bf16 v[90:93], v[164:167], v[204:207], v[90:93]
	v_mfma_f32_16x16x32_bf16 v[78:81], v[156:159], v[212:215], v[78:81]
	v_mfma_f32_16x16x32_bf16 v[74:77], v[164:167], v[212:215], v[74:77]
	v_mfma_f32_16x16x32_bf16 v[126:129], v[160:163], v[192:195], v[126:129]
	v_mfma_f32_16x16x32_bf16 v[122:125], v[168:171], v[192:195], v[122:125]
	v_mfma_f32_16x16x32_bf16 v[110:113], v[160:163], v[200:203], v[110:113]
	v_mfma_f32_16x16x32_bf16 v[106:109], v[168:171], v[200:203], v[106:109]
	v_mfma_f32_16x16x32_bf16 v[94:97], v[160:163], v[208:211], v[94:97]
	v_mfma_f32_16x16x32_bf16 v[90:93], v[168:171], v[208:211], v[90:93]
	v_mfma_f32_16x16x32_bf16 v[78:81], v[160:163], v[216:219], v[78:81]
	v_mfma_f32_16x16x32_bf16 v[74:77], v[168:171], v[216:219], v[74:77]
	v_mfma_f32_16x16x32_bf16 v[118:121], v[172:175], v[188:191], v[118:121]
	v_mfma_f32_16x16x32_bf16 v[114:117], v[180:183], v[188:191], v[114:117]
	v_mfma_f32_16x16x32_bf16 v[102:105], v[172:175], v[196:199], v[102:105]
	v_mfma_f32_16x16x32_bf16 v[98:101], v[180:183], v[196:199], v[98:101]
	v_mfma_f32_16x16x32_bf16 v[86:89], v[172:175], v[204:207], v[86:89]
	v_mfma_f32_16x16x32_bf16 v[82:85], v[180:183], v[204:207], v[82:85]
	v_mfma_f32_16x16x32_bf16 v[70:73], v[172:175], v[212:215], v[70:73]
	v_mfma_f32_16x16x32_bf16 v[66:69], v[180:183], v[212:215], v[66:69]
	v_mfma_f32_16x16x32_bf16 v[118:121], v[176:179], v[192:195], v[118:121]
	v_mfma_f32_16x16x32_bf16 v[114:117], v[184:187], v[192:195], v[114:117]
	v_mfma_f32_16x16x32_bf16 v[102:105], v[176:179], v[200:203], v[102:105]
	v_mfma_f32_16x16x32_bf16 v[98:101], v[184:187], v[200:203], v[98:101]
	v_mfma_f32_16x16x32_bf16 v[86:89], v[176:179], v[208:211], v[86:89]
	v_mfma_f32_16x16x32_bf16 v[82:85], v[184:187], v[208:211], v[82:85]
	v_mfma_f32_16x16x32_bf16 v[70:73], v[176:179], v[216:219], v[70:73]
	v_mfma_f32_16x16x32_bf16 v[66:69], v[184:187], v[216:219], v[66:69]
	s_barrier
; #define PG8_STAGEA(bufoff, gbase) PG8_STAGE_(bufoff, gbase, voffA)
; #define PG8_STAGEB(bufoff, gbase) PG8_STAGE_(bufoff, gbase, voffB)
; #define PG8_LDA(dst, b, h) do { _Pragma("unroll") for (int m = 0; m < 4; ++m) _Pragma("unroll") for (int k = 0; k < 2; ++k) dst[m][k] = *(const LAS bf16x8*)(lds + PG8_SA(b, h) + aoff + m * 2048 + k * 1024); } while (0)
; #define PG8_MMA(ai, bj, At, Bt_) do { __builtin_amdgcn_s_setprio(1); _Pragma("unroll") for (int m = 0; m < 4; ++m) _Pragma("unroll") for (int n = 0; n < 2; ++n) _Pragma("unroll") for (int k = 0; k < 2; ++k) \
;         acc[ai][bj][m][n] = __builtin_amdgcn_mfma_f32_16x16x32_bf16(Bt_[n][k], At[m][k], acc[ai][bj][m][n], 0, 0, 0); __builtin_amdgcn_s_setprio(0); } while (0)
; #define PG8_WAIT_V(n) asm volatile("s_waitcnt vmcnt(" #n ")" ::: "memory")
; #define PG8_WAIT_L(n) asm volatile("s_waitcnt lgkmcnt(" #n ")" ::: "memory")
; #define PG8_BAR __builtin_amdgcn_s_barrier()
; #define PG8_SCHED __builtin_amdgcn_sched_barrier(0)
; template <int EK, int SK = -1>
; __device__ __forceinline__ void gemm_phase(LAS unsigned char* lds, const bf16_t* A, const bf16_t* Bt, int nM, int N, int K, const EpiArgs& E) {
;     ...
;             PG8_LDA(At, 1, 1); PG8_STAGEB(PG8_SB(1, 0), b3); PG8_STAGEB(PG8_SB(1, 1), b3 + hstep); PG8_STAGEA(PG8_SA(1, 0), a3);
;             PG8_WAIT_V(8); PG8_WAIT_L(0); PG8_BAR; PG8_MMA(1, 0, At, B0); PG8_MMA(1, 1, At, B1); PG8_BAR; PG8_SCHED;
;         }
	s_add_i32 s44, s73, s52
	v_lshl_add_u64 v[220:221], v[220:221], 0, s[22:23]
	s_mov_b32 m0, s44
	ds_read_b128 v[188:191], v155 offset:49152
	ds_read_b128 v[192:195], v155 offset:50176
	ds_read_b128 v[196:199], v155 offset:51200
	ds_read_b128 v[200:203], v155 offset:52224
	ds_read_b128 v[204:207], v155 offset:53248
	ds_read_b128 v[208:211], v155 offset:54272
	ds_read_b128 v[212:215], v155 offset:55296
	ds_read_b128 v[216:219], v155 offset:56320
	s_mov_b64 exec, s[100:101]
	global_load_lds_dwordx4 v[220:221], off
	s_mov_b64 exec, -1
	s_add_i32 m0, s44, 0x2000
	s_add_u32 s42, s42, 0xb0080
	v_lshl_add_u64 v[220:221], v[222:223], 0, s[22:23]
	s_addc_u32 s43, s43, 0
	s_add_i32 s44, s74, s52
	s_mov_b64 exec, s[100:101]
	global_load_lds_dwordx4 v[220:221], off
	s_mov_b64 exec, -1
	v_lshl_add_u64 v[220:221], s[42:43], 0, v[132:133]
	s_mov_b32 m0, s44
	s_nop 0
	s_mov_b64 exec, s[100:101]
	global_load_lds_dwordx4 v[220:221], off
	s_mov_b64 exec, -1
	v_lshl_add_u64 v[220:221], s[42:43], 0, v[136:137]
	s_add_i32 m0, s44, 0x2000
	s_nop 0
	s_mov_b64 exec, s[100:101]
	global_load_lds_dwordx4 v[220:221], off
	s_mov_b64 exec, -1
	v_lshl_add_u64 v[220:221], v[224:225], 0, s[22:23]
	s_mov_b32 m0, s58
	s_nop 0
	s_mov_b64 exec, s[100:101]
	global_load_lds_dwordx4 v[220:221], off
	s_mov_b64 exec, -1
	v_lshl_add_u64 v[220:221], v[226:227], 0, s[22:23]
	s_mov_b32 m0, s59
	s_nop 0
	s_mov_b64 exec, s[100:101]
	global_load_lds_dwordx4 v[220:221], off
	s_mov_b64 exec, -1
	s_waitcnt vmcnt(8)
	s_waitcnt lgkmcnt(0)
	s_barrier
	s_waitcnt lgkmcnt(0)
	v_mfma_f32_16x16x32_bf16 v[62:65], v[156:159], v[188:191], v[62:65]
	v_mfma_f32_16x16x32_bf16 v[58:61], v[164:167], v[188:191], v[58:61]
	v_mfma_f32_16x16x32_bf16 v[46:49], v[156:159], v[196:199], v[46:49]
	v_mfma_f32_16x16x32_bf16 v[42:45], v[164:167], v[196:199], v[42:45]
	v_mfma_f32_16x16x32_bf16 v[30:33], v[156:159], v[204:207], v[30:33]
	v_mfma_f32_16x16x32_bf16 v[26:29], v[164:167], v[204:207], v[26:29]
	v_mfma_f32_16x16x32_bf16 v[14:17], v[156:159], v[212:215], v[14:17]
	v_mfma_f32_16x16x32_bf16 v[10:13], v[164:167], v[212:215], v[10:13]
	v_mfma_f32_16x16x32_bf16 v[62:65], v[160:163], v[192:195], v[62:65]
	v_mfma_f32_16x16x32_bf16 v[58:61], v[168:171], v[192:195], v[58:61]
	v_mfma_f32_16x16x32_bf16 v[46:49], v[160:163], v[200:203], v[46:49]
	v_mfma_f32_16x16x32_bf16 v[42:45], v[168:171], v[200:203], v[42:45]
	v_mfma_f32_16x16x32_bf16 v[30:33], v[160:163], v[208:211], v[30:33]
	v_mfma_f32_16x16x32_bf16 v[26:29], v[168:171], v[208:211], v[26:29]
	v_mfma_f32_16x16x32_bf16 v[14:17], v[160:163], v[216:219], v[14:17]
	v_mfma_f32_16x16x32_bf16 v[10:13], v[168:171], v[216:219], v[10:13]
	v_mfma_f32_16x16x32_bf16 v[54:57], v[172:175], v[188:191], v[54:57]
	v_mfma_f32_16x16x32_bf16 v[50:53], v[180:183], v[188:191], v[50:53]
	v_mfma_f32_16x16x32_bf16 v[38:41], v[172:175], v[196:199], v[38:41]
	v_mfma_f32_16x16x32_bf16 v[34:37], v[180:183], v[196:199], v[34:37]
	v_mfma_f32_16x16x32_bf16 v[22:25], v[172:175], v[204:207], v[22:25]
	v_mfma_f32_16x16x32_bf16 v[18:21], v[180:183], v[204:207], v[18:21]
	v_mfma_f32_16x16x32_bf16 v[6:9], v[172:175], v[212:215], v[6:9]
	v_mfma_f32_16x16x32_bf16 v[2:5], v[180:183], v[212:215], v[2:5]
	v_mfma_f32_16x16x32_bf16 v[54:57], v[176:179], v[192:195], v[54:57]
	v_mfma_f32_16x16x32_bf16 v[50:53], v[184:187], v[192:195], v[50:53]
	v_mfma_f32_16x16x32_bf16 v[38:41], v[176:179], v[200:203], v[38:41]
	v_mfma_f32_16x16x32_bf16 v[34:37], v[184:187], v[200:203], v[34:37]
	v_mfma_f32_16x16x32_bf16 v[22:25], v[176:179], v[208:211], v[22:25]
	v_mfma_f32_16x16x32_bf16 v[18:21], v[184:187], v[208:211], v[18:21]
	v_mfma_f32_16x16x32_bf16 v[6:9], v[176:179], v[216:219], v[6:9]
	v_mfma_f32_16x16x32_bf16 v[2:5], v[184:187], v[216:219], v[2:5]
	s_barrier
	s_add_i32 s72, s72, 2
	s_add_u32 s40, s40, 0x100
	s_addc_u32 s41, s41, 0
	s_cmp_gt_u32 s72, 41
	s_cbranch_scc0 .LBB0_1401
	s_and_b64 vcc, exec, s[26:27]
	s_cbranch_vccz .LBB0_1404
	s_barrier
